# GEMM K-loops: loop-carried counter/pointer updates and exit compare moved in front of the loop-back barrier (back-edge rotation)
# baseline (speedup 1.0000x reference)
; #define PG8_STAGE(bufoff, gbase, voff) do { _Pragma("unroll") for (int _i = 0; _i < 2; ++_i) \
;         __builtin_amdgcn_global_load_lds((const unsigned*)((const char*)(gbase) + (voff)[_i]), (PG8_LAS unsigned*)(lds + (bufoff) + ldsw + _i * 8192), 16, 0, 0); } while (0)
; #define PG8_LDA(dst, b, h) do { _Pragma("unroll") for (int m = 0; m < 4; ++m) _Pragma("unroll") for (int k = 0; k < 2; ++k) dst[m][k] = *(const PG8_LAS bf16x8*)(lds + PG8_SA(b, h) + aoff + m * 2048 + k * 1024); } while (0)
; #define PG8_LDB(dst, b, h) do { _Pragma("unroll") for (int n = 0; n < 2; ++n) _Pragma("unroll") for (int k = 0; k < 2; ++k) dst[n][k] = *(const PG8_LAS bf16x8*)(lds + PG8_SB(b, h) + boff + n * 2048 + k * 1024); } while (0)
; #define PG8_MMA(ai, bj, At, Bt) do { __builtin_amdgcn_s_setprio(1); _Pragma("unroll") for (int m = 0; m < 4; ++m) _Pragma("unroll") for (int n = 0; n < 2; ++n) _Pragma("unroll") for (int k = 0; k < 2; ++k) \
;         acc[ai][bj][m][n] = __builtin_amdgcn_mfma_f32_16x16x32_bf16(Bt[n][k], At[m][k], acc[ai][bj][m][n], 0, 0, 0); __builtin_amdgcn_s_setprio(0); } while (0)
; #define PG8_WAIT_V(n) asm volatile("s_waitcnt vmcnt(" #n ")" ::: "memory")
; #define PG8_WAIT_L(n) asm volatile("s_waitcnt lgkmcnt(" #n ")" ::: "memory")
; template <class Epi, class Sched, bool ALIGN_EPI = false, bool SP2 = false>
; __device__ __forceinline__ void gemm_phase(PG8_LAS unsigned char* lds, const Gemm g, const Sched& S, const Epi& E) {
;     ...
;             const bool last = (t == nt - 2);
;             const char* a1 = cA + (size_t)(t + 1) * kstep;
;             const char* a2 = last ? nA : cA + (size_t)(t + 2) * kstep; const char* b2 = last ? nB : cB + (size_t)(t + 2) * kstep;
;             const char* a3 = a2 + kstep; const char* b3 = b2 + kstep;
;             if (last && has_next) S.a_ready(nxt);
;             if constexpr (SP2) {
;             PG8_LDB(B0, 0, 0); PG8_LDB(B1, 0, 1); PG8_SCHED; PG8_LDA(At, 0, 0); PG8_STAGE(PG8_SA(1, 1), a1 + hstep, voffA);
;             PG8_WAIT_V(8); PG8_WAIT_L(0); PG8_BAR; PG8_MMA(0, 0, At, B0); PG8_MMA(0, 1, At, B1); PG8_BAR; PG8_SCHED;
;             PG8_LDA(At, 0, 1); PG8_STAGE(PG8_SB(0, 0), b2, voffB); PG8_STAGE(PG8_SB(0, 1), b2 + hstep, voffB); PG8_STAGE(PG8_SA(0, 0), a2, voffA);
;             PG8_WAIT_V(8); PG8_WAIT_L(0); PG8_BAR; PG8_MMA(1, 0, At, B0); PG8_MMA(1, 1, At, B1); PG8_BAR; PG8_SCHED;
.LBB0_194:
	ds_read_b128 v[152:155], v149
	ds_read_b128 v[156:159], v149 offset:1024
	ds_read_b128 v[162:165], v149 offset:2048
	ds_read_b128 v[166:169], v149 offset:3072
	ds_read_b128 v[170:173], v150
	ds_read_b128 v[174:177], v150 offset:1024
	ds_read_b128 v[178:181], v150 offset:2048
	ds_read_b128 v[182:185], v150 offset:3072
	s_add_u32 s40, s38, 0xfffc0080
	s_addc_u32 s41, s39, -1
	s_cmp_eq_u32 s78, 12
	s_cselect_b32 s53, s19, s41
	s_cselect_b32 s52, s72, s40
	s_cselect_b32 s41, s17, s77
	s_cselect_b32 s40, s73, s76
	v_lshl_add_u64 v[144:145], s[38:39], 0, v[136:137]
	s_add_i32 m0, s37, 0xc000
	ds_read_b128 v[186:189], v151
	ds_read_b128 v[190:193], v151 offset:1024
	ds_read_b128 v[194:197], v151 offset:2048
	ds_read_b128 v[198:201], v151 offset:3072
	ds_read_b128 v[202:205], v151 offset:4096
	ds_read_b128 v[206:209], v151 offset:5120
	ds_read_b128 v[210:213], v151 offset:6144
	ds_read_b128 v[214:217], v151 offset:7168
	global_load_lds_dwordx4 v[144:145], off
	v_lshl_add_u64 v[144:145], s[38:39], 0, v[138:139]
	s_add_i32 m0, s37, 0xe000
	s_nop 0
	global_load_lds_dwordx4 v[144:145], off
	s_waitcnt vmcnt(8)
	s_waitcnt lgkmcnt(0)
	s_barrier
	s_setprio 1
	s_waitcnt lgkmcnt(0)
	v_mfma_f32_16x16x32_bf16 v[124:127], v[152:155], v[186:189], v[124:127]
	v_mfma_f32_16x16x32_bf16 v[116:119], v[162:165], v[186:189], v[116:119]
	v_mfma_f32_16x16x32_bf16 v[108:111], v[152:155], v[194:197], v[108:111]
	v_mfma_f32_16x16x32_bf16 v[100:103], v[162:165], v[194:197], v[100:103]
	v_mfma_f32_16x16x32_bf16 v[92:95], v[152:155], v[202:205], v[92:95]
	v_mfma_f32_16x16x32_bf16 v[84:87], v[162:165], v[202:205], v[84:87]
	v_mfma_f32_16x16x32_bf16 v[76:79], v[152:155], v[210:213], v[76:79]
	v_mfma_f32_16x16x32_bf16 v[68:71], v[162:165], v[210:213], v[68:71]
	v_mfma_f32_16x16x32_bf16 v[124:127], v[156:159], v[190:193], v[124:127]
	v_mfma_f32_16x16x32_bf16 v[116:119], v[166:169], v[190:193], v[116:119]
	v_mfma_f32_16x16x32_bf16 v[108:111], v[156:159], v[198:201], v[108:111]
	v_mfma_f32_16x16x32_bf16 v[100:103], v[166:169], v[198:201], v[100:103]
	v_mfma_f32_16x16x32_bf16 v[92:95], v[156:159], v[206:209], v[92:95]
	v_mfma_f32_16x16x32_bf16 v[84:87], v[166:169], v[206:209], v[84:87]
	v_mfma_f32_16x16x32_bf16 v[76:79], v[156:159], v[214:217], v[76:79]
	v_mfma_f32_16x16x32_bf16 v[68:71], v[166:169], v[214:217], v[68:71]
	s_setprio 0
	s_setprio 1
	v_mfma_f32_16x16x32_bf16 v[120:123], v[170:173], v[186:189], v[120:123]
	v_mfma_f32_16x16x32_bf16 v[112:115], v[178:181], v[186:189], v[112:115]
	v_mfma_f32_16x16x32_bf16 v[104:107], v[170:173], v[194:197], v[104:107]
	v_mfma_f32_16x16x32_bf16 v[96:99], v[178:181], v[194:197], v[96:99]
	v_mfma_f32_16x16x32_bf16 v[88:91], v[170:173], v[202:205], v[88:91]
	v_mfma_f32_16x16x32_bf16 v[80:83], v[178:181], v[202:205], v[80:83]
	v_mfma_f32_16x16x32_bf16 v[72:75], v[170:173], v[210:213], v[72:75]
	v_mfma_f32_16x16x32_bf16 v[64:67], v[178:181], v[210:213], v[64:67]
	v_mfma_f32_16x16x32_bf16 v[120:123], v[174:177], v[190:193], v[120:123]
	v_mfma_f32_16x16x32_bf16 v[112:115], v[182:185], v[190:193], v[112:115]
	v_mfma_f32_16x16x32_bf16 v[104:107], v[174:177], v[198:201], v[104:107]
	v_mfma_f32_16x16x32_bf16 v[96:99], v[182:185], v[198:201], v[96:99]
	v_mfma_f32_16x16x32_bf16 v[88:91], v[174:177], v[206:209], v[88:91]
	v_mfma_f32_16x16x32_bf16 v[80:83], v[182:185], v[206:209], v[80:83]
	v_mfma_f32_16x16x32_bf16 v[72:75], v[174:177], v[214:217], v[72:75]
	v_mfma_f32_16x16x32_bf16 v[64:67], v[182:185], v[214:217], v[64:67]
	s_setprio 0
	s_barrier
	s_add_i32 s79, s66, s3
	v_lshl_add_u64 v[144:145], s[40:41], 0, v[132:133]
	s_mov_b32 m0, s79
	ds_read_b128 v[186:189], v151 offset:16384
	ds_read_b128 v[190:193], v151 offset:17408
	ds_read_b128 v[194:197], v151 offset:18432
	ds_read_b128 v[198:201], v151 offset:19456
	ds_read_b128 v[202:205], v151 offset:20480
	ds_read_b128 v[206:209], v151 offset:21504
	ds_read_b128 v[210:213], v151 offset:22528
	ds_read_b128 v[214:217], v151 offset:23552
	global_load_lds_dwordx4 v[144:145], off
	s_add_i32 m0, s79, 0x2000
	s_add_u32 s80, s40, 0x40000
	v_lshl_add_u64 v[218:219], s[40:41], 0, v[128:129]
	s_addc_u32 s81, s41, 0
	s_add_i32 s79, s67, s3
	global_load_lds_dwordx4 v[218:219], off
	v_lshl_add_u64 v[220:221], s[80:81], 0, v[132:133]
	s_mov_b32 m0, s79
	v_lshl_add_u64 v[222:223], s[52:53], 0, v[130:131]
	global_load_lds_dwordx4 v[220:221], off
	v_lshl_add_u64 v[220:221], s[80:81], 0, v[128:129]
	s_add_i32 m0, s79, 0x2000
	s_nop 0
	global_load_lds_dwordx4 v[220:221], off
	v_lshl_add_u64 v[220:221], s[52:53], 0, v[134:135]
	s_mov_b32 m0, s37
	s_nop 0
	global_load_lds_dwordx4 v[220:221], off
	s_mov_b32 m0, s56
	s_nop 0
	global_load_lds_dwordx4 v[222:223], off
	s_waitcnt vmcnt(8)
	s_waitcnt lgkmcnt(0)
	s_barrier
; #define PG8_STAGE(bufoff, gbase, voff) do { _Pragma("unroll") for (int _i = 0; _i < 2; ++_i) \
;         __builtin_amdgcn_global_load_lds((const unsigned*)((const char*)(gbase) + (voff)[_i]), (PG8_LAS unsigned*)(lds + (bufoff) + ldsw + _i * 8192), 16, 0, 0); } while (0)
; #define PG8_LDA(dst, b, h) do { _Pragma("unroll") for (int m = 0; m < 4; ++m) _Pragma("unroll") for (int k = 0; k < 2; ++k) dst[m][k] = *(const PG8_LAS bf16x8*)(lds + PG8_SA(b, h) + aoff + m * 2048 + k * 1024); } while (0)
; #define PG8_LDB(dst, b, h) do { _Pragma("unroll") for (int n = 0; n < 2; ++n) _Pragma("unroll") for (int k = 0; k < 2; ++k) dst[n][k] = *(const PG8_LAS bf16x8*)(lds + PG8_SB(b, h) + boff + n * 2048 + k * 1024); } while (0)
; #define PG8_MMA(ai, bj, At, Bt) do { __builtin_amdgcn_s_setprio(1); _Pragma("unroll") for (int m = 0; m < 4; ++m) _Pragma("unroll") for (int n = 0; n < 2; ++n) _Pragma("unroll") for (int k = 0; k < 2; ++k) \
;         acc[ai][bj][m][n] = __builtin_amdgcn_mfma_f32_16x16x32_bf16(Bt[n][k], At[m][k], acc[ai][bj][m][n], 0, 0, 0); __builtin_amdgcn_s_setprio(0); } while (0)
; #define PG8_WAIT_V(n) asm volatile("s_waitcnt vmcnt(" #n ")" ::: "memory")
; #define PG8_WAIT_L(n) asm volatile("s_waitcnt lgkmcnt(" #n ")" ::: "memory")
; #define PG8_BAR __builtin_amdgcn_s_barrier()
; #define PG8_SCHED __builtin_amdgcn_sched_barrier(0)
; template <class Epi, class Sched, bool ALIGN_EPI = false, bool SP2 = false>
; __device__ __forceinline__ void gemm_phase(PG8_LAS unsigned char* lds, const Gemm g, const Sched& S, const Epi& E) {
;     ...
;             PG8_WAIT_V(8); PG8_WAIT_L(0); PG8_BAR; PG8_MMA(1, 0, At, B0); PG8_MMA(1, 1, At, B1); PG8_BAR; PG8_SCHED;
;             PG8_LDB(B0, 1, 0); PG8_LDB(B1, 1, 1); PG8_SCHED; PG8_LDA(At, 1, 0); PG8_STAGE(PG8_SA(0, 1), a2 + hstep, voffA);
;             PG8_WAIT_V(8); PG8_WAIT_L(0); PG8_BAR; PG8_MMA(0, 0, At, B0); PG8_MMA(0, 1, At, B1); PG8_BAR; PG8_SCHED;
;             PG8_LDA(At, 1, 1); PG8_STAGE(PG8_SB(1, 0), b3, voffB); PG8_STAGE(PG8_SB(1, 1), b3 + hstep, voffB); PG8_STAGE(PG8_SA(1, 0), a3, voffA);
	s_setprio 1
	s_waitcnt lgkmcnt(0)
	v_mfma_f32_16x16x32_bf16 v[60:63], v[152:155], v[186:189], v[60:63]
	v_mfma_f32_16x16x32_bf16 v[52:55], v[162:165], v[186:189], v[52:55]
	v_mfma_f32_16x16x32_bf16 v[44:47], v[152:155], v[194:197], v[44:47]
	v_mfma_f32_16x16x32_bf16 v[36:39], v[162:165], v[194:197], v[36:39]
	v_mfma_f32_16x16x32_bf16 v[28:31], v[152:155], v[202:205], v[28:31]
	v_mfma_f32_16x16x32_bf16 v[20:23], v[162:165], v[202:205], v[20:23]
	v_mfma_f32_16x16x32_bf16 v[12:15], v[152:155], v[210:213], v[12:15]
	v_mfma_f32_16x16x32_bf16 v[4:7], v[162:165], v[210:213], v[4:7]
	v_mfma_f32_16x16x32_bf16 v[60:63], v[156:159], v[190:193], v[60:63]
	v_mfma_f32_16x16x32_bf16 v[52:55], v[166:169], v[190:193], v[52:55]
	v_mfma_f32_16x16x32_bf16 v[44:47], v[156:159], v[198:201], v[44:47]
	v_mfma_f32_16x16x32_bf16 v[36:39], v[166:169], v[198:201], v[36:39]
	v_mfma_f32_16x16x32_bf16 v[28:31], v[156:159], v[206:209], v[28:31]
	v_mfma_f32_16x16x32_bf16 v[20:23], v[166:169], v[206:209], v[20:23]
	v_mfma_f32_16x16x32_bf16 v[12:15], v[156:159], v[214:217], v[12:15]
	v_mfma_f32_16x16x32_bf16 v[4:7], v[166:169], v[214:217], v[4:7]
	s_setprio 0
	s_setprio 1
	v_mfma_f32_16x16x32_bf16 v[56:59], v[170:173], v[186:189], v[56:59]
	v_mfma_f32_16x16x32_bf16 v[48:51], v[178:181], v[186:189], v[48:51]
	v_mfma_f32_16x16x32_bf16 v[40:43], v[170:173], v[194:197], v[40:43]
	v_mfma_f32_16x16x32_bf16 v[32:35], v[178:181], v[194:197], v[32:35]
	v_mfma_f32_16x16x32_bf16 v[24:27], v[170:173], v[202:205], v[24:27]
	v_mfma_f32_16x16x32_bf16 v[16:19], v[178:181], v[202:205], v[16:19]
	v_mfma_f32_16x16x32_bf16 v[8:11], v[170:173], v[210:213], v[8:11]
	v_mfma_f32_16x16x32_bf16 v[0:3], v[178:181], v[210:213], v[0:3]
	v_mfma_f32_16x16x32_bf16 v[56:59], v[174:177], v[190:193], v[56:59]
	v_mfma_f32_16x16x32_bf16 v[48:51], v[182:185], v[190:193], v[48:51]
	v_mfma_f32_16x16x32_bf16 v[40:43], v[174:177], v[198:201], v[40:43]
	v_mfma_f32_16x16x32_bf16 v[32:35], v[182:185], v[198:201], v[32:35]
	v_mfma_f32_16x16x32_bf16 v[24:27], v[174:177], v[206:209], v[24:27]
	v_mfma_f32_16x16x32_bf16 v[16:19], v[182:185], v[206:209], v[16:19]
	v_mfma_f32_16x16x32_bf16 v[8:11], v[174:177], v[214:217], v[8:11]
	v_mfma_f32_16x16x32_bf16 v[0:3], v[182:185], v[214:217], v[0:3]
	s_setprio 0
	s_barrier
	s_add_i32 s79, 0, 0x18000
	v_add_u32_e32 v161, s79, v147
	s_add_i32 s80, 0, 0x1c000
	ds_read_b128 v[152:155], v161
	ds_read_b128 v[156:159], v161 offset:1024
	ds_read_b128 v[162:165], v161 offset:2048
	ds_read_b128 v[166:169], v161 offset:3072
	v_add_u32_e32 v161, s80, v147
	ds_read_b128 v[170:173], v161
	ds_read_b128 v[174:177], v161 offset:1024
	ds_read_b128 v[178:181], v161 offset:2048
	ds_read_b128 v[182:185], v161 offset:3072
	s_add_u32 s52, s52, 0x40000
	s_addc_u32 s53, s53, 0
	s_mov_b32 m0, s57
	v_lshl_add_u64 v[224:225], s[52:53], 0, v[134:135]
	ds_read_b128 v[186:189], v151 offset:32768
	ds_read_b128 v[190:193], v151 offset:33792
	ds_read_b128 v[194:197], v151 offset:34816
	ds_read_b128 v[198:201], v151 offset:35840
	ds_read_b128 v[202:205], v151 offset:36864
	ds_read_b128 v[206:209], v151 offset:37888
	ds_read_b128 v[210:213], v151 offset:38912
	ds_read_b128 v[214:217], v151 offset:39936
	global_load_lds_dwordx4 v[224:225], off
	v_lshl_add_u64 v[224:225], s[52:53], 0, v[130:131]
	s_mov_b32 m0, s58
	s_nop 0
	global_load_lds_dwordx4 v[224:225], off
	s_waitcnt vmcnt(8)
	s_waitcnt lgkmcnt(0)
	s_barrier
	s_setprio 1
	s_waitcnt lgkmcnt(0)
	v_mfma_f32_16x16x32_bf16 v[124:127], v[152:155], v[186:189], v[124:127]
	v_mfma_f32_16x16x32_bf16 v[116:119], v[162:165], v[186:189], v[116:119]
	v_mfma_f32_16x16x32_bf16 v[108:111], v[152:155], v[194:197], v[108:111]
	v_mfma_f32_16x16x32_bf16 v[100:103], v[162:165], v[194:197], v[100:103]
	v_mfma_f32_16x16x32_bf16 v[92:95], v[152:155], v[202:205], v[92:95]
	v_mfma_f32_16x16x32_bf16 v[84:87], v[162:165], v[202:205], v[84:87]
	v_mfma_f32_16x16x32_bf16 v[76:79], v[152:155], v[210:213], v[76:79]
	v_mfma_f32_16x16x32_bf16 v[68:71], v[162:165], v[210:213], v[68:71]
	v_mfma_f32_16x16x32_bf16 v[124:127], v[156:159], v[190:193], v[124:127]
	v_mfma_f32_16x16x32_bf16 v[116:119], v[166:169], v[190:193], v[116:119]
	v_mfma_f32_16x16x32_bf16 v[108:111], v[156:159], v[198:201], v[108:111]
	v_mfma_f32_16x16x32_bf16 v[100:103], v[166:169], v[198:201], v[100:103]
	v_mfma_f32_16x16x32_bf16 v[92:95], v[156:159], v[206:209], v[92:95]
	v_mfma_f32_16x16x32_bf16 v[84:87], v[166:169], v[206:209], v[84:87]
	v_mfma_f32_16x16x32_bf16 v[76:79], v[156:159], v[214:217], v[76:79]
	v_mfma_f32_16x16x32_bf16 v[68:71], v[166:169], v[214:217], v[68:71]
	s_setprio 0
	s_setprio 1
	v_mfma_f32_16x16x32_bf16 v[120:123], v[170:173], v[186:189], v[120:123]
	v_mfma_f32_16x16x32_bf16 v[112:115], v[178:181], v[186:189], v[112:115]
	v_mfma_f32_16x16x32_bf16 v[104:107], v[170:173], v[194:197], v[104:107]
	v_mfma_f32_16x16x32_bf16 v[96:99], v[178:181], v[194:197], v[96:99]
	v_mfma_f32_16x16x32_bf16 v[88:91], v[170:173], v[202:205], v[88:91]
	v_mfma_f32_16x16x32_bf16 v[80:83], v[178:181], v[202:205], v[80:83]
	v_mfma_f32_16x16x32_bf16 v[72:75], v[170:173], v[210:213], v[72:75]
	v_mfma_f32_16x16x32_bf16 v[64:67], v[178:181], v[210:213], v[64:67]
	v_mfma_f32_16x16x32_bf16 v[120:123], v[174:177], v[190:193], v[120:123]
	v_mfma_f32_16x16x32_bf16 v[112:115], v[182:185], v[190:193], v[112:115]
	v_mfma_f32_16x16x32_bf16 v[104:107], v[174:177], v[198:201], v[104:107]
	v_mfma_f32_16x16x32_bf16 v[96:99], v[182:185], v[198:201], v[96:99]
	v_mfma_f32_16x16x32_bf16 v[88:91], v[174:177], v[206:209], v[88:91]
	v_mfma_f32_16x16x32_bf16 v[80:83], v[182:185], v[206:209], v[80:83]
	v_mfma_f32_16x16x32_bf16 v[72:75], v[174:177], v[214:217], v[72:75]
	v_mfma_f32_16x16x32_bf16 v[64:67], v[182:185], v[214:217], v[64:67]
	s_setprio 0
	s_barrier
; #define PG8_STAGE(bufoff, gbase, voff) do { _Pragma("unroll") for (int _i = 0; _i < 2; ++_i) \
;         __builtin_amdgcn_global_load_lds((const unsigned*)((const char*)(gbase) + (voff)[_i]), (PG8_LAS unsigned*)(lds + (bufoff) + ldsw + _i * 8192), 16, 0, 0); } while (0)
; #define PG8_LDA(dst, b, h) do { _Pragma("unroll") for (int m = 0; m < 4; ++m) _Pragma("unroll") for (int k = 0; k < 2; ++k) dst[m][k] = *(const PG8_LAS bf16x8*)(lds + PG8_SA(b, h) + aoff + m * 2048 + k * 1024); } while (0)
; #define PG8_MMA(ai, bj, At, Bt) do { __builtin_amdgcn_s_setprio(1); _Pragma("unroll") for (int m = 0; m < 4; ++m) _Pragma("unroll") for (int n = 0; n < 2; ++n) _Pragma("unroll") for (int k = 0; k < 2; ++k) \
;         acc[ai][bj][m][n] = __builtin_amdgcn_mfma_f32_16x16x32_bf16(Bt[n][k], At[m][k], acc[ai][bj][m][n], 0, 0, 0); __builtin_amdgcn_s_setprio(0); } while (0)
; #define PG8_WAIT_V(n) asm volatile("s_waitcnt vmcnt(" #n ")" ::: "memory")
; #define PG8_WAIT_L(n) asm volatile("s_waitcnt lgkmcnt(" #n ")" ::: "memory")
; #define PG8_BAR __builtin_amdgcn_s_barrier()
; #define PG8_SCHED __builtin_amdgcn_sched_barrier(0)
; template <class Epi, class Sched, bool ALIGN_EPI = false, bool SP2 = false>
; __device__ __forceinline__ void gemm_phase(PG8_LAS unsigned char* lds, const Gemm g, const Sched& S, const Epi& E) {
;     ...
;             PG8_LDA(At, 1, 1); PG8_STAGE(PG8_SB(1, 0), b3, voffB); PG8_STAGE(PG8_SB(1, 1), b3 + hstep, voffB); PG8_STAGE(PG8_SA(1, 0), a3, voffA);
;             PG8_WAIT_V(8); PG8_WAIT_L(0); PG8_BAR; PG8_MMA(1, 0, At, B0); PG8_MMA(1, 1, At, B1); PG8_BAR; PG8_SCHED;
	s_add_i32 s52, s79, s3
	v_lshl_add_u64 v[144:145], v[144:145], 0, s[12:13]
	s_mov_b32 m0, s52
	ds_read_b128 v[186:189], v151 offset:49152
	ds_read_b128 v[190:193], v151 offset:50176
	ds_read_b128 v[194:197], v151 offset:51200
	ds_read_b128 v[198:201], v151 offset:52224
	ds_read_b128 v[202:205], v151 offset:53248
	ds_read_b128 v[206:209], v151 offset:54272
	ds_read_b128 v[210:213], v151 offset:55296
	ds_read_b128 v[214:217], v151 offset:56320
	global_load_lds_dwordx4 v[144:145], off
	s_add_i32 m0, s52, 0x2000
	s_add_u32 s40, s40, 0x40080
	v_lshl_add_u64 v[144:145], v[218:219], 0, s[12:13]
	s_addc_u32 s41, s41, 0
	s_add_i32 s52, s80, s3
	global_load_lds_dwordx4 v[144:145], off
	v_lshl_add_u64 v[144:145], s[40:41], 0, v[132:133]
	s_mov_b32 m0, s52
	s_nop 0
	global_load_lds_dwordx4 v[144:145], off
	v_lshl_add_u64 v[144:145], s[40:41], 0, v[128:129]
	s_add_i32 m0, s52, 0x2000
	s_nop 0
	global_load_lds_dwordx4 v[144:145], off
	v_lshl_add_u64 v[144:145], v[220:221], 0, s[12:13]
	s_mov_b32 m0, s62
	s_nop 0
	global_load_lds_dwordx4 v[144:145], off
	v_lshl_add_u64 v[144:145], v[222:223], 0, s[12:13]
	s_mov_b32 m0, s63
	s_nop 0
	global_load_lds_dwordx4 v[144:145], off
	s_waitcnt vmcnt(8)
	s_waitcnt lgkmcnt(0)
	s_barrier
	s_setprio 1
	s_waitcnt lgkmcnt(0)
	v_mfma_f32_16x16x32_bf16 v[60:63], v[152:155], v[186:189], v[60:63]
	v_mfma_f32_16x16x32_bf16 v[52:55], v[162:165], v[186:189], v[52:55]
	v_mfma_f32_16x16x32_bf16 v[44:47], v[152:155], v[194:197], v[44:47]
	v_mfma_f32_16x16x32_bf16 v[36:39], v[162:165], v[194:197], v[36:39]
	v_mfma_f32_16x16x32_bf16 v[28:31], v[152:155], v[202:205], v[28:31]
	v_mfma_f32_16x16x32_bf16 v[20:23], v[162:165], v[202:205], v[20:23]
	v_mfma_f32_16x16x32_bf16 v[12:15], v[152:155], v[210:213], v[12:15]
	v_mfma_f32_16x16x32_bf16 v[4:7], v[162:165], v[210:213], v[4:7]
	v_mfma_f32_16x16x32_bf16 v[60:63], v[156:159], v[190:193], v[60:63]
	v_mfma_f32_16x16x32_bf16 v[52:55], v[166:169], v[190:193], v[52:55]
	v_mfma_f32_16x16x32_bf16 v[44:47], v[156:159], v[198:201], v[44:47]
	v_mfma_f32_16x16x32_bf16 v[36:39], v[166:169], v[198:201], v[36:39]
	v_mfma_f32_16x16x32_bf16 v[28:31], v[156:159], v[206:209], v[28:31]
	v_mfma_f32_16x16x32_bf16 v[20:23], v[166:169], v[206:209], v[20:23]
	v_mfma_f32_16x16x32_bf16 v[12:15], v[156:159], v[214:217], v[12:15]
	v_mfma_f32_16x16x32_bf16 v[4:7], v[166:169], v[214:217], v[4:7]
	s_setprio 0
	s_setprio 1
	v_mfma_f32_16x16x32_bf16 v[56:59], v[170:173], v[186:189], v[56:59]
	v_mfma_f32_16x16x32_bf16 v[48:51], v[178:181], v[186:189], v[48:51]
	v_mfma_f32_16x16x32_bf16 v[40:43], v[170:173], v[194:197], v[40:43]
	v_mfma_f32_16x16x32_bf16 v[32:35], v[178:181], v[194:197], v[32:35]
	v_mfma_f32_16x16x32_bf16 v[24:27], v[170:173], v[202:205], v[24:27]
	v_mfma_f32_16x16x32_bf16 v[16:19], v[178:181], v[202:205], v[16:19]
	v_mfma_f32_16x16x32_bf16 v[8:11], v[170:173], v[210:213], v[8:11]
	v_mfma_f32_16x16x32_bf16 v[0:3], v[178:181], v[210:213], v[0:3]
	v_mfma_f32_16x16x32_bf16 v[56:59], v[174:177], v[190:193], v[56:59]
	v_mfma_f32_16x16x32_bf16 v[48:51], v[182:185], v[190:193], v[48:51]
	v_mfma_f32_16x16x32_bf16 v[40:43], v[174:177], v[198:201], v[40:43]
	v_mfma_f32_16x16x32_bf16 v[32:35], v[182:185], v[198:201], v[32:35]
	v_mfma_f32_16x16x32_bf16 v[24:27], v[174:177], v[206:209], v[24:27]
	v_mfma_f32_16x16x32_bf16 v[16:19], v[182:185], v[206:209], v[16:19]
	v_mfma_f32_16x16x32_bf16 v[8:11], v[174:177], v[214:217], v[8:11]
	v_mfma_f32_16x16x32_bf16 v[0:3], v[182:185], v[214:217], v[0:3]
	s_setprio 0
	s_add_i32 s78, s78, 2
	s_add_u32 s38, s38, 0x100
	s_addc_u32 s39, s39, 0
	s_add_u32 s76, s76, 0x100
	s_addc_u32 s77, s77, 0
	s_cmp_gt_u32 s78, 13
	s_barrier
	s_cbranch_scc0 .LBB0_194
	s_and_b64 vcc, exec, s[14:15]
	s_cbranch_vccz .LBB0_197
	s_barrier

; #define PG8_STAGE(bufoff, gbase, voff) do { _Pragma("unroll") for (int _i = 0; _i < 2; ++_i) \
;         __builtin_amdgcn_global_load_lds((const unsigned*)((const char*)(gbase) + (voff)[_i]), (PG8_LAS unsigned*)(lds + (bufoff) + ldsw + _i * 8192), 16, 0, 0); } while (0)
; #define PG8_LDA(dst, b, h) do { _Pragma("unroll") for (int m = 0; m < 4; ++m) _Pragma("unroll") for (int k = 0; k < 2; ++k) dst[m][k] = *(const PG8_LAS bf16x8*)(lds + PG8_SA(b, h) + aoff + m * 2048 + k * 1024); } while (0)
; #define PG8_LDB(dst, b, h) do { _Pragma("unroll") for (int n = 0; n < 2; ++n) _Pragma("unroll") for (int k = 0; k < 2; ++k) dst[n][k] = *(const PG8_LAS bf16x8*)(lds + PG8_SB(b, h) + boff + n * 2048 + k * 1024); } while (0)
; #define PG8_MMA(ai, bj, At, Bt) do { __builtin_amdgcn_s_setprio(1); _Pragma("unroll") for (int m = 0; m < 4; ++m) _Pragma("unroll") for (int n = 0; n < 2; ++n) _Pragma("unroll") for (int k = 0; k < 2; ++k) \
;         acc[ai][bj][m][n] = __builtin_amdgcn_mfma_f32_16x16x32_bf16(Bt[n][k], At[m][k], acc[ai][bj][m][n], 0, 0, 0); __builtin_amdgcn_s_setprio(0); } while (0)
; #define PG8_WAIT_V(n) asm volatile("s_waitcnt vmcnt(" #n ")" ::: "memory")
; #define PG8_WAIT_L(n) asm volatile("s_waitcnt lgkmcnt(" #n ")" ::: "memory")
; template <class Epi, class Sched, bool ALIGN_EPI = false, bool SP2 = false>
; __device__ __forceinline__ void gemm_phase(PG8_LAS unsigned char* lds, const Gemm g, const Sched& S, const Epi& E) {
;     ...
;             const bool last = (t == nt - 2);
;             const char* a1 = cA + (size_t)(t + 1) * kstep;
;             const char* a2 = last ? nA : cA + (size_t)(t + 2) * kstep; const char* b2 = last ? nB : cB + (size_t)(t + 2) * kstep;
;             const char* a3 = a2 + kstep; const char* b3 = b2 + kstep;
;             if (last && has_next) S.a_ready(nxt);
;             if constexpr (SP2) {
;             PG8_LDB(B0, 0, 0); PG8_LDB(B1, 0, 1); PG8_SCHED; PG8_LDA(At, 0, 0); PG8_STAGE(PG8_SA(1, 1), a1 + hstep, voffA);
;             PG8_WAIT_V(8); PG8_WAIT_L(0); PG8_BAR; PG8_MMA(0, 0, At, B0); PG8_MMA(0, 1, At, B1); PG8_BAR; PG8_SCHED;
;             PG8_LDA(At, 0, 1); PG8_STAGE(PG8_SB(0, 0), b2, voffB); PG8_STAGE(PG8_SB(0, 1), b2 + hstep, voffB); PG8_STAGE(PG8_SA(0, 0), a2, voffA);
;             PG8_WAIT_V(8); PG8_WAIT_L(0); PG8_BAR; PG8_MMA(1, 0, At, B0); PG8_MMA(1, 1, At, B1); PG8_BAR; PG8_SCHED;
.LBB0_289:
	ds_read_b128 v[144:147], v168
	ds_read_b128 v[148:151], v168 offset:1024
	ds_read_b128 v[152:155], v168 offset:2048
	ds_read_b128 v[156:159], v168 offset:3072
	ds_read_b128 v[162:165], v169
	ds_read_b128 v[172:175], v169 offset:1024
	ds_read_b128 v[176:179], v169 offset:2048
	ds_read_b128 v[180:183], v169 offset:3072
	s_add_u32 s34, s22, 0xfff50080
	s_addc_u32 s35, s23, -1
	s_cmp_eq_u32 s70, 40
	s_cselect_b32 s37, s1, s35
	s_cselect_b32 s36, s0, s34
	s_cselect_b32 s35, s21, s67
	s_cselect_b32 s34, s20, s66
	v_lshl_add_u64 v[216:217], s[22:23], 0, v[136:137]
	s_add_i32 m0, s38, 0xc000
	ds_read_b128 v[184:187], v170
	ds_read_b128 v[188:191], v170 offset:1024
	ds_read_b128 v[192:195], v170 offset:2048
	ds_read_b128 v[196:199], v170 offset:3072
	ds_read_b128 v[200:203], v170 offset:4096
	ds_read_b128 v[204:207], v170 offset:5120
	ds_read_b128 v[208:211], v170 offset:6144
	ds_read_b128 v[212:215], v170 offset:7168
	global_load_lds_dwordx4 v[216:217], off
	v_lshl_add_u64 v[216:217], s[22:23], 0, v[138:139]
	s_add_i32 m0, s38, 0xe000
	s_nop 0
	global_load_lds_dwordx4 v[216:217], off
	s_waitcnt vmcnt(8)
	s_waitcnt lgkmcnt(0)
	s_barrier
	s_setprio 1
	s_waitcnt lgkmcnt(0)
	v_mfma_f32_16x16x32_bf16 v[124:127], v[144:147], v[184:187], v[124:127]
	v_mfma_f32_16x16x32_bf16 v[120:123], v[152:155], v[184:187], v[120:123]
	v_mfma_f32_16x16x32_bf16 v[108:111], v[144:147], v[192:195], v[108:111]
	v_mfma_f32_16x16x32_bf16 v[104:107], v[152:155], v[192:195], v[104:107]
	v_mfma_f32_16x16x32_bf16 v[92:95], v[144:147], v[200:203], v[92:95]
	v_mfma_f32_16x16x32_bf16 v[88:91], v[152:155], v[200:203], v[88:91]
	v_mfma_f32_16x16x32_bf16 v[76:79], v[144:147], v[208:211], v[76:79]
	v_mfma_f32_16x16x32_bf16 v[72:75], v[152:155], v[208:211], v[72:75]
	v_mfma_f32_16x16x32_bf16 v[124:127], v[148:151], v[188:191], v[124:127]
	v_mfma_f32_16x16x32_bf16 v[120:123], v[156:159], v[188:191], v[120:123]
	v_mfma_f32_16x16x32_bf16 v[108:111], v[148:151], v[196:199], v[108:111]
	v_mfma_f32_16x16x32_bf16 v[104:107], v[156:159], v[196:199], v[104:107]
	v_mfma_f32_16x16x32_bf16 v[92:95], v[148:151], v[204:207], v[92:95]
	v_mfma_f32_16x16x32_bf16 v[88:91], v[156:159], v[204:207], v[88:91]
	v_mfma_f32_16x16x32_bf16 v[76:79], v[148:151], v[212:215], v[76:79]
	v_mfma_f32_16x16x32_bf16 v[72:75], v[156:159], v[212:215], v[72:75]
	s_setprio 0
	s_setprio 1
	v_mfma_f32_16x16x32_bf16 v[116:119], v[162:165], v[184:187], v[116:119]
	v_mfma_f32_16x16x32_bf16 v[112:115], v[176:179], v[184:187], v[112:115]
	v_mfma_f32_16x16x32_bf16 v[100:103], v[162:165], v[192:195], v[100:103]
	v_mfma_f32_16x16x32_bf16 v[96:99], v[176:179], v[192:195], v[96:99]
	v_mfma_f32_16x16x32_bf16 v[84:87], v[162:165], v[200:203], v[84:87]
	v_mfma_f32_16x16x32_bf16 v[80:83], v[176:179], v[200:203], v[80:83]
	v_mfma_f32_16x16x32_bf16 v[68:71], v[162:165], v[208:211], v[68:71]
	v_mfma_f32_16x16x32_bf16 v[64:67], v[176:179], v[208:211], v[64:67]
	v_mfma_f32_16x16x32_bf16 v[116:119], v[172:175], v[188:191], v[116:119]
	v_mfma_f32_16x16x32_bf16 v[112:115], v[180:183], v[188:191], v[112:115]
	v_mfma_f32_16x16x32_bf16 v[100:103], v[172:175], v[196:199], v[100:103]
	v_mfma_f32_16x16x32_bf16 v[96:99], v[180:183], v[196:199], v[96:99]
	v_mfma_f32_16x16x32_bf16 v[84:87], v[172:175], v[204:207], v[84:87]
	v_mfma_f32_16x16x32_bf16 v[80:83], v[180:183], v[204:207], v[80:83]
	v_mfma_f32_16x16x32_bf16 v[68:71], v[172:175], v[212:215], v[68:71]
	v_mfma_f32_16x16x32_bf16 v[64:67], v[180:183], v[212:215], v[64:67]
	s_setprio 0
	s_barrier
	s_add_i32 s71, s58, s3
	v_lshl_add_u64 v[216:217], s[34:35], 0, v[130:131]
	s_mov_b32 m0, s71
	ds_read_b128 v[184:187], v170 offset:16384
	ds_read_b128 v[188:191], v170 offset:17408
	ds_read_b128 v[192:195], v170 offset:18432
	ds_read_b128 v[196:199], v170 offset:19456
	ds_read_b128 v[200:203], v170 offset:20480
	ds_read_b128 v[204:207], v170 offset:21504
	ds_read_b128 v[208:211], v170 offset:22528
	ds_read_b128 v[212:215], v170 offset:23552
	global_load_lds_dwordx4 v[216:217], off
	s_add_i32 m0, s71, 0x2000
	s_add_u32 s72, s34, 0xb0000
	v_lshl_add_u64 v[218:219], s[34:35], 0, v[134:135]
	s_addc_u32 s73, s35, 0
	s_add_i32 s71, s59, s3
	global_load_lds_dwordx4 v[218:219], off
	v_lshl_add_u64 v[220:221], s[72:73], 0, v[130:131]
	s_mov_b32 m0, s71
	v_lshl_add_u64 v[222:223], s[36:37], 0, v[132:133]
	global_load_lds_dwordx4 v[220:221], off
	v_lshl_add_u64 v[220:221], s[72:73], 0, v[134:135]
	s_add_i32 m0, s71, 0x2000
	s_nop 0
	global_load_lds_dwordx4 v[220:221], off
	v_lshl_add_u64 v[220:221], s[36:37], 0, v[128:129]
	s_mov_b32 m0, s38
	s_nop 0
	global_load_lds_dwordx4 v[220:221], off
	s_mov_b32 m0, s39
	s_nop 0
	global_load_lds_dwordx4 v[222:223], off
	s_waitcnt vmcnt(8)
	s_waitcnt lgkmcnt(0)
	s_barrier
; #define PG8_STAGE(bufoff, gbase, voff) do { _Pragma("unroll") for (int _i = 0; _i < 2; ++_i) \
;         __builtin_amdgcn_global_load_lds((const unsigned*)((const char*)(gbase) + (voff)[_i]), (PG8_LAS unsigned*)(lds + (bufoff) + ldsw + _i * 8192), 16, 0, 0); } while (0)
; #define PG8_LDA(dst, b, h) do { _Pragma("unroll") for (int m = 0; m < 4; ++m) _Pragma("unroll") for (int k = 0; k < 2; ++k) dst[m][k] = *(const PG8_LAS bf16x8*)(lds + PG8_SA(b, h) + aoff + m * 2048 + k * 1024); } while (0)
; #define PG8_LDB(dst, b, h) do { _Pragma("unroll") for (int n = 0; n < 2; ++n) _Pragma("unroll") for (int k = 0; k < 2; ++k) dst[n][k] = *(const PG8_LAS bf16x8*)(lds + PG8_SB(b, h) + boff + n * 2048 + k * 1024); } while (0)
; #define PG8_MMA(ai, bj, At, Bt) do { __builtin_amdgcn_s_setprio(1); _Pragma("unroll") for (int m = 0; m < 4; ++m) _Pragma("unroll") for (int n = 0; n < 2; ++n) _Pragma("unroll") for (int k = 0; k < 2; ++k) \
;         acc[ai][bj][m][n] = __builtin_amdgcn_mfma_f32_16x16x32_bf16(Bt[n][k], At[m][k], acc[ai][bj][m][n], 0, 0, 0); __builtin_amdgcn_s_setprio(0); } while (0)
; #define PG8_WAIT_V(n) asm volatile("s_waitcnt vmcnt(" #n ")" ::: "memory")
; #define PG8_WAIT_L(n) asm volatile("s_waitcnt lgkmcnt(" #n ")" ::: "memory")
; #define PG8_BAR __builtin_amdgcn_s_barrier()
; #define PG8_SCHED __builtin_amdgcn_sched_barrier(0)
; template <class Epi, class Sched, bool ALIGN_EPI = false, bool SP2 = false>
; __device__ __forceinline__ void gemm_phase(PG8_LAS unsigned char* lds, const Gemm g, const Sched& S, const Epi& E) {
;     ...
;             PG8_WAIT_V(8); PG8_WAIT_L(0); PG8_BAR; PG8_MMA(1, 0, At, B0); PG8_MMA(1, 1, At, B1); PG8_BAR; PG8_SCHED;
;             PG8_LDB(B0, 1, 0); PG8_LDB(B1, 1, 1); PG8_SCHED; PG8_LDA(At, 1, 0); PG8_STAGE(PG8_SA(0, 1), a2 + hstep, voffA);
;             PG8_WAIT_V(8); PG8_WAIT_L(0); PG8_BAR; PG8_MMA(0, 0, At, B0); PG8_MMA(0, 1, At, B1); PG8_BAR; PG8_SCHED;
	s_setprio 1
	s_waitcnt lgkmcnt(0)
	v_mfma_f32_16x16x32_bf16 v[60:63], v[144:147], v[184:187], v[60:63]
	v_mfma_f32_16x16x32_bf16 v[56:59], v[152:155], v[184:187], v[56:59]
	v_mfma_f32_16x16x32_bf16 v[44:47], v[144:147], v[192:195], v[44:47]
	v_mfma_f32_16x16x32_bf16 v[40:43], v[152:155], v[192:195], v[40:43]
	v_mfma_f32_16x16x32_bf16 v[28:31], v[144:147], v[200:203], v[28:31]
	v_mfma_f32_16x16x32_bf16 v[24:27], v[152:155], v[200:203], v[24:27]
	v_mfma_f32_16x16x32_bf16 v[12:15], v[144:147], v[208:211], v[12:15]
	v_mfma_f32_16x16x32_bf16 v[8:11], v[152:155], v[208:211], v[8:11]
	v_mfma_f32_16x16x32_bf16 v[60:63], v[148:151], v[188:191], v[60:63]
	v_mfma_f32_16x16x32_bf16 v[56:59], v[156:159], v[188:191], v[56:59]
	v_mfma_f32_16x16x32_bf16 v[44:47], v[148:151], v[196:199], v[44:47]
	v_mfma_f32_16x16x32_bf16 v[40:43], v[156:159], v[196:199], v[40:43]
	v_mfma_f32_16x16x32_bf16 v[28:31], v[148:151], v[204:207], v[28:31]
	v_mfma_f32_16x16x32_bf16 v[24:27], v[156:159], v[204:207], v[24:27]
	v_mfma_f32_16x16x32_bf16 v[12:15], v[148:151], v[212:215], v[12:15]
	v_mfma_f32_16x16x32_bf16 v[8:11], v[156:159], v[212:215], v[8:11]
	s_setprio 0
	s_setprio 1
	v_mfma_f32_16x16x32_bf16 v[52:55], v[162:165], v[184:187], v[52:55]
	v_mfma_f32_16x16x32_bf16 v[48:51], v[176:179], v[184:187], v[48:51]
	v_mfma_f32_16x16x32_bf16 v[36:39], v[162:165], v[192:195], v[36:39]
	v_mfma_f32_16x16x32_bf16 v[32:35], v[176:179], v[192:195], v[32:35]
	v_mfma_f32_16x16x32_bf16 v[20:23], v[162:165], v[200:203], v[20:23]
	v_mfma_f32_16x16x32_bf16 v[16:19], v[176:179], v[200:203], v[16:19]
	v_mfma_f32_16x16x32_bf16 v[4:7], v[162:165], v[208:211], v[4:7]
	v_mfma_f32_16x16x32_bf16 v[0:3], v[176:179], v[208:211], v[0:3]
	v_mfma_f32_16x16x32_bf16 v[52:55], v[172:175], v[188:191], v[52:55]
	v_mfma_f32_16x16x32_bf16 v[48:51], v[180:183], v[188:191], v[48:51]
	v_mfma_f32_16x16x32_bf16 v[36:39], v[172:175], v[196:199], v[36:39]
	v_mfma_f32_16x16x32_bf16 v[32:35], v[180:183], v[196:199], v[32:35]
	v_mfma_f32_16x16x32_bf16 v[20:23], v[172:175], v[204:207], v[20:23]
	v_mfma_f32_16x16x32_bf16 v[16:19], v[180:183], v[204:207], v[16:19]
	v_mfma_f32_16x16x32_bf16 v[4:7], v[172:175], v[212:215], v[4:7]
	v_mfma_f32_16x16x32_bf16 v[0:3], v[180:183], v[212:215], v[0:3]
	s_setprio 0
	s_barrier
	s_add_i32 s71, 0, 0x18000
	s_add_i32 s72, 0, 0x1c000
	v_add_u32_e32 v156, s71, v166
	v_add_u32_e32 v180, s72, v166
	ds_read_b128 v[144:147], v156
	ds_read_b128 v[148:151], v156 offset:1024
	ds_read_b128 v[152:155], v156 offset:2048
	ds_read_b128 v[156:159], v156 offset:3072
	ds_read_b128 v[162:165], v180
	ds_read_b128 v[172:175], v180 offset:1024
	ds_read_b128 v[176:179], v180 offset:2048
	ds_read_b128 v[180:183], v180 offset:3072
	s_add_u32 s36, s36, 0xb0000
	s_addc_u32 s37, s37, 0
	s_mov_b32 m0, s40
	v_lshl_add_u64 v[224:225], s[36:37], 0, v[128:129]
	ds_read_b128 v[184:187], v170 offset:32768
	ds_read_b128 v[188:191], v170 offset:33792
	ds_read_b128 v[192:195], v170 offset:34816
	ds_read_b128 v[196:199], v170 offset:35840
	ds_read_b128 v[200:203], v170 offset:36864
	ds_read_b128 v[204:207], v170 offset:37888
	ds_read_b128 v[208:211], v170 offset:38912
	ds_read_b128 v[212:215], v170 offset:39936
	global_load_lds_dwordx4 v[224:225], off
	v_lshl_add_u64 v[224:225], s[36:37], 0, v[132:133]
	s_mov_b32 m0, s41
	s_nop 0
	global_load_lds_dwordx4 v[224:225], off
	s_waitcnt vmcnt(8)
	s_waitcnt lgkmcnt(0)
	s_barrier
	s_setprio 1
	s_waitcnt lgkmcnt(0)
	v_mfma_f32_16x16x32_bf16 v[124:127], v[144:147], v[184:187], v[124:127]
	v_mfma_f32_16x16x32_bf16 v[120:123], v[152:155], v[184:187], v[120:123]
	v_mfma_f32_16x16x32_bf16 v[108:111], v[144:147], v[192:195], v[108:111]
	v_mfma_f32_16x16x32_bf16 v[104:107], v[152:155], v[192:195], v[104:107]
	v_mfma_f32_16x16x32_bf16 v[92:95], v[144:147], v[200:203], v[92:95]
	v_mfma_f32_16x16x32_bf16 v[88:91], v[152:155], v[200:203], v[88:91]
	v_mfma_f32_16x16x32_bf16 v[76:79], v[144:147], v[208:211], v[76:79]
	v_mfma_f32_16x16x32_bf16 v[72:75], v[152:155], v[208:211], v[72:75]
	v_mfma_f32_16x16x32_bf16 v[124:127], v[148:151], v[188:191], v[124:127]
	v_mfma_f32_16x16x32_bf16 v[120:123], v[156:159], v[188:191], v[120:123]
	v_mfma_f32_16x16x32_bf16 v[108:111], v[148:151], v[196:199], v[108:111]
	v_mfma_f32_16x16x32_bf16 v[104:107], v[156:159], v[196:199], v[104:107]
	v_mfma_f32_16x16x32_bf16 v[92:95], v[148:151], v[204:207], v[92:95]
	v_mfma_f32_16x16x32_bf16 v[88:91], v[156:159], v[204:207], v[88:91]
	v_mfma_f32_16x16x32_bf16 v[76:79], v[148:151], v[212:215], v[76:79]
	v_mfma_f32_16x16x32_bf16 v[72:75], v[156:159], v[212:215], v[72:75]
	s_setprio 0
	s_setprio 1
	v_mfma_f32_16x16x32_bf16 v[116:119], v[162:165], v[184:187], v[116:119]
	v_mfma_f32_16x16x32_bf16 v[112:115], v[176:179], v[184:187], v[112:115]
	v_mfma_f32_16x16x32_bf16 v[100:103], v[162:165], v[192:195], v[100:103]
	v_mfma_f32_16x16x32_bf16 v[96:99], v[176:179], v[192:195], v[96:99]
	v_mfma_f32_16x16x32_bf16 v[84:87], v[162:165], v[200:203], v[84:87]
	v_mfma_f32_16x16x32_bf16 v[80:83], v[176:179], v[200:203], v[80:83]
	v_mfma_f32_16x16x32_bf16 v[68:71], v[162:165], v[208:211], v[68:71]
	v_mfma_f32_16x16x32_bf16 v[64:67], v[176:179], v[208:211], v[64:67]
	v_mfma_f32_16x16x32_bf16 v[116:119], v[172:175], v[188:191], v[116:119]
	v_mfma_f32_16x16x32_bf16 v[112:115], v[180:183], v[188:191], v[112:115]
	v_mfma_f32_16x16x32_bf16 v[100:103], v[172:175], v[196:199], v[100:103]
	v_mfma_f32_16x16x32_bf16 v[96:99], v[180:183], v[196:199], v[96:99]
	v_mfma_f32_16x16x32_bf16 v[84:87], v[172:175], v[204:207], v[84:87]
	v_mfma_f32_16x16x32_bf16 v[80:83], v[180:183], v[204:207], v[80:83]
	v_mfma_f32_16x16x32_bf16 v[68:71], v[172:175], v[212:215], v[68:71]
	v_mfma_f32_16x16x32_bf16 v[64:67], v[180:183], v[212:215], v[64:67]
	s_setprio 0
	s_barrier
; #define PG8_STAGE(bufoff, gbase, voff) do { _Pragma("unroll") for (int _i = 0; _i < 2; ++_i) \
;         __builtin_amdgcn_global_load_lds((const unsigned*)((const char*)(gbase) + (voff)[_i]), (PG8_LAS unsigned*)(lds + (bufoff) + ldsw + _i * 8192), 16, 0, 0); } while (0)
; #define PG8_LDA(dst, b, h) do { _Pragma("unroll") for (int m = 0; m < 4; ++m) _Pragma("unroll") for (int k = 0; k < 2; ++k) dst[m][k] = *(const PG8_LAS bf16x8*)(lds + PG8_SA(b, h) + aoff + m * 2048 + k * 1024); } while (0)
; #define PG8_MMA(ai, bj, At, Bt) do { __builtin_amdgcn_s_setprio(1); _Pragma("unroll") for (int m = 0; m < 4; ++m) _Pragma("unroll") for (int n = 0; n < 2; ++n) _Pragma("unroll") for (int k = 0; k < 2; ++k) \
;         acc[ai][bj][m][n] = __builtin_amdgcn_mfma_f32_16x16x32_bf16(Bt[n][k], At[m][k], acc[ai][bj][m][n], 0, 0, 0); __builtin_amdgcn_s_setprio(0); } while (0)
; #define PG8_WAIT_V(n) asm volatile("s_waitcnt vmcnt(" #n ")" ::: "memory")
; #define PG8_WAIT_L(n) asm volatile("s_waitcnt lgkmcnt(" #n ")" ::: "memory")
; #define PG8_BAR __builtin_amdgcn_s_barrier()
; #define PG8_SCHED __builtin_amdgcn_sched_barrier(0)
; template <class Epi, class Sched, bool ALIGN_EPI = false, bool SP2 = false>
; __device__ __forceinline__ void gemm_phase(PG8_LAS unsigned char* lds, const Gemm g, const Sched& S, const Epi& E) {
;     ...
;             PG8_LDA(At, 1, 1); PG8_STAGE(PG8_SB(1, 0), b3, voffB); PG8_STAGE(PG8_SB(1, 1), b3 + hstep, voffB); PG8_STAGE(PG8_SA(1, 0), a3, voffA);
;             PG8_WAIT_V(8); PG8_WAIT_L(0); PG8_BAR; PG8_MMA(1, 0, At, B0); PG8_MMA(1, 1, At, B1); PG8_BAR; PG8_SCHED;
; __global__ void __launch_bounds__(512, 2) hybrid_fwd(Args args) {
;     ...
;         for (int idx = blk * 512 + tid; idx < 2 * NBIAS; idx += G * 512) { const int bb = idx / NBIAS, col = idx - bb * NBIAS; float sacc = 0.f;
; #pragma unroll
;             for (int kb = 0; kb < 16; ++kb) sacc += BIASP[((size_t)bb * 16 + kb) * NBIAS + col];
	s_add_i32 s36, s71, s3
	v_lshl_add_u64 v[216:217], v[216:217], 0, s[16:17]
	s_mov_b32 m0, s36
	ds_read_b128 v[184:187], v170 offset:49152
	ds_read_b128 v[188:191], v170 offset:50176
	ds_read_b128 v[192:195], v170 offset:51200
	ds_read_b128 v[196:199], v170 offset:52224
	ds_read_b128 v[200:203], v170 offset:53248
	ds_read_b128 v[204:207], v170 offset:54272
	ds_read_b128 v[208:211], v170 offset:55296
	ds_read_b128 v[212:215], v170 offset:56320
	global_load_lds_dwordx4 v[216:217], off
	s_add_i32 m0, s36, 0x2000
	s_add_u32 s34, s34, 0xb0080
	v_lshl_add_u64 v[216:217], v[218:219], 0, s[16:17]
	s_addc_u32 s35, s35, 0
	s_add_i32 s36, s72, s3
	global_load_lds_dwordx4 v[216:217], off
	v_lshl_add_u64 v[216:217], s[34:35], 0, v[130:131]
	s_mov_b32 m0, s36
	s_nop 0
	global_load_lds_dwordx4 v[216:217], off
	v_lshl_add_u64 v[216:217], s[34:35], 0, v[134:135]
	s_add_i32 m0, s36, 0x2000
	s_nop 0
	global_load_lds_dwordx4 v[216:217], off
	v_lshl_add_u64 v[216:217], v[220:221], 0, s[16:17]
	s_mov_b32 m0, s53
	s_nop 0
	global_load_lds_dwordx4 v[216:217], off
	v_lshl_add_u64 v[216:217], v[222:223], 0, s[16:17]
	s_mov_b32 m0, s54
	s_nop 0
	global_load_lds_dwordx4 v[216:217], off
	s_waitcnt vmcnt(8)
	s_waitcnt lgkmcnt(0)
	s_barrier
	s_setprio 1
	s_waitcnt lgkmcnt(0)
	v_mfma_f32_16x16x32_bf16 v[60:63], v[144:147], v[184:187], v[60:63]
	v_mfma_f32_16x16x32_bf16 v[56:59], v[152:155], v[184:187], v[56:59]
	v_mfma_f32_16x16x32_bf16 v[44:47], v[144:147], v[192:195], v[44:47]
	v_mfma_f32_16x16x32_bf16 v[40:43], v[152:155], v[192:195], v[40:43]
	v_mfma_f32_16x16x32_bf16 v[28:31], v[144:147], v[200:203], v[28:31]
	v_mfma_f32_16x16x32_bf16 v[24:27], v[152:155], v[200:203], v[24:27]
	v_mfma_f32_16x16x32_bf16 v[12:15], v[144:147], v[208:211], v[12:15]
	v_mfma_f32_16x16x32_bf16 v[8:11], v[152:155], v[208:211], v[8:11]
	v_mfma_f32_16x16x32_bf16 v[60:63], v[148:151], v[188:191], v[60:63]
	v_mfma_f32_16x16x32_bf16 v[56:59], v[156:159], v[188:191], v[56:59]
	v_mfma_f32_16x16x32_bf16 v[44:47], v[148:151], v[196:199], v[44:47]
	v_mfma_f32_16x16x32_bf16 v[40:43], v[156:159], v[196:199], v[40:43]
	v_mfma_f32_16x16x32_bf16 v[28:31], v[148:151], v[204:207], v[28:31]
	v_mfma_f32_16x16x32_bf16 v[24:27], v[156:159], v[204:207], v[24:27]
	v_mfma_f32_16x16x32_bf16 v[12:15], v[148:151], v[212:215], v[12:15]
	v_mfma_f32_16x16x32_bf16 v[8:11], v[156:159], v[212:215], v[8:11]
	s_setprio 0
	s_setprio 1
	v_mfma_f32_16x16x32_bf16 v[52:55], v[162:165], v[184:187], v[52:55]
	v_mfma_f32_16x16x32_bf16 v[48:51], v[176:179], v[184:187], v[48:51]
	v_mfma_f32_16x16x32_bf16 v[36:39], v[162:165], v[192:195], v[36:39]
	v_mfma_f32_16x16x32_bf16 v[32:35], v[176:179], v[192:195], v[32:35]
	v_mfma_f32_16x16x32_bf16 v[20:23], v[162:165], v[200:203], v[20:23]
	v_mfma_f32_16x16x32_bf16 v[16:19], v[176:179], v[200:203], v[16:19]
	v_mfma_f32_16x16x32_bf16 v[4:7], v[162:165], v[208:211], v[4:7]
	v_mfma_f32_16x16x32_bf16 v[0:3], v[176:179], v[208:211], v[0:3]
	v_mfma_f32_16x16x32_bf16 v[52:55], v[172:175], v[188:191], v[52:55]
	v_mfma_f32_16x16x32_bf16 v[48:51], v[180:183], v[188:191], v[48:51]
	v_mfma_f32_16x16x32_bf16 v[36:39], v[172:175], v[196:199], v[36:39]
	v_mfma_f32_16x16x32_bf16 v[32:35], v[180:183], v[196:199], v[32:35]
	v_mfma_f32_16x16x32_bf16 v[20:23], v[172:175], v[204:207], v[20:23]
	v_mfma_f32_16x16x32_bf16 v[16:19], v[180:183], v[204:207], v[16:19]
	v_mfma_f32_16x16x32_bf16 v[4:7], v[172:175], v[212:215], v[4:7]
	v_mfma_f32_16x16x32_bf16 v[0:3], v[180:183], v[212:215], v[0:3]
	s_setprio 0
	s_add_i32 s70, s70, 2
	s_add_u32 s22, s22, 0x100
	s_addc_u32 s23, s23, 0
	s_add_u32 s66, s66, 0x100
	s_addc_u32 s67, s67, 0
	s_cmp_gt_u32 s70, 41
	s_barrier
	s_cbranch_scc0 .LBB0_289
	s_cmp_lt_u32 s2, 38
	s_cbranch_scc0 .Lp3_bias_noload
	s_cmp_ge_u32 s2, 19
	s_cselect_b32 s99, 0x98000, 0
	s_cselect_b32 s100, 19, 0
	s_sub_i32 s100, s2, s100
	s_lshl_b32 s100, s100, 11
	s_add_u32 s100, s100, s99
	s_add_u32 s100, s100, 0xe800000
	s_add_u32 s100, s86, s100
	s_addc_u32 s101, s87, 0
	v_lshlrev_b32_e32 v227, 2, v226
	global_load_dword v228, v227, s[100:101]
	s_add_u32 s100, s100, 0x9800
	s_addc_u32 s101, s101, 0
	global_load_dword v229, v227, s[100:101]
	s_add_u32 s100, s100, 0x9800
	s_addc_u32 s101, s101, 0
	global_load_dword v230, v227, s[100:101]
	s_add_u32 s100, s100, 0x9800
	s_addc_u32 s101, s101, 0
	global_load_dword v231, v227, s[100:101]
	s_add_u32 s100, s100, 0x9800
	s_addc_u32 s101, s101, 0
	global_load_dword v232, v227, s[100:101]
	s_add_u32 s100, s100, 0x9800
	s_addc_u32 s101, s101, 0
	global_load_dword v233, v227, s[100:101]
	s_add_u32 s100, s100, 0x9800
	s_addc_u32 s101, s101, 0
	global_load_dword v234, v227, s[100:101]
	s_add_u32 s100, s100, 0x9800
	s_addc_u32 s101, s101, 0
	global_load_dword v235, v227, s[100:101]
	s_add_u32 s100, s100, 0x9800
	s_addc_u32 s101, s101, 0
	global_load_dword v236, v227, s[100:101]
	s_add_u32 s100, s100, 0x9800
	s_addc_u32 s101, s101, 0
	global_load_dword v237, v227, s[100:101]
	s_add_u32 s100, s100, 0x9800
	s_addc_u32 s101, s101, 0
	global_load_dword v238, v227, s[100:101]
	s_add_u32 s100, s100, 0x9800
	s_addc_u32 s101, s101, 0
	global_load_dword v239, v227, s[100:101]
	s_add_u32 s100, s100, 0x9800
	s_addc_u32 s101, s101, 0
	global_load_dword v240, v227, s[100:101]
	s_add_u32 s100, s100, 0x9800
	s_addc_u32 s101, s101, 0
	global_load_dword v241, v227, s[100:101]
	s_add_u32 s100, s100, 0x9800
	s_addc_u32 s101, s101, 0
	global_load_dword v242, v227, s[100:101]
	s_add_u32 s100, s100, 0x9800
	s_addc_u32 s101, s101, 0
	global_load_dword v243, v227, s[100:101]

; #define PG8_STAGE(bufoff, gbase, voff) do { _Pragma("unroll") for (int _i = 0; _i < 2; ++_i) \
;         __builtin_amdgcn_global_load_lds((const unsigned*)((const char*)(gbase) + (voff)[_i]), (PG8_LAS unsigned*)(lds + (bufoff) + ldsw + _i * 8192), 16, 0, 0); } while (0)
; #define PG8_LDA(dst, b, h) do { _Pragma("unroll") for (int m = 0; m < 4; ++m) _Pragma("unroll") for (int k = 0; k < 2; ++k) dst[m][k] = *(const PG8_LAS bf16x8*)(lds + PG8_SA(b, h) + aoff + m * 2048 + k * 1024); } while (0)
; #define PG8_LDB(dst, b, h) do { _Pragma("unroll") for (int n = 0; n < 2; ++n) _Pragma("unroll") for (int k = 0; k < 2; ++k) dst[n][k] = *(const PG8_LAS bf16x8*)(lds + PG8_SB(b, h) + boff + n * 2048 + k * 1024); } while (0)
; #define PG8_MMA(ai, bj, At, Bt) do { __builtin_amdgcn_s_setprio(1); _Pragma("unroll") for (int m = 0; m < 4; ++m) _Pragma("unroll") for (int n = 0; n < 2; ++n) _Pragma("unroll") for (int k = 0; k < 2; ++k) \
;         acc[ai][bj][m][n] = __builtin_amdgcn_mfma_f32_16x16x32_bf16(Bt[n][k], At[m][k], acc[ai][bj][m][n], 0, 0, 0); __builtin_amdgcn_s_setprio(0); } while (0)
; #define PG8_WAIT_V(n) asm volatile("s_waitcnt vmcnt(" #n ")" ::: "memory")
; #define PG8_WAIT_L(n) asm volatile("s_waitcnt lgkmcnt(" #n ")" ::: "memory")
; #define PG8_BAR __builtin_amdgcn_s_barrier()
; #define PG8_SCHED __builtin_amdgcn_sched_barrier(0)
; template <class Epi, class Sched, bool ALIGN_EPI = false, bool SP2 = false>
; __device__ __forceinline__ void gemm_phase(PG8_LAS unsigned char* lds, const Gemm g, const Sched& S, const Epi& E) {
;     ...
;             const bool last = (t == nt - 2);
;             const char* a1 = cA + (size_t)(t + 1) * kstep;
;             const char* a2 = last ? nA : cA + (size_t)(t + 2) * kstep; const char* b2 = last ? nB : cB + (size_t)(t + 2) * kstep;
;             const char* a3 = a2 + kstep; const char* b3 = b2 + kstep;
;             if (last && has_next) S.a_ready(nxt);
;             if constexpr (SP2) {
;             PG8_LDB(B0, 0, 0); PG8_LDB(B1, 0, 1); PG8_SCHED; PG8_LDA(At, 0, 0); PG8_STAGE(PG8_SA(1, 1), a1 + hstep, voffA);
;             PG8_WAIT_V(8); PG8_WAIT_L(0); PG8_BAR; PG8_MMA(0, 0, At, B0); PG8_MMA(0, 1, At, B1); PG8_BAR; PG8_SCHED;
;             PG8_LDA(At, 0, 1); PG8_STAGE(PG8_SB(0, 0), b2, voffB); PG8_STAGE(PG8_SB(0, 1), b2 + hstep, voffB); PG8_STAGE(PG8_SA(0, 0), a2, voffA);
.LBB0_407:
	ds_read_b128 v[24:27], v189
	ds_read_b128 v[28:31], v189 offset:1024
	ds_read_b128 v[36:39], v189 offset:2048
	ds_read_b128 v[44:47], v189 offset:3072
	ds_read_b128 v[48:51], v190
	ds_read_b128 v[52:55], v190 offset:1024
	ds_read_b128 v[56:59], v190 offset:2048
	ds_read_b128 v[60:63], v190 offset:3072
	s_add_u32 s48, s0, 0xfffc0080
	s_addc_u32 s49, s1, -1
	s_cmp_eq_u32 s55, 12
	s_cselect_b32 s53, s7, s49
	s_cselect_b32 s52, s9, s48
	s_cselect_b32 s49, s12, s54
	s_cselect_b32 s48, s23, s41
	v_lshl_add_u64 v[184:185], s[0:1], 0, v[176:177]
	s_add_i32 m0, s60, 0xc000
	ds_read_b128 v[196:199], v191
	ds_read_b128 v[200:203], v191 offset:1024
	ds_read_b128 v[204:207], v191 offset:2048
	ds_read_b128 v[208:211], v191 offset:3072
	ds_read_b128 v[212:215], v191 offset:4096
	ds_read_b128 v[216:219], v191 offset:5120
	ds_read_b128 v[220:223], v191 offset:6144
	ds_read_b128 v[228:231], v191 offset:7168
	global_load_lds_dwordx4 v[184:185], off
	v_lshl_add_u64 v[184:185], s[0:1], 0, v[178:179]
	s_add_i32 m0, s60, 0xe000
	s_nop 0
	global_load_lds_dwordx4 v[184:185], off
	s_waitcnt vmcnt(8)
	s_waitcnt lgkmcnt(0)
	s_barrier
	s_setprio 1
	s_waitcnt lgkmcnt(0)
	v_mfma_f32_16x16x32_bf16 v[156:159], v[24:27], v[196:199], v[156:159]
	v_mfma_f32_16x16x32_bf16 v[152:155], v[36:39], v[196:199], v[152:155]
	v_mfma_f32_16x16x32_bf16 v[140:143], v[24:27], v[204:207], v[140:143]
	v_mfma_f32_16x16x32_bf16 v[136:139], v[36:39], v[204:207], v[136:139]
	v_mfma_f32_16x16x32_bf16 v[124:127], v[24:27], v[212:215], v[124:127]
	v_mfma_f32_16x16x32_bf16 v[120:123], v[36:39], v[212:215], v[120:123]
	v_mfma_f32_16x16x32_bf16 v[108:111], v[24:27], v[220:223], v[108:111]
	v_mfma_f32_16x16x32_bf16 v[104:107], v[36:39], v[220:223], v[104:107]
	v_mfma_f32_16x16x32_bf16 v[156:159], v[28:31], v[200:203], v[156:159]
	v_mfma_f32_16x16x32_bf16 v[152:155], v[44:47], v[200:203], v[152:155]
	v_mfma_f32_16x16x32_bf16 v[140:143], v[28:31], v[208:211], v[140:143]
	v_mfma_f32_16x16x32_bf16 v[136:139], v[44:47], v[208:211], v[136:139]
	v_mfma_f32_16x16x32_bf16 v[124:127], v[28:31], v[216:219], v[124:127]
	v_mfma_f32_16x16x32_bf16 v[120:123], v[44:47], v[216:219], v[120:123]
	v_mfma_f32_16x16x32_bf16 v[108:111], v[28:31], v[228:231], v[108:111]
	v_mfma_f32_16x16x32_bf16 v[104:107], v[44:47], v[228:231], v[104:107]
	s_setprio 0
	s_setprio 1
	v_mfma_f32_16x16x32_bf16 v[148:151], v[48:51], v[196:199], v[148:151]
	v_mfma_f32_16x16x32_bf16 v[144:147], v[56:59], v[196:199], v[144:147]
	v_mfma_f32_16x16x32_bf16 v[132:135], v[48:51], v[204:207], v[132:135]
	v_mfma_f32_16x16x32_bf16 v[128:131], v[56:59], v[204:207], v[128:131]
	v_mfma_f32_16x16x32_bf16 v[116:119], v[48:51], v[212:215], v[116:119]
	v_mfma_f32_16x16x32_bf16 v[112:115], v[56:59], v[212:215], v[112:115]
	v_mfma_f32_16x16x32_bf16 v[100:103], v[48:51], v[220:223], v[100:103]
	v_mfma_f32_16x16x32_bf16 v[96:99], v[56:59], v[220:223], v[96:99]
	v_mfma_f32_16x16x32_bf16 v[148:151], v[52:55], v[200:203], v[148:151]
	v_mfma_f32_16x16x32_bf16 v[144:147], v[60:63], v[200:203], v[144:147]
	v_mfma_f32_16x16x32_bf16 v[132:135], v[52:55], v[208:211], v[132:135]
	v_mfma_f32_16x16x32_bf16 v[128:131], v[60:63], v[208:211], v[128:131]
	v_mfma_f32_16x16x32_bf16 v[116:119], v[52:55], v[216:219], v[116:119]
	v_mfma_f32_16x16x32_bf16 v[112:115], v[60:63], v[216:219], v[112:115]
	v_mfma_f32_16x16x32_bf16 v[100:103], v[52:55], v[228:231], v[100:103]
	v_mfma_f32_16x16x32_bf16 v[96:99], v[60:63], v[228:231], v[96:99]
	s_setprio 0
	s_barrier
	s_add_i32 s56, s74, s59
	v_lshl_add_u64 v[184:185], s[48:49], 0, v[164:165]
	s_mov_b32 m0, s56
	ds_read_b128 v[196:199], v191 offset:16384
	ds_read_b128 v[200:203], v191 offset:17408
	ds_read_b128 v[204:207], v191 offset:18432
	ds_read_b128 v[208:211], v191 offset:19456
	ds_read_b128 v[212:215], v191 offset:20480
	ds_read_b128 v[216:219], v191 offset:21504
	ds_read_b128 v[220:223], v191 offset:22528
	ds_read_b128 v[228:231], v191 offset:23552
	global_load_lds_dwordx4 v[184:185], off
	s_add_i32 m0, s56, 0x2000
	s_add_u32 s56, s48, 0x40000
	v_lshl_add_u64 v[224:225], s[48:49], 0, v[168:169]
	s_addc_u32 s57, s49, 0
	s_add_i32 s79, s75, s59
	global_load_lds_dwordx4 v[224:225], off
	v_lshl_add_u64 v[232:233], s[56:57], 0, v[164:165]
	s_mov_b32 m0, s79
	v_lshl_add_u64 v[240:241], s[52:53], 0, v[162:163]
	global_load_lds_dwordx4 v[232:233], off
	v_lshl_add_u64 v[232:233], s[56:57], 0, v[168:169]
	s_add_i32 m0, s79, 0x2000
	v_lshl_add_u64 v[242:243], s[52:53], 0, v[166:167]
	global_load_lds_dwordx4 v[232:233], off
	s_mov_b32 m0, s60
	s_nop 0
	global_load_lds_dwordx4 v[240:241], off
	s_mov_b32 m0, s61
	s_nop 0
	global_load_lds_dwordx4 v[242:243], off
	s_waitcnt vmcnt(8)
	s_waitcnt lgkmcnt(0)
	s_barrier
; #define PG8_STAGE(bufoff, gbase, voff) do { _Pragma("unroll") for (int _i = 0; _i < 2; ++_i) \
;         __builtin_amdgcn_global_load_lds((const unsigned*)((const char*)(gbase) + (voff)[_i]), (PG8_LAS unsigned*)(lds + (bufoff) + ldsw + _i * 8192), 16, 0, 0); } while (0)
; #define PG8_LDA(dst, b, h) do { _Pragma("unroll") for (int m = 0; m < 4; ++m) _Pragma("unroll") for (int k = 0; k < 2; ++k) dst[m][k] = *(const PG8_LAS bf16x8*)(lds + PG8_SA(b, h) + aoff + m * 2048 + k * 1024); } while (0)
; #define PG8_LDB(dst, b, h) do { _Pragma("unroll") for (int n = 0; n < 2; ++n) _Pragma("unroll") for (int k = 0; k < 2; ++k) dst[n][k] = *(const PG8_LAS bf16x8*)(lds + PG8_SB(b, h) + boff + n * 2048 + k * 1024); } while (0)
; #define PG8_MMA(ai, bj, At, Bt) do { __builtin_amdgcn_s_setprio(1); _Pragma("unroll") for (int m = 0; m < 4; ++m) _Pragma("unroll") for (int n = 0; n < 2; ++n) _Pragma("unroll") for (int k = 0; k < 2; ++k) \
;         acc[ai][bj][m][n] = __builtin_amdgcn_mfma_f32_16x16x32_bf16(Bt[n][k], At[m][k], acc[ai][bj][m][n], 0, 0, 0); __builtin_amdgcn_s_setprio(0); } while (0)
; #define PG8_WAIT_V(n) asm volatile("s_waitcnt vmcnt(" #n ")" ::: "memory")
; #define PG8_WAIT_L(n) asm volatile("s_waitcnt lgkmcnt(" #n ")" ::: "memory")
; #define PG8_BAR __builtin_amdgcn_s_barrier()
; #define PG8_SCHED __builtin_amdgcn_sched_barrier(0)
; template <class Epi, class Sched, bool ALIGN_EPI = false, bool SP2 = false>
; __device__ __forceinline__ void gemm_phase(PG8_LAS unsigned char* lds, const Gemm g, const Sched& S, const Epi& E) {
;     ...
;             PG8_WAIT_V(8); PG8_WAIT_L(0); PG8_BAR; PG8_MMA(1, 0, At, B0); PG8_MMA(1, 1, At, B1); PG8_BAR; PG8_SCHED;
;             PG8_LDB(B0, 1, 0); PG8_LDB(B1, 1, 1); PG8_SCHED; PG8_LDA(At, 1, 0); PG8_STAGE(PG8_SA(0, 1), a2 + hstep, voffA);
;             PG8_WAIT_V(8); PG8_WAIT_L(0); PG8_BAR; PG8_MMA(0, 0, At, B0); PG8_MMA(0, 1, At, B1); PG8_BAR; PG8_SCHED;
	s_setprio 1
	s_waitcnt lgkmcnt(0)
	v_mfma_f32_16x16x32_bf16 v[92:95], v[24:27], v[196:199], v[92:95]
	v_mfma_f32_16x16x32_bf16 v[88:91], v[36:39], v[196:199], v[88:91]
	v_mfma_f32_16x16x32_bf16 v[76:79], v[24:27], v[204:207], v[76:79]
	v_mfma_f32_16x16x32_bf16 v[72:75], v[36:39], v[204:207], v[72:75]
	v_mfma_f32_16x16x32_bf16 v[40:43], v[24:27], v[212:215], v[40:43]
	v_mfma_f32_16x16x32_bf16 v[32:35], v[36:39], v[212:215], v[32:35]
	v_mfma_f32_16x16x32_bf16 v[12:15], v[24:27], v[220:223], v[12:15]
	v_mfma_f32_16x16x32_bf16 v[8:11], v[36:39], v[220:223], v[8:11]
	v_mfma_f32_16x16x32_bf16 v[92:95], v[28:31], v[200:203], v[92:95]
	v_mfma_f32_16x16x32_bf16 v[88:91], v[44:47], v[200:203], v[88:91]
	v_mfma_f32_16x16x32_bf16 v[76:79], v[28:31], v[208:211], v[76:79]
	v_mfma_f32_16x16x32_bf16 v[72:75], v[44:47], v[208:211], v[72:75]
	v_mfma_f32_16x16x32_bf16 v[40:43], v[28:31], v[216:219], v[40:43]
	v_mfma_f32_16x16x32_bf16 v[32:35], v[44:47], v[216:219], v[32:35]
	v_mfma_f32_16x16x32_bf16 v[12:15], v[28:31], v[228:231], v[12:15]
	v_mfma_f32_16x16x32_bf16 v[8:11], v[44:47], v[228:231], v[8:11]
	s_setprio 0
	s_setprio 1
	v_mfma_f32_16x16x32_bf16 v[20:23], v[48:51], v[212:215], v[20:23]
	v_mfma_f32_16x16x32_bf16 v[16:19], v[56:59], v[212:215], v[16:19]
	v_mfma_f32_16x16x32_bf16 v[4:7], v[48:51], v[220:223], v[4:7]
	v_mfma_f32_16x16x32_bf16 v[0:3], v[56:59], v[220:223], v[0:3]
	v_mfma_f32_16x16x32_bf16 v[24:27], v[48:51], v[196:199], v[84:87]
	v_mfma_f32_16x16x32_bf16 v[28:31], v[56:59], v[196:199], v[80:83]
	v_mfma_f32_16x16x32_bf16 v[36:39], v[48:51], v[204:207], v[68:71]
	v_mfma_f32_16x16x32_bf16 v[44:47], v[56:59], v[204:207], v[64:67]
	v_mfma_f32_16x16x32_bf16 v[20:23], v[52:55], v[216:219], v[20:23]
	v_mfma_f32_16x16x32_bf16 v[16:19], v[60:63], v[216:219], v[16:19]
	v_mfma_f32_16x16x32_bf16 v[4:7], v[52:55], v[228:231], v[4:7]
	v_mfma_f32_16x16x32_bf16 v[0:3], v[60:63], v[228:231], v[0:3]
	v_mfma_f32_16x16x32_bf16 v[24:27], v[52:55], v[200:203], v[24:27]
	v_mfma_f32_16x16x32_bf16 v[28:31], v[60:63], v[200:203], v[28:31]
	v_mfma_f32_16x16x32_bf16 v[36:39], v[52:55], v[208:211], v[36:39]
	v_mfma_f32_16x16x32_bf16 v[44:47], v[60:63], v[208:211], v[44:47]
	s_setprio 0
	s_barrier
	s_add_i32 s56, 0, 0x18000
	s_add_i32 s57, 0, 0x1c000
	v_add_u32_e32 v60, s56, v186
	v_add_u32_e32 v64, s57, v186
	ds_read_b128 v[48:51], v60
	ds_read_b128 v[52:55], v60 offset:1024
	ds_read_b128 v[56:59], v60 offset:2048
	ds_read_b128 v[60:63], v60 offset:3072
	ds_read_b128 v[196:199], v64
	ds_read_b128 v[200:203], v64 offset:1024
	ds_read_b128 v[204:207], v64 offset:2048
	ds_read_b128 v[208:211], v64 offset:3072
	s_add_u32 s52, s52, 0x40000
	s_addc_u32 s53, s53, 0
	s_mov_b32 m0, s62
	v_lshl_add_u64 v[232:233], s[52:53], 0, v[162:163]
	ds_read_b128 v[64:67], v191 offset:32768
	ds_read_b128 v[68:71], v191 offset:33792
	ds_read_b128 v[80:83], v191 offset:34816
	ds_read_b128 v[84:87], v191 offset:35840
	ds_read_b128 v[212:215], v191 offset:36864
	ds_read_b128 v[216:219], v191 offset:37888
	ds_read_b128 v[220:223], v191 offset:38912
	ds_read_b128 v[228:231], v191 offset:39936
	global_load_lds_dwordx4 v[232:233], off
	v_lshl_add_u64 v[232:233], s[52:53], 0, v[166:167]
	s_mov_b32 m0, s63
	s_nop 0
	global_load_lds_dwordx4 v[232:233], off
	s_waitcnt vmcnt(8)
	s_waitcnt lgkmcnt(0)
	s_barrier
	s_setprio 1
	s_waitcnt lgkmcnt(0)
	v_mfma_f32_16x16x32_bf16 v[156:159], v[48:51], v[64:67], v[156:159]
	v_mfma_f32_16x16x32_bf16 v[152:155], v[56:59], v[64:67], v[152:155]
	v_mfma_f32_16x16x32_bf16 v[140:143], v[48:51], v[80:83], v[140:143]
	v_mfma_f32_16x16x32_bf16 v[136:139], v[56:59], v[80:83], v[136:139]
	v_mfma_f32_16x16x32_bf16 v[124:127], v[48:51], v[212:215], v[124:127]
	v_mfma_f32_16x16x32_bf16 v[120:123], v[56:59], v[212:215], v[120:123]
	v_mfma_f32_16x16x32_bf16 v[108:111], v[48:51], v[220:223], v[108:111]
	v_mfma_f32_16x16x32_bf16 v[104:107], v[56:59], v[220:223], v[104:107]
	v_mfma_f32_16x16x32_bf16 v[156:159], v[52:55], v[68:71], v[156:159]
	v_mfma_f32_16x16x32_bf16 v[152:155], v[60:63], v[68:71], v[152:155]
	v_mfma_f32_16x16x32_bf16 v[140:143], v[52:55], v[84:87], v[140:143]
	v_mfma_f32_16x16x32_bf16 v[136:139], v[60:63], v[84:87], v[136:139]
	v_mfma_f32_16x16x32_bf16 v[124:127], v[52:55], v[216:219], v[124:127]
	v_mfma_f32_16x16x32_bf16 v[120:123], v[60:63], v[216:219], v[120:123]
	v_mfma_f32_16x16x32_bf16 v[108:111], v[52:55], v[228:231], v[108:111]
	v_mfma_f32_16x16x32_bf16 v[104:107], v[60:63], v[228:231], v[104:107]
	s_setprio 0
	s_setprio 1
	v_mfma_f32_16x16x32_bf16 v[148:151], v[196:199], v[64:67], v[148:151]
	v_mfma_f32_16x16x32_bf16 v[64:67], v[204:207], v[64:67], v[144:147]
	v_mfma_f32_16x16x32_bf16 v[144:147], v[208:211], v[68:71], v[64:67]
	v_mfma_f32_16x16x32_bf16 v[64:67], v[196:199], v[80:83], v[132:135]
	v_mfma_f32_16x16x32_bf16 v[132:135], v[200:203], v[84:87], v[64:67]
	v_mfma_f32_16x16x32_bf16 v[64:67], v[204:207], v[80:83], v[128:131]
	v_mfma_f32_16x16x32_bf16 v[128:131], v[208:211], v[84:87], v[64:67]
	v_mfma_f32_16x16x32_bf16 v[64:67], v[196:199], v[212:215], v[116:119]
	v_mfma_f32_16x16x32_bf16 v[116:119], v[200:203], v[216:219], v[64:67]
	v_mfma_f32_16x16x32_bf16 v[64:67], v[204:207], v[212:215], v[112:115]
	v_mfma_f32_16x16x32_bf16 v[112:115], v[208:211], v[216:219], v[64:67]
	v_mfma_f32_16x16x32_bf16 v[64:67], v[196:199], v[220:223], v[100:103]
	v_mfma_f32_16x16x32_bf16 v[100:103], v[200:203], v[228:231], v[64:67]
	v_mfma_f32_16x16x32_bf16 v[64:67], v[204:207], v[220:223], v[96:99]
	v_mfma_f32_16x16x32_bf16 v[148:151], v[200:203], v[68:71], v[148:151]
	v_mfma_f32_16x16x32_bf16 v[96:99], v[208:211], v[228:231], v[64:67]
	s_setprio 0
	s_barrier
; #define PG8_STAGE(bufoff, gbase, voff) do { _Pragma("unroll") for (int _i = 0; _i < 2; ++_i) \
;         __builtin_amdgcn_global_load_lds((const unsigned*)((const char*)(gbase) + (voff)[_i]), (PG8_LAS unsigned*)(lds + (bufoff) + ldsw + _i * 8192), 16, 0, 0); } while (0)
; #define PG8_LDA(dst, b, h) do { _Pragma("unroll") for (int m = 0; m < 4; ++m) _Pragma("unroll") for (int k = 0; k < 2; ++k) dst[m][k] = *(const PG8_LAS bf16x8*)(lds + PG8_SA(b, h) + aoff + m * 2048 + k * 1024); } while (0)
; #define PG8_MMA(ai, bj, At, Bt) do { __builtin_amdgcn_s_setprio(1); _Pragma("unroll") for (int m = 0; m < 4; ++m) _Pragma("unroll") for (int n = 0; n < 2; ++n) _Pragma("unroll") for (int k = 0; k < 2; ++k) \
;         acc[ai][bj][m][n] = __builtin_amdgcn_mfma_f32_16x16x32_bf16(Bt[n][k], At[m][k], acc[ai][bj][m][n], 0, 0, 0); __builtin_amdgcn_s_setprio(0); } while (0)
; #define PG8_WAIT_V(n) asm volatile("s_waitcnt vmcnt(" #n ")" ::: "memory")
; #define PG8_WAIT_L(n) asm volatile("s_waitcnt lgkmcnt(" #n ")" ::: "memory")
; #define PG8_BAR __builtin_amdgcn_s_barrier()
; #define PG8_SCHED __builtin_amdgcn_sched_barrier(0)
; template <class Epi, class Sched, bool ALIGN_EPI = false, bool SP2 = false>
; __device__ __forceinline__ void gemm_phase(PG8_LAS unsigned char* lds, const Gemm g, const Sched& S, const Epi& E) {
;     ...
;             PG8_LDA(At, 1, 1); PG8_STAGE(PG8_SB(1, 0), b3, voffB); PG8_STAGE(PG8_SB(1, 1), b3 + hstep, voffB); PG8_STAGE(PG8_SA(1, 0), a3, voffA);
;             PG8_WAIT_V(8); PG8_WAIT_L(0); PG8_BAR; PG8_MMA(1, 0, At, B0); PG8_MMA(1, 1, At, B1); PG8_BAR; PG8_SCHED;
;     ...
;         if constexpr (ALIGN_EPI) { if (wr == 0) PG8_BAR; }
	s_add_i32 s52, s56, s59
	v_lshl_add_u64 v[80:81], v[184:185], 0, s[16:17]
	s_mov_b32 m0, s52
	s_nop 0
	ds_read_b128 v[64:67], v191 offset:49152
	ds_read_b128 v[68:71], v191 offset:50176
	ds_read_b128 v[212:215], v191 offset:51200
	ds_read_b128 v[216:219], v191 offset:52224
	ds_read_b128 v[220:223], v191 offset:53248
	ds_read_b128 v[228:231], v191 offset:54272
	ds_read_b128 v[232:235], v191 offset:55296
	ds_read_b128 v[236:239], v191 offset:56320
	global_load_lds_dwordx4 v[80:81], off
	s_add_i32 m0, s52, 0x2000
	s_add_u32 s48, s48, 0x40080
	v_lshl_add_u64 v[80:81], v[224:225], 0, s[16:17]
	s_addc_u32 s49, s49, 0
	s_add_i32 s52, s57, s59
	global_load_lds_dwordx4 v[80:81], off
	v_lshl_add_u64 v[80:81], s[48:49], 0, v[164:165]
	s_mov_b32 m0, s52
	s_nop 0
	global_load_lds_dwordx4 v[80:81], off
	v_lshl_add_u64 v[80:81], s[48:49], 0, v[168:169]
	s_add_i32 m0, s52, 0x2000
	s_nop 0
	global_load_lds_dwordx4 v[80:81], off
	v_lshl_add_u64 v[80:81], v[240:241], 0, s[16:17]
	s_mov_b32 m0, s65
	s_nop 0
	global_load_lds_dwordx4 v[80:81], off
	v_lshl_add_u64 v[80:81], v[242:243], 0, s[16:17]
	s_mov_b32 m0, s68
	s_nop 0
	global_load_lds_dwordx4 v[80:81], off
	s_waitcnt vmcnt(8)
	s_waitcnt lgkmcnt(0)
	s_barrier
	s_setprio 1
	s_waitcnt lgkmcnt(0)
	v_mfma_f32_16x16x32_bf16 v[80:83], v[48:51], v[64:67], v[92:95]
	v_mfma_f32_16x16x32_bf16 v[92:95], v[52:55], v[68:71], v[80:83]
	v_mfma_f32_16x16x32_bf16 v[80:83], v[56:59], v[64:67], v[88:91]
	v_mfma_f32_16x16x32_bf16 v[76:79], v[48:51], v[212:215], v[76:79]
	v_mfma_f32_16x16x32_bf16 v[72:75], v[56:59], v[212:215], v[72:75]
	v_mfma_f32_16x16x32_bf16 v[40:43], v[48:51], v[220:223], v[40:43]
	v_mfma_f32_16x16x32_bf16 v[32:35], v[56:59], v[220:223], v[32:35]
	v_mfma_f32_16x16x32_bf16 v[12:15], v[48:51], v[232:235], v[12:15]
	v_mfma_f32_16x16x32_bf16 v[8:11], v[56:59], v[232:235], v[8:11]
	v_mfma_f32_16x16x32_bf16 v[88:91], v[60:63], v[68:71], v[80:83]
	v_mfma_f32_16x16x32_bf16 v[76:79], v[52:55], v[216:219], v[76:79]
	v_mfma_f32_16x16x32_bf16 v[72:75], v[60:63], v[216:219], v[72:75]
	v_mfma_f32_16x16x32_bf16 v[40:43], v[52:55], v[228:231], v[40:43]
	v_mfma_f32_16x16x32_bf16 v[32:35], v[60:63], v[228:231], v[32:35]
	v_mfma_f32_16x16x32_bf16 v[12:15], v[52:55], v[236:239], v[12:15]
	v_mfma_f32_16x16x32_bf16 v[8:11], v[60:63], v[236:239], v[8:11]
	s_setprio 0
	s_setprio 1
	v_mfma_f32_16x16x32_bf16 v[24:27], v[196:199], v[64:67], v[24:27]
	v_mfma_f32_16x16x32_bf16 v[84:87], v[200:203], v[68:71], v[24:27]
	v_mfma_f32_16x16x32_bf16 v[24:27], v[204:207], v[64:67], v[28:31]
	v_mfma_f32_16x16x32_bf16 v[80:83], v[208:211], v[68:71], v[24:27]
	v_mfma_f32_16x16x32_bf16 v[24:27], v[196:199], v[212:215], v[36:39]
	v_mfma_f32_16x16x32_bf16 v[68:71], v[200:203], v[216:219], v[24:27]
	v_mfma_f32_16x16x32_bf16 v[24:27], v[204:207], v[212:215], v[44:47]
	v_mfma_f32_16x16x32_bf16 v[20:23], v[196:199], v[220:223], v[20:23]
	v_mfma_f32_16x16x32_bf16 v[16:19], v[204:207], v[220:223], v[16:19]
	v_mfma_f32_16x16x32_bf16 v[4:7], v[196:199], v[232:235], v[4:7]
	v_mfma_f32_16x16x32_bf16 v[0:3], v[204:207], v[232:235], v[0:3]
	v_mfma_f32_16x16x32_bf16 v[64:67], v[208:211], v[216:219], v[24:27]
	v_mfma_f32_16x16x32_bf16 v[20:23], v[200:203], v[228:231], v[20:23]
	v_mfma_f32_16x16x32_bf16 v[16:19], v[208:211], v[228:231], v[16:19]
	v_mfma_f32_16x16x32_bf16 v[4:7], v[200:203], v[236:239], v[4:7]
	v_mfma_f32_16x16x32_bf16 v[0:3], v[208:211], v[236:239], v[0:3]
	s_setprio 0
	s_add_i32 s55, s55, 2
	s_add_u32 s0, s0, 0x100
	s_addc_u32 s1, s1, 0
	s_add_u32 s41, s41, 0x100
	s_addc_u32 s54, s54, 0
	s_cmp_gt_u32 s55, 13
	s_barrier
	s_cbranch_scc0 .LBB0_407
	s_and_b64 vcc, exec, s[18:19]
	s_cbranch_vccz .LBB0_410
	s_barrier

; #define PG8_STAGE(bufoff, gbase, voff) do { _Pragma("unroll") for (int _i = 0; _i < 2; ++_i) \
;         __builtin_amdgcn_global_load_lds((const unsigned*)((const char*)(gbase) + (voff)[_i]), (PG8_LAS unsigned*)(lds + (bufoff) + ldsw + _i * 8192), 16, 0, 0); } while (0)
; #define PG8_LDA(dst, b, h) do { _Pragma("unroll") for (int m = 0; m < 4; ++m) _Pragma("unroll") for (int k = 0; k < 2; ++k) dst[m][k] = *(const PG8_LAS bf16x8*)(lds + PG8_SA(b, h) + aoff + m * 2048 + k * 1024); } while (0)
; #define PG8_LDB(dst, b, h) do { _Pragma("unroll") for (int n = 0; n < 2; ++n) _Pragma("unroll") for (int k = 0; k < 2; ++k) dst[n][k] = *(const PG8_LAS bf16x8*)(lds + PG8_SB(b, h) + boff + n * 2048 + k * 1024); } while (0)
; #define PG8_MMA(ai, bj, At, Bt) do { __builtin_amdgcn_s_setprio(1); _Pragma("unroll") for (int m = 0; m < 4; ++m) _Pragma("unroll") for (int n = 0; n < 2; ++n) _Pragma("unroll") for (int k = 0; k < 2; ++k) \
;         acc[ai][bj][m][n] = __builtin_amdgcn_mfma_f32_16x16x32_bf16(Bt[n][k], At[m][k], acc[ai][bj][m][n], 0, 0, 0); __builtin_amdgcn_s_setprio(0); } while (0)
; #define PG8_WAIT_V(n) asm volatile("s_waitcnt vmcnt(" #n ")" ::: "memory")
; #define PG8_WAIT_L(n) asm volatile("s_waitcnt lgkmcnt(" #n ")" ::: "memory")
; #define PG8_BAR __builtin_amdgcn_s_barrier()
; #define PG8_SCHED __builtin_amdgcn_sched_barrier(0)
; template <class Epi, class Sched, bool ALIGN_EPI = false, bool SP2 = false>
; __device__ __forceinline__ void gemm_phase(PG8_LAS unsigned char* lds, const Gemm g, const Sched& S, const Epi& E) {
;     ...
;             const bool last = (t == nt - 2);
;             const char* a1 = cA + (size_t)(t + 1) * kstep;
;             const char* a2 = last ? nA : cA + (size_t)(t + 2) * kstep; const char* b2 = last ? nB : cB + (size_t)(t + 2) * kstep;
;             const char* a3 = a2 + kstep; const char* b3 = b2 + kstep;
;             if (last && has_next) S.a_ready(nxt);
;             if constexpr (SP2) {
;             PG8_LDB(B0, 0, 0); PG8_LDB(B1, 0, 1); PG8_SCHED; PG8_LDA(At, 0, 0); PG8_STAGE(PG8_SA(1, 1), a1 + hstep, voffA);
;             PG8_WAIT_V(8); PG8_WAIT_L(0); PG8_BAR; PG8_MMA(0, 0, At, B0); PG8_MMA(0, 1, At, B1); PG8_BAR; PG8_SCHED;
;             PG8_LDA(At, 0, 1); PG8_STAGE(PG8_SB(0, 0), b2, voffB); PG8_STAGE(PG8_SB(0, 1), b2 + hstep, voffB); PG8_STAGE(PG8_SA(0, 0), a2, voffA);
.LBB0_647:
	v_add_u32_e32 v52, s54, v178
	v_add_u32_e32 v116, s55, v178
	ds_read_b128 v[16:19], v52
	ds_read_b128 v[20:23], v52 offset:1024
	ds_read_b128 v[48:51], v52 offset:2048
	ds_read_b128 v[52:55], v52 offset:3072
	ds_read_b128 v[80:83], v116
	ds_read_b128 v[84:87], v116 offset:1024
	ds_read_b128 v[112:115], v116 offset:2048
	ds_read_b128 v[116:119], v116 offset:3072
	s_add_u32 s44, s40, 0xfffe0080
	s_addc_u32 s45, s41, -1
	s_cmp_eq_u32 s59, 4
	s_cselect_b32 s47, s7, s45
	s_cselect_b32 s46, s15, s44
	s_cselect_b32 s45, s17, s58
	s_cselect_b32 s44, s39, s57
	v_lshl_add_u64 v[210:211], s[40:41], 0, v[170:171]
	s_add_i32 m0, s48, 0xc000
	ds_read_b128 v[174:177], v180
	ds_read_b128 v[182:185], v180 offset:1024
	ds_read_b128 v[186:189], v180 offset:2048
	ds_read_b128 v[190:193], v180 offset:3072
	ds_read_b128 v[194:197], v180 offset:4096
	ds_read_b128 v[198:201], v180 offset:5120
	ds_read_b128 v[202:205], v180 offset:6144
	ds_read_b128 v[206:209], v180 offset:7168
	global_load_lds_dwordx4 v[210:211], off
	v_lshl_add_u64 v[210:211], s[40:41], 0, v[172:173]
	s_add_i32 m0, s48, 0xe000
	s_nop 0
	global_load_lds_dwordx4 v[210:211], off
	s_waitcnt vmcnt(8)
	s_waitcnt lgkmcnt(0)
	s_barrier
	s_setprio 1
	s_waitcnt lgkmcnt(0)
	v_mfma_f32_16x16x32_bf16 v[36:39], v[16:19], v[174:177], v[36:39]
	v_mfma_f32_16x16x32_bf16 v[32:35], v[48:51], v[174:177], v[32:35]
	v_mfma_f32_16x16x32_bf16 v[68:71], v[16:19], v[186:189], v[68:71]
	v_mfma_f32_16x16x32_bf16 v[64:67], v[48:51], v[186:189], v[64:67]
	v_mfma_f32_16x16x32_bf16 v[100:103], v[16:19], v[194:197], v[100:103]
	v_mfma_f32_16x16x32_bf16 v[96:99], v[48:51], v[194:197], v[96:99]
	v_mfma_f32_16x16x32_bf16 v[132:135], v[16:19], v[202:205], v[132:135]
	v_mfma_f32_16x16x32_bf16 v[128:131], v[48:51], v[202:205], v[128:131]
	v_mfma_f32_16x16x32_bf16 v[36:39], v[20:23], v[182:185], v[36:39]
	v_mfma_f32_16x16x32_bf16 v[32:35], v[52:55], v[182:185], v[32:35]
	v_mfma_f32_16x16x32_bf16 v[68:71], v[20:23], v[190:193], v[68:71]
	v_mfma_f32_16x16x32_bf16 v[64:67], v[52:55], v[190:193], v[64:67]
	v_mfma_f32_16x16x32_bf16 v[100:103], v[20:23], v[198:201], v[100:103]
	v_mfma_f32_16x16x32_bf16 v[96:99], v[52:55], v[198:201], v[96:99]
	v_mfma_f32_16x16x32_bf16 v[132:135], v[20:23], v[206:209], v[132:135]
	v_mfma_f32_16x16x32_bf16 v[128:131], v[52:55], v[206:209], v[128:131]
	s_setprio 0
	s_setprio 1
	v_mfma_f32_16x16x32_bf16 v[156:159], v[80:83], v[174:177], v[156:159]
	v_mfma_f32_16x16x32_bf16 v[152:155], v[112:115], v[174:177], v[152:155]
	v_mfma_f32_16x16x32_bf16 v[148:151], v[80:83], v[186:189], v[148:151]
	v_mfma_f32_16x16x32_bf16 v[144:147], v[112:115], v[186:189], v[144:147]
	v_mfma_f32_16x16x32_bf16 v[140:143], v[80:83], v[194:197], v[140:143]
	v_mfma_f32_16x16x32_bf16 v[136:139], v[112:115], v[194:197], v[136:139]
	v_mfma_f32_16x16x32_bf16 v[124:127], v[80:83], v[202:205], v[124:127]
	v_mfma_f32_16x16x32_bf16 v[120:123], v[112:115], v[202:205], v[120:123]
	v_mfma_f32_16x16x32_bf16 v[156:159], v[84:87], v[182:185], v[156:159]
	v_mfma_f32_16x16x32_bf16 v[152:155], v[116:119], v[182:185], v[152:155]
	v_mfma_f32_16x16x32_bf16 v[148:151], v[84:87], v[190:193], v[148:151]
	v_mfma_f32_16x16x32_bf16 v[144:147], v[116:119], v[190:193], v[144:147]
	v_mfma_f32_16x16x32_bf16 v[140:143], v[84:87], v[198:201], v[140:143]
	v_mfma_f32_16x16x32_bf16 v[136:139], v[116:119], v[198:201], v[136:139]
	v_mfma_f32_16x16x32_bf16 v[124:127], v[84:87], v[206:209], v[124:127]
	v_mfma_f32_16x16x32_bf16 v[120:123], v[116:119], v[206:209], v[120:123]
	s_setprio 0
	s_barrier
	s_add_i32 s60, s54, s19
	v_lshl_add_u64 v[214:215], s[44:45], 0, v[164:165]
	s_mov_b32 m0, s60
	ds_read_b128 v[174:177], v180 offset:16384
	ds_read_b128 v[182:185], v180 offset:17408
	ds_read_b128 v[186:189], v180 offset:18432
	ds_read_b128 v[190:193], v180 offset:19456
	ds_read_b128 v[194:197], v180 offset:20480
	ds_read_b128 v[198:201], v180 offset:21504
	ds_read_b128 v[202:205], v180 offset:22528
	ds_read_b128 v[206:209], v180 offset:23552
	global_load_lds_dwordx4 v[214:215], off
	s_add_i32 m0, s60, 0x2000
	s_add_u32 s60, s44, 0x20000
	v_lshl_add_u64 v[216:217], s[44:45], 0, v[168:169]
	s_addc_u32 s61, s45, 0
	s_add_i32 s63, s55, s19
	global_load_lds_dwordx4 v[216:217], off
	v_lshl_add_u64 v[210:211], s[60:61], 0, v[164:165]
	s_mov_b32 m0, s63
	v_lshl_add_u64 v[218:219], s[46:47], 0, v[160:161]
	global_load_lds_dwordx4 v[210:211], off
	v_lshl_add_u64 v[210:211], s[60:61], 0, v[168:169]
	s_add_i32 m0, s63, 0x2000
	v_lshl_add_u64 v[220:221], s[46:47], 0, v[166:167]
	global_load_lds_dwordx4 v[210:211], off
	s_mov_b32 m0, s48
	s_nop 0
	global_load_lds_dwordx4 v[218:219], off
	s_mov_b32 m0, s49
	s_nop 0
	global_load_lds_dwordx4 v[220:221], off
	s_waitcnt vmcnt(8)
	s_waitcnt lgkmcnt(0)
	s_barrier
; #define PG8_STAGE(bufoff, gbase, voff) do { _Pragma("unroll") for (int _i = 0; _i < 2; ++_i) \
;         __builtin_amdgcn_global_load_lds((const unsigned*)((const char*)(gbase) + (voff)[_i]), (PG8_LAS unsigned*)(lds + (bufoff) + ldsw + _i * 8192), 16, 0, 0); } while (0)
; #define PG8_LDA(dst, b, h) do { _Pragma("unroll") for (int m = 0; m < 4; ++m) _Pragma("unroll") for (int k = 0; k < 2; ++k) dst[m][k] = *(const PG8_LAS bf16x8*)(lds + PG8_SA(b, h) + aoff + m * 2048 + k * 1024); } while (0)
; #define PG8_LDB(dst, b, h) do { _Pragma("unroll") for (int n = 0; n < 2; ++n) _Pragma("unroll") for (int k = 0; k < 2; ++k) dst[n][k] = *(const PG8_LAS bf16x8*)(lds + PG8_SB(b, h) + boff + n * 2048 + k * 1024); } while (0)
; #define PG8_MMA(ai, bj, At, Bt) do { __builtin_amdgcn_s_setprio(1); _Pragma("unroll") for (int m = 0; m < 4; ++m) _Pragma("unroll") for (int n = 0; n < 2; ++n) _Pragma("unroll") for (int k = 0; k < 2; ++k) \
;         acc[ai][bj][m][n] = __builtin_amdgcn_mfma_f32_16x16x32_bf16(Bt[n][k], At[m][k], acc[ai][bj][m][n], 0, 0, 0); __builtin_amdgcn_s_setprio(0); } while (0)
; #define PG8_WAIT_V(n) asm volatile("s_waitcnt vmcnt(" #n ")" ::: "memory")
; #define PG8_WAIT_L(n) asm volatile("s_waitcnt lgkmcnt(" #n ")" ::: "memory")
; #define PG8_BAR __builtin_amdgcn_s_barrier()
; #define PG8_SCHED __builtin_amdgcn_sched_barrier(0)
; template <class Epi, class Sched, bool ALIGN_EPI = false, bool SP2 = false>
; __device__ __forceinline__ void gemm_phase(PG8_LAS unsigned char* lds, const Gemm g, const Sched& S, const Epi& E) {
;     ...
;             PG8_WAIT_V(8); PG8_WAIT_L(0); PG8_BAR; PG8_MMA(1, 0, At, B0); PG8_MMA(1, 1, At, B1); PG8_BAR; PG8_SCHED;
;             PG8_LDB(B0, 1, 0); PG8_LDB(B1, 1, 1); PG8_SCHED; PG8_LDA(At, 1, 0); PG8_STAGE(PG8_SA(0, 1), a2 + hstep, voffA);
;             PG8_WAIT_V(8); PG8_WAIT_L(0); PG8_BAR; PG8_MMA(0, 0, At, B0); PG8_MMA(0, 1, At, B1); PG8_BAR; PG8_SCHED;
	s_setprio 1
	s_waitcnt lgkmcnt(0)
	v_mfma_f32_16x16x32_bf16 v[108:111], v[16:19], v[174:177], v[108:111]
	v_mfma_f32_16x16x32_bf16 v[104:107], v[48:51], v[174:177], v[104:107]
	v_mfma_f32_16x16x32_bf16 v[76:79], v[16:19], v[186:189], v[76:79]
	v_mfma_f32_16x16x32_bf16 v[72:75], v[48:51], v[186:189], v[72:75]
	v_mfma_f32_16x16x32_bf16 v[44:47], v[16:19], v[194:197], v[44:47]
	v_mfma_f32_16x16x32_bf16 v[40:43], v[48:51], v[194:197], v[40:43]
	v_mfma_f32_16x16x32_bf16 v[12:15], v[16:19], v[202:205], v[12:15]
	v_mfma_f32_16x16x32_bf16 v[8:11], v[48:51], v[202:205], v[8:11]
	v_mfma_f32_16x16x32_bf16 v[108:111], v[20:23], v[182:185], v[108:111]
	v_mfma_f32_16x16x32_bf16 v[104:107], v[52:55], v[182:185], v[104:107]
	v_mfma_f32_16x16x32_bf16 v[76:79], v[20:23], v[190:193], v[76:79]
	v_mfma_f32_16x16x32_bf16 v[72:75], v[52:55], v[190:193], v[72:75]
	v_mfma_f32_16x16x32_bf16 v[44:47], v[20:23], v[198:201], v[44:47]
	v_mfma_f32_16x16x32_bf16 v[40:43], v[52:55], v[198:201], v[40:43]
	v_mfma_f32_16x16x32_bf16 v[12:15], v[20:23], v[206:209], v[12:15]
	v_mfma_f32_16x16x32_bf16 v[8:11], v[52:55], v[206:209], v[8:11]
	s_setprio 0
	s_setprio 1
	v_mfma_f32_16x16x32_bf16 v[28:31], v[80:83], v[194:197], v[28:31]
	v_mfma_f32_16x16x32_bf16 v[24:27], v[112:115], v[194:197], v[24:27]
	v_mfma_f32_16x16x32_bf16 v[4:7], v[80:83], v[202:205], v[4:7]
	v_mfma_f32_16x16x32_bf16 v[0:3], v[112:115], v[202:205], v[0:3]
	v_mfma_f32_16x16x32_bf16 v[16:19], v[80:83], v[174:177], v[92:95]
	v_mfma_f32_16x16x32_bf16 v[20:23], v[112:115], v[174:177], v[88:91]
	v_mfma_f32_16x16x32_bf16 v[48:51], v[80:83], v[186:189], v[60:63]
	v_mfma_f32_16x16x32_bf16 v[52:55], v[112:115], v[186:189], v[56:59]
	v_mfma_f32_16x16x32_bf16 v[28:31], v[84:87], v[198:201], v[28:31]
	v_mfma_f32_16x16x32_bf16 v[24:27], v[116:119], v[198:201], v[24:27]
	v_mfma_f32_16x16x32_bf16 v[4:7], v[84:87], v[206:209], v[4:7]
	v_mfma_f32_16x16x32_bf16 v[0:3], v[116:119], v[206:209], v[0:3]
	v_mfma_f32_16x16x32_bf16 v[16:19], v[84:87], v[182:185], v[16:19]
	v_mfma_f32_16x16x32_bf16 v[20:23], v[116:119], v[182:185], v[20:23]
	v_mfma_f32_16x16x32_bf16 v[48:51], v[84:87], v[190:193], v[48:51]
	v_mfma_f32_16x16x32_bf16 v[52:55], v[116:119], v[190:193], v[52:55]
	s_setprio 0
	s_barrier
	s_add_i32 s60, 0, 0x18000
	s_add_i32 s61, 0, 0x1c000
	v_add_u32_e32 v84, s60, v178
	v_add_u32_e32 v88, s61, v178
	ds_read_b128 v[56:59], v84
	ds_read_b128 v[60:63], v84 offset:1024
	ds_read_b128 v[80:83], v84 offset:2048
	ds_read_b128 v[84:87], v84 offset:3072
	ds_read_b128 v[112:115], v88
	ds_read_b128 v[116:119], v88 offset:1024
	ds_read_b128 v[174:177], v88 offset:2048
	ds_read_b128 v[182:185], v88 offset:3072
	s_add_u32 s46, s46, 0x20000
	s_addc_u32 s47, s47, 0
	s_mov_b32 m0, s50
	v_lshl_add_u64 v[210:211], s[46:47], 0, v[160:161]
	ds_read_b128 v[88:91], v180 offset:32768
	ds_read_b128 v[92:95], v180 offset:33792
	ds_read_b128 v[186:189], v180 offset:34816
	ds_read_b128 v[190:193], v180 offset:35840
	ds_read_b128 v[194:197], v180 offset:36864
	ds_read_b128 v[198:201], v180 offset:37888
	ds_read_b128 v[202:205], v180 offset:38912
	ds_read_b128 v[206:209], v180 offset:39936
	global_load_lds_dwordx4 v[210:211], off
	v_lshl_add_u64 v[210:211], s[46:47], 0, v[166:167]
	s_mov_b32 m0, s51
	s_nop 0
	global_load_lds_dwordx4 v[210:211], off
	s_waitcnt vmcnt(8)
	s_waitcnt lgkmcnt(0)
	s_barrier
	s_setprio 1
	s_waitcnt lgkmcnt(0)
	v_mfma_f32_16x16x32_bf16 v[36:39], v[56:59], v[88:91], v[36:39]
	v_mfma_f32_16x16x32_bf16 v[32:35], v[80:83], v[88:91], v[32:35]
	v_mfma_f32_16x16x32_bf16 v[68:71], v[56:59], v[186:189], v[68:71]
	v_mfma_f32_16x16x32_bf16 v[64:67], v[80:83], v[186:189], v[64:67]
	v_mfma_f32_16x16x32_bf16 v[100:103], v[56:59], v[194:197], v[100:103]
	v_mfma_f32_16x16x32_bf16 v[96:99], v[80:83], v[194:197], v[96:99]
	v_mfma_f32_16x16x32_bf16 v[132:135], v[56:59], v[202:205], v[132:135]
	v_mfma_f32_16x16x32_bf16 v[128:131], v[80:83], v[202:205], v[128:131]
	v_mfma_f32_16x16x32_bf16 v[36:39], v[60:63], v[92:95], v[36:39]
	v_mfma_f32_16x16x32_bf16 v[32:35], v[84:87], v[92:95], v[32:35]
	v_mfma_f32_16x16x32_bf16 v[68:71], v[60:63], v[190:193], v[68:71]
	v_mfma_f32_16x16x32_bf16 v[64:67], v[84:87], v[190:193], v[64:67]
	v_mfma_f32_16x16x32_bf16 v[100:103], v[60:63], v[198:201], v[100:103]
	v_mfma_f32_16x16x32_bf16 v[96:99], v[84:87], v[198:201], v[96:99]
	v_mfma_f32_16x16x32_bf16 v[132:135], v[60:63], v[206:209], v[132:135]
	v_mfma_f32_16x16x32_bf16 v[128:131], v[84:87], v[206:209], v[128:131]
	s_setprio 0
	s_setprio 1
	v_mfma_f32_16x16x32_bf16 v[156:159], v[112:115], v[88:91], v[156:159]
	v_mfma_f32_16x16x32_bf16 v[88:91], v[174:177], v[88:91], v[152:155]
	v_mfma_f32_16x16x32_bf16 v[152:155], v[182:185], v[92:95], v[88:91]
	v_mfma_f32_16x16x32_bf16 v[88:91], v[112:115], v[186:189], v[148:151]
	v_mfma_f32_16x16x32_bf16 v[148:151], v[116:119], v[190:193], v[88:91]
	v_mfma_f32_16x16x32_bf16 v[88:91], v[174:177], v[186:189], v[144:147]
	v_mfma_f32_16x16x32_bf16 v[144:147], v[182:185], v[190:193], v[88:91]
	v_mfma_f32_16x16x32_bf16 v[88:91], v[112:115], v[194:197], v[140:143]
	v_mfma_f32_16x16x32_bf16 v[140:143], v[116:119], v[198:201], v[88:91]
	v_mfma_f32_16x16x32_bf16 v[88:91], v[174:177], v[194:197], v[136:139]
	v_mfma_f32_16x16x32_bf16 v[136:139], v[182:185], v[198:201], v[88:91]
	v_mfma_f32_16x16x32_bf16 v[88:91], v[112:115], v[202:205], v[124:127]
	v_mfma_f32_16x16x32_bf16 v[124:127], v[116:119], v[206:209], v[88:91]
	v_mfma_f32_16x16x32_bf16 v[88:91], v[174:177], v[202:205], v[120:123]
	v_mfma_f32_16x16x32_bf16 v[156:159], v[116:119], v[92:95], v[156:159]
	v_mfma_f32_16x16x32_bf16 v[120:123], v[182:185], v[206:209], v[88:91]
	s_setprio 0
	s_barrier
; #define PG8_STAGE(bufoff, gbase, voff) do { _Pragma("unroll") for (int _i = 0; _i < 2; ++_i) \
;         __builtin_amdgcn_global_load_lds((const unsigned*)((const char*)(gbase) + (voff)[_i]), (PG8_LAS unsigned*)(lds + (bufoff) + ldsw + _i * 8192), 16, 0, 0); } while (0)
; #define PG8_LDA(dst, b, h) do { _Pragma("unroll") for (int m = 0; m < 4; ++m) _Pragma("unroll") for (int k = 0; k < 2; ++k) dst[m][k] = *(const PG8_LAS bf16x8*)(lds + PG8_SA(b, h) + aoff + m * 2048 + k * 1024); } while (0)
; #define PG8_MMA(ai, bj, At, Bt) do { __builtin_amdgcn_s_setprio(1); _Pragma("unroll") for (int m = 0; m < 4; ++m) _Pragma("unroll") for (int n = 0; n < 2; ++n) _Pragma("unroll") for (int k = 0; k < 2; ++k) \
;         acc[ai][bj][m][n] = __builtin_amdgcn_mfma_f32_16x16x32_bf16(Bt[n][k], At[m][k], acc[ai][bj][m][n], 0, 0, 0); __builtin_amdgcn_s_setprio(0); } while (0)
; #define PG8_WAIT_V(n) asm volatile("s_waitcnt vmcnt(" #n ")" ::: "memory")
; #define PG8_WAIT_L(n) asm volatile("s_waitcnt lgkmcnt(" #n ")" ::: "memory")
; #define PG8_BAR __builtin_amdgcn_s_barrier()
; #define PG8_SCHED __builtin_amdgcn_sched_barrier(0)
; template <class Epi, class Sched, bool ALIGN_EPI = false, bool SP2 = false>
; __device__ __forceinline__ void gemm_phase(PG8_LAS unsigned char* lds, const Gemm g, const Sched& S, const Epi& E) {
;     ...
;             PG8_LDA(At, 1, 1); PG8_STAGE(PG8_SB(1, 0), b3, voffB); PG8_STAGE(PG8_SB(1, 1), b3 + hstep, voffB); PG8_STAGE(PG8_SA(1, 0), a3, voffA);
;             PG8_WAIT_V(8); PG8_WAIT_L(0); PG8_BAR; PG8_MMA(1, 0, At, B0); PG8_MMA(1, 1, At, B1); PG8_BAR; PG8_SCHED;
;     ...
;         if constexpr (ALIGN_EPI) { if (wr == 0) PG8_BAR; }
	s_add_i32 s46, s60, s19
	v_lshl_add_u64 v[92:93], v[214:215], 0, s[10:11]
	s_mov_b32 m0, s46
	s_nop 0
	ds_read_b128 v[88:91], v180 offset:49152
	ds_read_b128 v[186:189], v180 offset:50176
	ds_read_b128 v[190:193], v180 offset:51200
	ds_read_b128 v[194:197], v180 offset:52224
	ds_read_b128 v[198:201], v180 offset:53248
	ds_read_b128 v[202:205], v180 offset:54272
	ds_read_b128 v[206:209], v180 offset:55296
	ds_read_b128 v[210:213], v180 offset:56320
	global_load_lds_dwordx4 v[92:93], off
	s_add_i32 m0, s46, 0x2000
	s_add_u32 s44, s44, 0x20080
	v_lshl_add_u64 v[92:93], v[216:217], 0, s[10:11]
	s_addc_u32 s45, s45, 0
	s_add_i32 s46, s61, s19
	global_load_lds_dwordx4 v[92:93], off
	v_lshl_add_u64 v[92:93], s[44:45], 0, v[164:165]
	s_mov_b32 m0, s46
	s_nop 0
	global_load_lds_dwordx4 v[92:93], off
	v_lshl_add_u64 v[92:93], s[44:45], 0, v[168:169]
	s_add_i32 m0, s46, 0x2000
	s_nop 0
	global_load_lds_dwordx4 v[92:93], off
	v_lshl_add_u64 v[92:93], v[218:219], 0, s[10:11]
	s_mov_b32 m0, s52
	s_nop 0
	global_load_lds_dwordx4 v[92:93], off
	v_lshl_add_u64 v[92:93], v[220:221], 0, s[10:11]
	s_mov_b32 m0, s53
	s_nop 0
	global_load_lds_dwordx4 v[92:93], off
	s_waitcnt vmcnt(8)
	s_waitcnt lgkmcnt(0)
	s_barrier
	s_setprio 1
	s_waitcnt lgkmcnt(0)
	v_mfma_f32_16x16x32_bf16 v[92:95], v[56:59], v[88:91], v[108:111]
	v_mfma_f32_16x16x32_bf16 v[108:111], v[60:63], v[186:189], v[92:95]
	v_mfma_f32_16x16x32_bf16 v[92:95], v[80:83], v[88:91], v[104:107]
	v_mfma_f32_16x16x32_bf16 v[76:79], v[56:59], v[190:193], v[76:79]
	v_mfma_f32_16x16x32_bf16 v[72:75], v[80:83], v[190:193], v[72:75]
	v_mfma_f32_16x16x32_bf16 v[44:47], v[56:59], v[198:201], v[44:47]
	v_mfma_f32_16x16x32_bf16 v[40:43], v[80:83], v[198:201], v[40:43]
	v_mfma_f32_16x16x32_bf16 v[12:15], v[56:59], v[206:209], v[12:15]
	v_mfma_f32_16x16x32_bf16 v[8:11], v[80:83], v[206:209], v[8:11]
	v_mfma_f32_16x16x32_bf16 v[104:107], v[84:87], v[186:189], v[92:95]
	v_mfma_f32_16x16x32_bf16 v[76:79], v[60:63], v[194:197], v[76:79]
	v_mfma_f32_16x16x32_bf16 v[72:75], v[84:87], v[194:197], v[72:75]
	v_mfma_f32_16x16x32_bf16 v[44:47], v[60:63], v[202:205], v[44:47]
	v_mfma_f32_16x16x32_bf16 v[40:43], v[84:87], v[202:205], v[40:43]
	v_mfma_f32_16x16x32_bf16 v[12:15], v[60:63], v[210:213], v[12:15]
	v_mfma_f32_16x16x32_bf16 v[8:11], v[84:87], v[210:213], v[8:11]
	s_setprio 0
	s_setprio 1
	v_mfma_f32_16x16x32_bf16 v[16:19], v[112:115], v[88:91], v[16:19]
	v_mfma_f32_16x16x32_bf16 v[92:95], v[116:119], v[186:189], v[16:19]
	v_mfma_f32_16x16x32_bf16 v[16:19], v[174:177], v[88:91], v[20:23]
	v_mfma_f32_16x16x32_bf16 v[88:91], v[182:185], v[186:189], v[16:19]
	v_mfma_f32_16x16x32_bf16 v[16:19], v[112:115], v[190:193], v[48:51]
	v_mfma_f32_16x16x32_bf16 v[60:63], v[116:119], v[194:197], v[16:19]
	v_mfma_f32_16x16x32_bf16 v[16:19], v[174:177], v[190:193], v[52:55]
	v_mfma_f32_16x16x32_bf16 v[56:59], v[182:185], v[194:197], v[16:19]
	v_mfma_f32_16x16x32_bf16 v[16:19], v[112:115], v[198:201], v[28:31]
	v_mfma_f32_16x16x32_bf16 v[28:31], v[116:119], v[202:205], v[16:19]
	v_mfma_f32_16x16x32_bf16 v[16:19], v[174:177], v[198:201], v[24:27]
	v_mfma_f32_16x16x32_bf16 v[4:7], v[112:115], v[206:209], v[4:7]
	v_mfma_f32_16x16x32_bf16 v[0:3], v[174:177], v[206:209], v[0:3]
	v_mfma_f32_16x16x32_bf16 v[24:27], v[182:185], v[202:205], v[16:19]
	v_mfma_f32_16x16x32_bf16 v[4:7], v[116:119], v[210:213], v[4:7]
	v_mfma_f32_16x16x32_bf16 v[0:3], v[182:185], v[210:213], v[0:3]
	s_setprio 0
	s_add_i32 s59, s59, 2
	s_add_u32 s40, s40, 0x100
	s_addc_u32 s41, s41, 0
	s_add_u32 s57, s57, 0x100
	s_addc_u32 s58, s58, 0
	s_cmp_gt_u32 s59, 5
	s_barrier
	s_cbranch_scc0 .LBB0_647
	s_and_b64 vcc, exec, s[12:13]
	s_cbranch_vccz .LBB0_650
	s_barrier

; #define PG8_STAGE(bufoff, gbase, voff) do { _Pragma("unroll") for (int _i = 0; _i < 2; ++_i) \
;         __builtin_amdgcn_global_load_lds((const unsigned*)((const char*)(gbase) + (voff)[_i]), (PG8_LAS unsigned*)(lds + (bufoff) + ldsw + _i * 8192), 16, 0, 0); } while (0)
; #define PG8_LDA(dst, b, h) do { _Pragma("unroll") for (int m = 0; m < 4; ++m) _Pragma("unroll") for (int k = 0; k < 2; ++k) dst[m][k] = *(const PG8_LAS bf16x8*)(lds + PG8_SA(b, h) + aoff + m * 2048 + k * 1024); } while (0)
; #define PG8_LDB(dst, b, h) do { _Pragma("unroll") for (int n = 0; n < 2; ++n) _Pragma("unroll") for (int k = 0; k < 2; ++k) dst[n][k] = *(const PG8_LAS bf16x8*)(lds + PG8_SB(b, h) + boff + n * 2048 + k * 1024); } while (0)
; #define PG8_MMA(ai, bj, At, Bt) do { __builtin_amdgcn_s_setprio(1); _Pragma("unroll") for (int m = 0; m < 4; ++m) _Pragma("unroll") for (int n = 0; n < 2; ++n) _Pragma("unroll") for (int k = 0; k < 2; ++k) \
;         acc[ai][bj][m][n] = __builtin_amdgcn_mfma_f32_16x16x32_bf16(Bt[n][k], At[m][k], acc[ai][bj][m][n], 0, 0, 0); __builtin_amdgcn_s_setprio(0); } while (0)
; #define PG8_WAIT_V(n) asm volatile("s_waitcnt vmcnt(" #n ")" ::: "memory")
; #define PG8_WAIT_L(n) asm volatile("s_waitcnt lgkmcnt(" #n ")" ::: "memory")
; #define PG8_BAR __builtin_amdgcn_s_barrier()
; #define PG8_SCHED __builtin_amdgcn_sched_barrier(0)
; template <class Epi, class Sched, bool ALIGN_EPI = false, bool SP2 = false>
; __device__ __forceinline__ void gemm_phase(PG8_LAS unsigned char* lds, const Gemm g, const Sched& S, const Epi& E) {
;     ...
;             const bool last = (t == nt - 2);
;             const char* a1 = cA + (size_t)(t + 1) * kstep;
;             const char* a2 = last ? nA : cA + (size_t)(t + 2) * kstep; const char* b2 = last ? nB : cB + (size_t)(t + 2) * kstep;
;             const char* a3 = a2 + kstep; const char* b3 = b2 + kstep;
;             if (last && has_next) S.a_ready(nxt);
;             if constexpr (SP2) {
;             PG8_LDB(B0, 0, 0); PG8_LDB(B1, 0, 1); PG8_SCHED; PG8_LDA(At, 0, 0); PG8_STAGE(PG8_SA(1, 1), a1 + hstep, voffA);
;             PG8_WAIT_V(8); PG8_WAIT_L(0); PG8_BAR; PG8_MMA(0, 0, At, B0); PG8_MMA(0, 1, At, B1); PG8_BAR; PG8_SCHED;
;             PG8_LDA(At, 0, 1); PG8_STAGE(PG8_SB(0, 0), b2, voffB); PG8_STAGE(PG8_SB(0, 1), b2 + hstep, voffB); PG8_STAGE(PG8_SA(0, 0), a2, voffA);
.LBB0_808:
	ds_read_b128 v[80:83], v168
	ds_read_b128 v[84:87], v168 offset:1024
	ds_read_b128 v[96:99], v168 offset:2048
	ds_read_b128 v[100:103], v168 offset:3072
	ds_read_b128 v[172:175], v169
	ds_read_b128 v[176:179], v169 offset:1024
	ds_read_b128 v[180:183], v169 offset:2048
	ds_read_b128 v[184:187], v169 offset:3072
	s_add_u32 s46, s44, 0xfffc0080
	s_addc_u32 s47, s45, -1
	s_cmp_eq_u32 s71, 12
	s_cselect_b32 s49, s23, s47
	s_cselect_b32 s48, s41, s46
	s_cselect_b32 s47, s21, s70
	s_cselect_b32 s46, s68, s69
	v_lshl_add_u64 v[160:161], s[44:45], 0, v[152:153]
	s_add_i32 m0, s50, 0xc000
	ds_read_b128 v[188:191], v170
	ds_read_b128 v[192:195], v170 offset:1024
	ds_read_b128 v[196:199], v170 offset:2048
	ds_read_b128 v[200:203], v170 offset:3072
	ds_read_b128 v[204:207], v170 offset:4096
	ds_read_b128 v[208:211], v170 offset:5120
	ds_read_b128 v[212:215], v170 offset:6144
	ds_read_b128 v[216:219], v170 offset:7168
	global_load_lds_dwordx4 v[160:161], off
	v_lshl_add_u64 v[160:161], s[44:45], 0, v[154:155]
	s_add_i32 m0, s50, 0xe000
	s_nop 0
	global_load_lds_dwordx4 v[160:161], off
	s_waitcnt vmcnt(8)
	s_waitcnt lgkmcnt(0)
	s_barrier
	s_setprio 1
	s_waitcnt lgkmcnt(0)
	v_mfma_f32_16x16x32_bf16 v[140:143], v[80:83], v[188:191], v[140:143]
	v_mfma_f32_16x16x32_bf16 v[136:139], v[96:99], v[188:191], v[136:139]
	v_mfma_f32_16x16x32_bf16 v[124:127], v[80:83], v[196:199], v[124:127]
	v_mfma_f32_16x16x32_bf16 v[120:123], v[96:99], v[196:199], v[120:123]
	v_mfma_f32_16x16x32_bf16 v[108:111], v[80:83], v[204:207], v[108:111]
	v_mfma_f32_16x16x32_bf16 v[104:107], v[96:99], v[204:207], v[104:107]
	v_mfma_f32_16x16x32_bf16 v[76:79], v[80:83], v[212:215], v[76:79]
	v_mfma_f32_16x16x32_bf16 v[72:75], v[96:99], v[212:215], v[72:75]
	v_mfma_f32_16x16x32_bf16 v[140:143], v[84:87], v[192:195], v[140:143]
	v_mfma_f32_16x16x32_bf16 v[136:139], v[100:103], v[192:195], v[136:139]
	v_mfma_f32_16x16x32_bf16 v[124:127], v[84:87], v[200:203], v[124:127]
	v_mfma_f32_16x16x32_bf16 v[120:123], v[100:103], v[200:203], v[120:123]
	v_mfma_f32_16x16x32_bf16 v[108:111], v[84:87], v[208:211], v[108:111]
	v_mfma_f32_16x16x32_bf16 v[104:107], v[100:103], v[208:211], v[104:107]
	v_mfma_f32_16x16x32_bf16 v[76:79], v[84:87], v[216:219], v[76:79]
	v_mfma_f32_16x16x32_bf16 v[72:75], v[100:103], v[216:219], v[72:75]
	s_setprio 0
	s_setprio 1
	v_mfma_f32_16x16x32_bf16 v[132:135], v[172:175], v[188:191], v[132:135]
	v_mfma_f32_16x16x32_bf16 v[128:131], v[180:183], v[188:191], v[128:131]
	v_mfma_f32_16x16x32_bf16 v[116:119], v[172:175], v[196:199], v[116:119]
	v_mfma_f32_16x16x32_bf16 v[112:115], v[180:183], v[196:199], v[112:115]
	v_mfma_f32_16x16x32_bf16 v[92:95], v[172:175], v[204:207], v[92:95]
	v_mfma_f32_16x16x32_bf16 v[88:91], v[180:183], v[204:207], v[88:91]
	v_mfma_f32_16x16x32_bf16 v[68:71], v[172:175], v[212:215], v[68:71]
	v_mfma_f32_16x16x32_bf16 v[64:67], v[180:183], v[212:215], v[64:67]
	v_mfma_f32_16x16x32_bf16 v[132:135], v[176:179], v[192:195], v[132:135]
	v_mfma_f32_16x16x32_bf16 v[128:131], v[184:187], v[192:195], v[128:131]
	v_mfma_f32_16x16x32_bf16 v[116:119], v[176:179], v[200:203], v[116:119]
	v_mfma_f32_16x16x32_bf16 v[112:115], v[184:187], v[200:203], v[112:115]
	v_mfma_f32_16x16x32_bf16 v[92:95], v[176:179], v[208:211], v[92:95]
	v_mfma_f32_16x16x32_bf16 v[88:91], v[184:187], v[208:211], v[88:91]
	v_mfma_f32_16x16x32_bf16 v[68:71], v[176:179], v[216:219], v[68:71]
	v_mfma_f32_16x16x32_bf16 v[64:67], v[184:187], v[216:219], v[64:67]
	s_setprio 0
	s_barrier
	s_add_i32 s72, s63, s3
	v_lshl_add_u64 v[160:161], s[46:47], 0, v[146:147]
	s_mov_b32 m0, s72
	ds_read_b128 v[188:191], v170 offset:16384
	ds_read_b128 v[192:195], v170 offset:17408
	ds_read_b128 v[196:199], v170 offset:18432
	ds_read_b128 v[200:203], v170 offset:19456
	ds_read_b128 v[204:207], v170 offset:20480
	ds_read_b128 v[208:211], v170 offset:21504
	ds_read_b128 v[212:215], v170 offset:22528
	ds_read_b128 v[216:219], v170 offset:23552
	global_load_lds_dwordx4 v[160:161], off
	s_add_i32 m0, s72, 0x2000
	s_add_u32 s72, s46, 0x40000
	v_lshl_add_u64 v[164:165], s[46:47], 0, v[150:151]
	s_addc_u32 s73, s47, 0
	s_add_i32 s74, s64, s3
	global_load_lds_dwordx4 v[164:165], off
	v_lshl_add_u64 v[220:221], s[72:73], 0, v[146:147]
	s_mov_b32 m0, s74
	v_lshl_add_u64 v[222:223], s[48:49], 0, v[148:149]
	global_load_lds_dwordx4 v[220:221], off
	v_lshl_add_u64 v[220:221], s[72:73], 0, v[150:151]
	s_add_i32 m0, s74, 0x2000
	s_nop 0
	global_load_lds_dwordx4 v[220:221], off
	v_lshl_add_u64 v[220:221], s[48:49], 0, v[144:145]
	s_mov_b32 m0, s50
	s_nop 0
	global_load_lds_dwordx4 v[220:221], off
	s_mov_b32 m0, s51
	s_nop 0
	global_load_lds_dwordx4 v[222:223], off
	s_waitcnt vmcnt(8)
	s_waitcnt lgkmcnt(0)
	s_barrier
; #define PG8_STAGE(bufoff, gbase, voff) do { _Pragma("unroll") for (int _i = 0; _i < 2; ++_i) \
;         __builtin_amdgcn_global_load_lds((const unsigned*)((const char*)(gbase) + (voff)[_i]), (PG8_LAS unsigned*)(lds + (bufoff) + ldsw + _i * 8192), 16, 0, 0); } while (0)
; #define PG8_LDA(dst, b, h) do { _Pragma("unroll") for (int m = 0; m < 4; ++m) _Pragma("unroll") for (int k = 0; k < 2; ++k) dst[m][k] = *(const PG8_LAS bf16x8*)(lds + PG8_SA(b, h) + aoff + m * 2048 + k * 1024); } while (0)
; #define PG8_LDB(dst, b, h) do { _Pragma("unroll") for (int n = 0; n < 2; ++n) _Pragma("unroll") for (int k = 0; k < 2; ++k) dst[n][k] = *(const PG8_LAS bf16x8*)(lds + PG8_SB(b, h) + boff + n * 2048 + k * 1024); } while (0)
; #define PG8_MMA(ai, bj, At, Bt) do { __builtin_amdgcn_s_setprio(1); _Pragma("unroll") for (int m = 0; m < 4; ++m) _Pragma("unroll") for (int n = 0; n < 2; ++n) _Pragma("unroll") for (int k = 0; k < 2; ++k) \
;         acc[ai][bj][m][n] = __builtin_amdgcn_mfma_f32_16x16x32_bf16(Bt[n][k], At[m][k], acc[ai][bj][m][n], 0, 0, 0); __builtin_amdgcn_s_setprio(0); } while (0)
; #define PG8_WAIT_V(n) asm volatile("s_waitcnt vmcnt(" #n ")" ::: "memory")
; #define PG8_WAIT_L(n) asm volatile("s_waitcnt lgkmcnt(" #n ")" ::: "memory")
; #define PG8_BAR __builtin_amdgcn_s_barrier()
; #define PG8_SCHED __builtin_amdgcn_sched_barrier(0)
; template <class Epi, class Sched, bool ALIGN_EPI = false, bool SP2 = false>
; __device__ __forceinline__ void gemm_phase(PG8_LAS unsigned char* lds, const Gemm g, const Sched& S, const Epi& E) {
;     ...
;             PG8_WAIT_V(8); PG8_WAIT_L(0); PG8_BAR; PG8_MMA(1, 0, At, B0); PG8_MMA(1, 1, At, B1); PG8_BAR; PG8_SCHED;
;             PG8_LDB(B0, 1, 0); PG8_LDB(B1, 1, 1); PG8_SCHED; PG8_LDA(At, 1, 0); PG8_STAGE(PG8_SA(0, 1), a2 + hstep, voffA);
;             PG8_WAIT_V(8); PG8_WAIT_L(0); PG8_BAR; PG8_MMA(0, 0, At, B0); PG8_MMA(0, 1, At, B1); PG8_BAR; PG8_SCHED;
	s_setprio 1
	s_waitcnt lgkmcnt(0)
	v_mfma_f32_16x16x32_bf16 v[60:63], v[80:83], v[188:191], v[60:63]
	v_mfma_f32_16x16x32_bf16 v[56:59], v[96:99], v[188:191], v[56:59]
	v_mfma_f32_16x16x32_bf16 v[44:47], v[80:83], v[196:199], v[44:47]
	v_mfma_f32_16x16x32_bf16 v[40:43], v[96:99], v[196:199], v[40:43]
	v_mfma_f32_16x16x32_bf16 v[28:31], v[80:83], v[204:207], v[28:31]
	v_mfma_f32_16x16x32_bf16 v[24:27], v[96:99], v[204:207], v[24:27]
	v_mfma_f32_16x16x32_bf16 v[12:15], v[80:83], v[212:215], v[12:15]
	v_mfma_f32_16x16x32_bf16 v[8:11], v[96:99], v[212:215], v[8:11]
	v_mfma_f32_16x16x32_bf16 v[60:63], v[84:87], v[192:195], v[60:63]
	v_mfma_f32_16x16x32_bf16 v[56:59], v[100:103], v[192:195], v[56:59]
	v_mfma_f32_16x16x32_bf16 v[44:47], v[84:87], v[200:203], v[44:47]
	v_mfma_f32_16x16x32_bf16 v[40:43], v[100:103], v[200:203], v[40:43]
	v_mfma_f32_16x16x32_bf16 v[28:31], v[84:87], v[208:211], v[28:31]
	v_mfma_f32_16x16x32_bf16 v[24:27], v[100:103], v[208:211], v[24:27]
	v_mfma_f32_16x16x32_bf16 v[12:15], v[84:87], v[216:219], v[12:15]
	v_mfma_f32_16x16x32_bf16 v[8:11], v[100:103], v[216:219], v[8:11]
	s_setprio 0
	s_setprio 1
	v_mfma_f32_16x16x32_bf16 v[52:55], v[172:175], v[188:191], v[52:55]
	v_mfma_f32_16x16x32_bf16 v[48:51], v[180:183], v[188:191], v[48:51]
	v_mfma_f32_16x16x32_bf16 v[36:39], v[172:175], v[196:199], v[36:39]
	v_mfma_f32_16x16x32_bf16 v[32:35], v[180:183], v[196:199], v[32:35]
	v_mfma_f32_16x16x32_bf16 v[20:23], v[172:175], v[204:207], v[20:23]
	v_mfma_f32_16x16x32_bf16 v[16:19], v[180:183], v[204:207], v[16:19]
	v_mfma_f32_16x16x32_bf16 v[4:7], v[172:175], v[212:215], v[4:7]
	v_mfma_f32_16x16x32_bf16 v[0:3], v[180:183], v[212:215], v[0:3]
	v_mfma_f32_16x16x32_bf16 v[52:55], v[176:179], v[192:195], v[52:55]
	v_mfma_f32_16x16x32_bf16 v[48:51], v[184:187], v[192:195], v[48:51]
	v_mfma_f32_16x16x32_bf16 v[36:39], v[176:179], v[200:203], v[36:39]
	v_mfma_f32_16x16x32_bf16 v[32:35], v[184:187], v[200:203], v[32:35]
	v_mfma_f32_16x16x32_bf16 v[20:23], v[176:179], v[208:211], v[20:23]
	v_mfma_f32_16x16x32_bf16 v[16:19], v[184:187], v[208:211], v[16:19]
	v_mfma_f32_16x16x32_bf16 v[4:7], v[176:179], v[216:219], v[4:7]
	v_mfma_f32_16x16x32_bf16 v[0:3], v[184:187], v[216:219], v[0:3]
	s_setprio 0
	s_barrier
	s_add_i32 s72, 0, 0x18000
	s_add_i32 s73, 0, 0x1c000
	v_add_u32_e32 v100, s72, v166
	v_add_u32_e32 v184, s73, v166
	ds_read_b128 v[80:83], v100
	ds_read_b128 v[84:87], v100 offset:1024
	ds_read_b128 v[96:99], v100 offset:2048
	ds_read_b128 v[100:103], v100 offset:3072
	ds_read_b128 v[172:175], v184
	ds_read_b128 v[176:179], v184 offset:1024
	ds_read_b128 v[180:183], v184 offset:2048
	ds_read_b128 v[184:187], v184 offset:3072
	s_add_u32 s48, s48, 0x40000
	s_addc_u32 s49, s49, 0
	s_mov_b32 m0, s52
	v_lshl_add_u64 v[224:225], s[48:49], 0, v[144:145]
	ds_read_b128 v[188:191], v170 offset:32768
	ds_read_b128 v[192:195], v170 offset:33792
	ds_read_b128 v[196:199], v170 offset:34816
	ds_read_b128 v[200:203], v170 offset:35840
	ds_read_b128 v[204:207], v170 offset:36864
	ds_read_b128 v[208:211], v170 offset:37888
	ds_read_b128 v[212:215], v170 offset:38912
	ds_read_b128 v[216:219], v170 offset:39936
	global_load_lds_dwordx4 v[224:225], off
	v_lshl_add_u64 v[224:225], s[48:49], 0, v[148:149]
	s_mov_b32 m0, s53
	s_nop 0
	global_load_lds_dwordx4 v[224:225], off
	s_waitcnt vmcnt(8)
	s_waitcnt lgkmcnt(0)
	s_barrier
	s_setprio 1
	s_waitcnt lgkmcnt(0)
	v_mfma_f32_16x16x32_bf16 v[140:143], v[80:83], v[188:191], v[140:143]
	v_mfma_f32_16x16x32_bf16 v[136:139], v[96:99], v[188:191], v[136:139]
	v_mfma_f32_16x16x32_bf16 v[124:127], v[80:83], v[196:199], v[124:127]
	v_mfma_f32_16x16x32_bf16 v[120:123], v[96:99], v[196:199], v[120:123]
	v_mfma_f32_16x16x32_bf16 v[108:111], v[80:83], v[204:207], v[108:111]
	v_mfma_f32_16x16x32_bf16 v[104:107], v[96:99], v[204:207], v[104:107]
	v_mfma_f32_16x16x32_bf16 v[76:79], v[80:83], v[212:215], v[76:79]
	v_mfma_f32_16x16x32_bf16 v[72:75], v[96:99], v[212:215], v[72:75]
	v_mfma_f32_16x16x32_bf16 v[140:143], v[84:87], v[192:195], v[140:143]
	v_mfma_f32_16x16x32_bf16 v[136:139], v[100:103], v[192:195], v[136:139]
	v_mfma_f32_16x16x32_bf16 v[124:127], v[84:87], v[200:203], v[124:127]
	v_mfma_f32_16x16x32_bf16 v[120:123], v[100:103], v[200:203], v[120:123]
	v_mfma_f32_16x16x32_bf16 v[108:111], v[84:87], v[208:211], v[108:111]
	v_mfma_f32_16x16x32_bf16 v[104:107], v[100:103], v[208:211], v[104:107]
	v_mfma_f32_16x16x32_bf16 v[76:79], v[84:87], v[216:219], v[76:79]
	v_mfma_f32_16x16x32_bf16 v[72:75], v[100:103], v[216:219], v[72:75]
	s_setprio 0
	s_setprio 1
	v_mfma_f32_16x16x32_bf16 v[132:135], v[172:175], v[188:191], v[132:135]
	v_mfma_f32_16x16x32_bf16 v[128:131], v[180:183], v[188:191], v[128:131]
	v_mfma_f32_16x16x32_bf16 v[116:119], v[172:175], v[196:199], v[116:119]
	v_mfma_f32_16x16x32_bf16 v[112:115], v[180:183], v[196:199], v[112:115]
	v_mfma_f32_16x16x32_bf16 v[92:95], v[172:175], v[204:207], v[92:95]
	v_mfma_f32_16x16x32_bf16 v[88:91], v[180:183], v[204:207], v[88:91]
	v_mfma_f32_16x16x32_bf16 v[68:71], v[172:175], v[212:215], v[68:71]
	v_mfma_f32_16x16x32_bf16 v[64:67], v[180:183], v[212:215], v[64:67]
	v_mfma_f32_16x16x32_bf16 v[132:135], v[176:179], v[192:195], v[132:135]
	v_mfma_f32_16x16x32_bf16 v[128:131], v[184:187], v[192:195], v[128:131]
	v_mfma_f32_16x16x32_bf16 v[116:119], v[176:179], v[200:203], v[116:119]
	v_mfma_f32_16x16x32_bf16 v[112:115], v[184:187], v[200:203], v[112:115]
	v_mfma_f32_16x16x32_bf16 v[92:95], v[176:179], v[208:211], v[92:95]
	v_mfma_f32_16x16x32_bf16 v[88:91], v[184:187], v[208:211], v[88:91]
	v_mfma_f32_16x16x32_bf16 v[68:71], v[176:179], v[216:219], v[68:71]
	v_mfma_f32_16x16x32_bf16 v[64:67], v[184:187], v[216:219], v[64:67]
	s_setprio 0
	s_barrier
; #define PG8_STAGE(bufoff, gbase, voff) do { _Pragma("unroll") for (int _i = 0; _i < 2; ++_i) \
;         __builtin_amdgcn_global_load_lds((const unsigned*)((const char*)(gbase) + (voff)[_i]), (PG8_LAS unsigned*)(lds + (bufoff) + ldsw + _i * 8192), 16, 0, 0); } while (0)
; #define PG8_LDA(dst, b, h) do { _Pragma("unroll") for (int m = 0; m < 4; ++m) _Pragma("unroll") for (int k = 0; k < 2; ++k) dst[m][k] = *(const PG8_LAS bf16x8*)(lds + PG8_SA(b, h) + aoff + m * 2048 + k * 1024); } while (0)
; #define PG8_MMA(ai, bj, At, Bt) do { __builtin_amdgcn_s_setprio(1); _Pragma("unroll") for (int m = 0; m < 4; ++m) _Pragma("unroll") for (int n = 0; n < 2; ++n) _Pragma("unroll") for (int k = 0; k < 2; ++k) \
;         acc[ai][bj][m][n] = __builtin_amdgcn_mfma_f32_16x16x32_bf16(Bt[n][k], At[m][k], acc[ai][bj][m][n], 0, 0, 0); __builtin_amdgcn_s_setprio(0); } while (0)
; #define PG8_WAIT_V(n) asm volatile("s_waitcnt vmcnt(" #n ")" ::: "memory")
; #define PG8_WAIT_L(n) asm volatile("s_waitcnt lgkmcnt(" #n ")" ::: "memory")
; #define PG8_BAR __builtin_amdgcn_s_barrier()
; #define PG8_SCHED __builtin_amdgcn_sched_barrier(0)
; template <class Epi, class Sched, bool ALIGN_EPI = false, bool SP2 = false>
; __device__ __forceinline__ void gemm_phase(PG8_LAS unsigned char* lds, const Gemm g, const Sched& S, const Epi& E) {
;     ...
;             PG8_LDA(At, 1, 1); PG8_STAGE(PG8_SB(1, 0), b3, voffB); PG8_STAGE(PG8_SB(1, 1), b3 + hstep, voffB); PG8_STAGE(PG8_SA(1, 0), a3, voffA);
;             PG8_WAIT_V(8); PG8_WAIT_L(0); PG8_BAR; PG8_MMA(1, 0, At, B0); PG8_MMA(1, 1, At, B1); PG8_BAR; PG8_SCHED;
;     ...
;         if constexpr (ALIGN_EPI) { if (wr == 0) PG8_BAR; }
	s_add_i32 s48, s72, s3
	v_lshl_add_u64 v[160:161], v[160:161], 0, s[16:17]
	s_mov_b32 m0, s48
	ds_read_b128 v[188:191], v170 offset:49152
	ds_read_b128 v[192:195], v170 offset:50176
	ds_read_b128 v[196:199], v170 offset:51200
	ds_read_b128 v[200:203], v170 offset:52224
	ds_read_b128 v[204:207], v170 offset:53248
	ds_read_b128 v[208:211], v170 offset:54272
	ds_read_b128 v[212:215], v170 offset:55296
	ds_read_b128 v[216:219], v170 offset:56320
	global_load_lds_dwordx4 v[160:161], off
	s_add_i32 m0, s48, 0x2000
	s_add_u32 s46, s46, 0x40080
	v_lshl_add_u64 v[160:161], v[164:165], 0, s[16:17]
	s_addc_u32 s47, s47, 0
	s_add_i32 s48, s73, s3
	global_load_lds_dwordx4 v[160:161], off
	v_lshl_add_u64 v[160:161], s[46:47], 0, v[146:147]
	s_mov_b32 m0, s48
	s_nop 0
	global_load_lds_dwordx4 v[160:161], off
	v_lshl_add_u64 v[160:161], s[46:47], 0, v[150:151]
	s_add_i32 m0, s48, 0x2000
	s_nop 0
	global_load_lds_dwordx4 v[160:161], off
	v_lshl_add_u64 v[160:161], v[220:221], 0, s[16:17]
	s_mov_b32 m0, s57
	s_nop 0
	global_load_lds_dwordx4 v[160:161], off
	v_lshl_add_u64 v[160:161], v[222:223], 0, s[16:17]
	s_mov_b32 m0, s58
	s_nop 0
	global_load_lds_dwordx4 v[160:161], off
	s_waitcnt vmcnt(8)
	s_waitcnt lgkmcnt(0)
	s_barrier
	s_setprio 1
	s_waitcnt lgkmcnt(0)
	v_mfma_f32_16x16x32_bf16 v[60:63], v[80:83], v[188:191], v[60:63]
	v_mfma_f32_16x16x32_bf16 v[56:59], v[96:99], v[188:191], v[56:59]
	v_mfma_f32_16x16x32_bf16 v[44:47], v[80:83], v[196:199], v[44:47]
	v_mfma_f32_16x16x32_bf16 v[40:43], v[96:99], v[196:199], v[40:43]
	v_mfma_f32_16x16x32_bf16 v[28:31], v[80:83], v[204:207], v[28:31]
	v_mfma_f32_16x16x32_bf16 v[24:27], v[96:99], v[204:207], v[24:27]
	v_mfma_f32_16x16x32_bf16 v[12:15], v[80:83], v[212:215], v[12:15]
	v_mfma_f32_16x16x32_bf16 v[8:11], v[96:99], v[212:215], v[8:11]
	v_mfma_f32_16x16x32_bf16 v[60:63], v[84:87], v[192:195], v[60:63]
	v_mfma_f32_16x16x32_bf16 v[56:59], v[100:103], v[192:195], v[56:59]
	v_mfma_f32_16x16x32_bf16 v[44:47], v[84:87], v[200:203], v[44:47]
	v_mfma_f32_16x16x32_bf16 v[40:43], v[100:103], v[200:203], v[40:43]
	v_mfma_f32_16x16x32_bf16 v[28:31], v[84:87], v[208:211], v[28:31]
	v_mfma_f32_16x16x32_bf16 v[24:27], v[100:103], v[208:211], v[24:27]
	v_mfma_f32_16x16x32_bf16 v[12:15], v[84:87], v[216:219], v[12:15]
	v_mfma_f32_16x16x32_bf16 v[8:11], v[100:103], v[216:219], v[8:11]
	s_setprio 0
	s_setprio 1
	v_mfma_f32_16x16x32_bf16 v[52:55], v[172:175], v[188:191], v[52:55]
	v_mfma_f32_16x16x32_bf16 v[48:51], v[180:183], v[188:191], v[48:51]
	v_mfma_f32_16x16x32_bf16 v[36:39], v[172:175], v[196:199], v[36:39]
	v_mfma_f32_16x16x32_bf16 v[32:35], v[180:183], v[196:199], v[32:35]
	v_mfma_f32_16x16x32_bf16 v[20:23], v[172:175], v[204:207], v[20:23]
	v_mfma_f32_16x16x32_bf16 v[16:19], v[180:183], v[204:207], v[16:19]
	v_mfma_f32_16x16x32_bf16 v[4:7], v[172:175], v[212:215], v[4:7]
	v_mfma_f32_16x16x32_bf16 v[0:3], v[180:183], v[212:215], v[0:3]
	v_mfma_f32_16x16x32_bf16 v[52:55], v[176:179], v[192:195], v[52:55]
	v_mfma_f32_16x16x32_bf16 v[48:51], v[184:187], v[192:195], v[48:51]
	v_mfma_f32_16x16x32_bf16 v[36:39], v[176:179], v[200:203], v[36:39]
	v_mfma_f32_16x16x32_bf16 v[32:35], v[184:187], v[200:203], v[32:35]
	v_mfma_f32_16x16x32_bf16 v[20:23], v[176:179], v[208:211], v[20:23]
	v_mfma_f32_16x16x32_bf16 v[16:19], v[184:187], v[208:211], v[16:19]
	v_mfma_f32_16x16x32_bf16 v[4:7], v[176:179], v[216:219], v[4:7]
	v_mfma_f32_16x16x32_bf16 v[0:3], v[184:187], v[216:219], v[0:3]
	s_setprio 0
	s_add_i32 s71, s71, 2
	s_add_u32 s44, s44, 0x100
	s_addc_u32 s45, s45, 0
	s_add_u32 s69, s69, 0x100
	s_addc_u32 s70, s70, 0
	s_cmp_gt_u32 s71, 13
	s_barrier
	s_cbranch_scc0 .LBB0_808
	s_and_b64 vcc, exec, s[18:19]
	s_cbranch_vccz .LBB0_811
	s_barrier

; #define PG8_STAGE(bufoff, gbase, voff) do { _Pragma("unroll") for (int _i = 0; _i < 2; ++_i) \
;         __builtin_amdgcn_global_load_lds((const unsigned*)((const char*)(gbase) + (voff)[_i]), (PG8_LAS unsigned*)(lds + (bufoff) + ldsw + _i * 8192), 16, 0, 0); } while (0)
; #define PG8_LDA(dst, b, h) do { _Pragma("unroll") for (int m = 0; m < 4; ++m) _Pragma("unroll") for (int k = 0; k < 2; ++k) dst[m][k] = *(const PG8_LAS bf16x8*)(lds + PG8_SA(b, h) + aoff + m * 2048 + k * 1024); } while (0)
; #define PG8_LDB(dst, b, h) do { _Pragma("unroll") for (int n = 0; n < 2; ++n) _Pragma("unroll") for (int k = 0; k < 2; ++k) dst[n][k] = *(const PG8_LAS bf16x8*)(lds + PG8_SB(b, h) + boff + n * 2048 + k * 1024); } while (0)
; #define PG8_MMA(ai, bj, At, Bt) do { __builtin_amdgcn_s_setprio(1); _Pragma("unroll") for (int m = 0; m < 4; ++m) _Pragma("unroll") for (int n = 0; n < 2; ++n) _Pragma("unroll") for (int k = 0; k < 2; ++k) \
;         acc[ai][bj][m][n] = __builtin_amdgcn_mfma_f32_16x16x32_bf16(Bt[n][k], At[m][k], acc[ai][bj][m][n], 0, 0, 0); __builtin_amdgcn_s_setprio(0); } while (0)
; #define PG8_WAIT_V(n) asm volatile("s_waitcnt vmcnt(" #n ")" ::: "memory")
; #define PG8_WAIT_L(n) asm volatile("s_waitcnt lgkmcnt(" #n ")" ::: "memory")
; #define PG8_BAR __builtin_amdgcn_s_barrier()
; #define PG8_SCHED __builtin_amdgcn_sched_barrier(0)
; template <class Epi, class Sched, bool ALIGN_EPI = false, bool SP2 = false>
; __device__ __forceinline__ void gemm_phase(PG8_LAS unsigned char* lds, const Gemm g, const Sched& S, const Epi& E) {
;     ...
;             const bool last = (t == nt - 2);
;             const char* a1 = cA + (size_t)(t + 1) * kstep;
;             const char* a2 = last ? nA : cA + (size_t)(t + 2) * kstep; const char* b2 = last ? nB : cB + (size_t)(t + 2) * kstep;
;             const char* a3 = a2 + kstep; const char* b3 = b2 + kstep;
;             if (last && has_next) S.a_ready(nxt);
;             if constexpr (SP2) {
;             PG8_LDB(B0, 0, 0); PG8_LDB(B1, 0, 1); PG8_SCHED; PG8_LDA(At, 0, 0); PG8_STAGE(PG8_SA(1, 1), a1 + hstep, voffA);
;             PG8_WAIT_V(8); PG8_WAIT_L(0); PG8_BAR; PG8_MMA(0, 0, At, B0); PG8_MMA(0, 1, At, B1); PG8_BAR; PG8_SCHED;
;             PG8_LDA(At, 0, 1); PG8_STAGE(PG8_SB(0, 0), b2, voffB); PG8_STAGE(PG8_SB(0, 1), b2 + hstep, voffB); PG8_STAGE(PG8_SA(0, 0), a2, voffA);
.LBB0_907:
	ds_read_b128 v[132:135], v171
	ds_read_b128 v[136:139], v171 offset:1024
	ds_read_b128 v[140:143], v171 offset:2048
	ds_read_b128 v[174:177], v171 offset:3072
	ds_read_b128 v[178:181], v172
	ds_read_b128 v[182:185], v172 offset:1024
	ds_read_b128 v[186:189], v172 offset:2048
	ds_read_b128 v[190:193], v172 offset:3072
	s_add_u32 s59, s36, 0xfffc0080
	s_addc_u32 s60, s37, -1
	s_cmp_eq_u32 s21, 12
	s_cselect_b64 vcc, -1, 0
	s_and_b64 s[38:39], vcc, exec
	v_cndmask_b32_e32 v165, v131, v129, vcc
	s_cselect_b32 s39, s23, s60
	s_cselect_b32 s38, s58, s59
	v_cndmask_b32_e32 v164, v130, v128, vcc
	s_mov_b32 m0, s55
	v_lshl_add_u64 v[228:229], s[36:37], 0, v[154:155]
	ds_read_b128 v[194:197], v173
	ds_read_b128 v[198:201], v173 offset:1024
	ds_read_b128 v[202:205], v173 offset:2048
	ds_read_b128 v[206:209], v173 offset:3072
	ds_read_b128 v[210:213], v173 offset:4096
	ds_read_b128 v[214:217], v173 offset:5120
	ds_read_b128 v[218:221], v173 offset:6144
	ds_read_b128 v[222:225], v173 offset:7168
	global_load_lds_dwordx4 v[228:229], off
	v_lshl_add_u64 v[228:229], s[36:37], 0, v[156:157]
	s_mov_b32 m0, s56
	s_nop 0
	global_load_lds_dwordx4 v[228:229], off
	s_waitcnt vmcnt(8)
	s_waitcnt lgkmcnt(0)
	s_barrier
	s_setprio 1
	s_waitcnt lgkmcnt(0)
	v_mfma_f32_16x16x32_bf16 v[124:127], v[132:135], v[194:197], v[124:127]
	v_mfma_f32_16x16x32_bf16 v[120:123], v[140:143], v[194:197], v[120:123]
	v_mfma_f32_16x16x32_bf16 v[108:111], v[132:135], v[202:205], v[108:111]
	v_mfma_f32_16x16x32_bf16 v[104:107], v[140:143], v[202:205], v[104:107]
	v_mfma_f32_16x16x32_bf16 v[92:95], v[132:135], v[210:213], v[92:95]
	v_mfma_f32_16x16x32_bf16 v[88:91], v[140:143], v[210:213], v[88:91]
	v_mfma_f32_16x16x32_bf16 v[76:79], v[132:135], v[218:221], v[76:79]
	v_mfma_f32_16x16x32_bf16 v[72:75], v[140:143], v[218:221], v[72:75]
	v_mfma_f32_16x16x32_bf16 v[124:127], v[136:139], v[198:201], v[124:127]
	v_mfma_f32_16x16x32_bf16 v[120:123], v[174:177], v[198:201], v[120:123]
	v_mfma_f32_16x16x32_bf16 v[108:111], v[136:139], v[206:209], v[108:111]
	v_mfma_f32_16x16x32_bf16 v[104:107], v[174:177], v[206:209], v[104:107]
	v_mfma_f32_16x16x32_bf16 v[92:95], v[136:139], v[214:217], v[92:95]
	v_mfma_f32_16x16x32_bf16 v[88:91], v[174:177], v[214:217], v[88:91]
	v_mfma_f32_16x16x32_bf16 v[76:79], v[136:139], v[222:225], v[76:79]
	v_mfma_f32_16x16x32_bf16 v[72:75], v[174:177], v[222:225], v[72:75]
	s_setprio 0
	s_setprio 1
	v_mfma_f32_16x16x32_bf16 v[116:119], v[178:181], v[194:197], v[116:119]
	v_mfma_f32_16x16x32_bf16 v[112:115], v[186:189], v[194:197], v[112:115]
	v_mfma_f32_16x16x32_bf16 v[100:103], v[178:181], v[202:205], v[100:103]
	v_mfma_f32_16x16x32_bf16 v[96:99], v[186:189], v[202:205], v[96:99]
	v_mfma_f32_16x16x32_bf16 v[84:87], v[178:181], v[210:213], v[84:87]
	v_mfma_f32_16x16x32_bf16 v[80:83], v[186:189], v[210:213], v[80:83]
	v_mfma_f32_16x16x32_bf16 v[68:71], v[178:181], v[218:221], v[68:71]
	v_mfma_f32_16x16x32_bf16 v[64:67], v[186:189], v[218:221], v[64:67]
	v_mfma_f32_16x16x32_bf16 v[116:119], v[182:185], v[198:201], v[116:119]
	v_mfma_f32_16x16x32_bf16 v[112:115], v[190:193], v[198:201], v[112:115]
	v_mfma_f32_16x16x32_bf16 v[100:103], v[182:185], v[206:209], v[100:103]
	v_mfma_f32_16x16x32_bf16 v[96:99], v[190:193], v[206:209], v[96:99]
	v_mfma_f32_16x16x32_bf16 v[84:87], v[182:185], v[214:217], v[84:87]
	v_mfma_f32_16x16x32_bf16 v[80:83], v[190:193], v[214:217], v[80:83]
	v_mfma_f32_16x16x32_bf16 v[68:71], v[182:185], v[222:225], v[68:71]
	v_mfma_f32_16x16x32_bf16 v[64:67], v[190:193], v[222:225], v[64:67]
	s_setprio 0
	s_barrier
	s_add_i32 s59, s52, s40
	v_lshl_add_u64 v[228:229], v[164:165], 0, v[150:151]
	s_mov_b32 m0, s59
	ds_read_b128 v[194:197], v173 offset:16384
	ds_read_b128 v[198:201], v173 offset:17408
	ds_read_b128 v[202:205], v173 offset:18432
	ds_read_b128 v[206:209], v173 offset:19456
	ds_read_b128 v[210:213], v173 offset:20480
	ds_read_b128 v[214:217], v173 offset:21504
	ds_read_b128 v[218:221], v173 offset:22528
	ds_read_b128 v[222:225], v173 offset:23552
	global_load_lds_dwordx4 v[228:229], off
	v_lshl_add_u64 v[230:231], v[164:165], 0, v[146:147]
	s_add_i32 m0, s59, 0x2000
	v_lshl_add_u64 v[232:233], v[164:165], 0, s[0:1]
	s_add_i32 s59, s53, s40
	global_load_lds_dwordx4 v[230:231], off
	v_lshl_add_u64 v[234:235], v[232:233], 0, v[150:151]
	s_mov_b32 m0, s59
	v_lshl_add_u64 v[232:233], v[232:233], 0, v[146:147]
	global_load_lds_dwordx4 v[234:235], off
	s_add_i32 m0, s59, 0x2000
	v_lshl_add_u64 v[234:235], s[38:39], 0, v[148:149]
	global_load_lds_dwordx4 v[232:233], off
	v_lshl_add_u64 v[232:233], s[38:39], 0, v[152:153]
	s_mov_b32 m0, s31
	s_nop 0
	global_load_lds_dwordx4 v[232:233], off
	s_mov_b32 m0, s44
	s_nop 0
	global_load_lds_dwordx4 v[234:235], off
	s_waitcnt vmcnt(8)
	s_waitcnt lgkmcnt(0)
	s_barrier
; #define PG8_STAGE(bufoff, gbase, voff) do { _Pragma("unroll") for (int _i = 0; _i < 2; ++_i) \
;         __builtin_amdgcn_global_load_lds((const unsigned*)((const char*)(gbase) + (voff)[_i]), (PG8_LAS unsigned*)(lds + (bufoff) + ldsw + _i * 8192), 16, 0, 0); } while (0)
; #define PG8_LDA(dst, b, h) do { _Pragma("unroll") for (int m = 0; m < 4; ++m) _Pragma("unroll") for (int k = 0; k < 2; ++k) dst[m][k] = *(const PG8_LAS bf16x8*)(lds + PG8_SA(b, h) + aoff + m * 2048 + k * 1024); } while (0)
; #define PG8_LDB(dst, b, h) do { _Pragma("unroll") for (int n = 0; n < 2; ++n) _Pragma("unroll") for (int k = 0; k < 2; ++k) dst[n][k] = *(const PG8_LAS bf16x8*)(lds + PG8_SB(b, h) + boff + n * 2048 + k * 1024); } while (0)
; #define PG8_MMA(ai, bj, At, Bt) do { __builtin_amdgcn_s_setprio(1); _Pragma("unroll") for (int m = 0; m < 4; ++m) _Pragma("unroll") for (int n = 0; n < 2; ++n) _Pragma("unroll") for (int k = 0; k < 2; ++k) \
;         acc[ai][bj][m][n] = __builtin_amdgcn_mfma_f32_16x16x32_bf16(Bt[n][k], At[m][k], acc[ai][bj][m][n], 0, 0, 0); __builtin_amdgcn_s_setprio(0); } while (0)
; #define PG8_WAIT_V(n) asm volatile("s_waitcnt vmcnt(" #n ")" ::: "memory")
; #define PG8_WAIT_L(n) asm volatile("s_waitcnt lgkmcnt(" #n ")" ::: "memory")
; #define PG8_BAR __builtin_amdgcn_s_barrier()
; #define PG8_SCHED __builtin_amdgcn_sched_barrier(0)
; template <class Epi, class Sched, bool ALIGN_EPI = false, bool SP2 = false>
; __device__ __forceinline__ void gemm_phase(PG8_LAS unsigned char* lds, const Gemm g, const Sched& S, const Epi& E) {
;     ...
;             PG8_WAIT_V(8); PG8_WAIT_L(0); PG8_BAR; PG8_MMA(1, 0, At, B0); PG8_MMA(1, 1, At, B1); PG8_BAR; PG8_SCHED;
;             PG8_LDB(B0, 1, 0); PG8_LDB(B1, 1, 1); PG8_SCHED; PG8_LDA(At, 1, 0); PG8_STAGE(PG8_SA(0, 1), a2 + hstep, voffA);
;             PG8_WAIT_V(8); PG8_WAIT_L(0); PG8_BAR; PG8_MMA(0, 0, At, B0); PG8_MMA(0, 1, At, B1); PG8_BAR; PG8_SCHED;
	s_setprio 1
	s_waitcnt lgkmcnt(0)
	v_mfma_f32_16x16x32_bf16 v[60:63], v[132:135], v[194:197], v[60:63]
	v_mfma_f32_16x16x32_bf16 v[56:59], v[140:143], v[194:197], v[56:59]
	v_mfma_f32_16x16x32_bf16 v[44:47], v[132:135], v[202:205], v[44:47]
	v_mfma_f32_16x16x32_bf16 v[40:43], v[140:143], v[202:205], v[40:43]
	v_mfma_f32_16x16x32_bf16 v[28:31], v[132:135], v[210:213], v[28:31]
	v_mfma_f32_16x16x32_bf16 v[24:27], v[140:143], v[210:213], v[24:27]
	v_mfma_f32_16x16x32_bf16 v[12:15], v[132:135], v[218:221], v[12:15]
	v_mfma_f32_16x16x32_bf16 v[8:11], v[140:143], v[218:221], v[8:11]
	v_mfma_f32_16x16x32_bf16 v[60:63], v[136:139], v[198:201], v[60:63]
	v_mfma_f32_16x16x32_bf16 v[56:59], v[174:177], v[198:201], v[56:59]
	v_mfma_f32_16x16x32_bf16 v[44:47], v[136:139], v[206:209], v[44:47]
	v_mfma_f32_16x16x32_bf16 v[40:43], v[174:177], v[206:209], v[40:43]
	v_mfma_f32_16x16x32_bf16 v[28:31], v[136:139], v[214:217], v[28:31]
	v_mfma_f32_16x16x32_bf16 v[24:27], v[174:177], v[214:217], v[24:27]
	v_mfma_f32_16x16x32_bf16 v[12:15], v[136:139], v[222:225], v[12:15]
	v_mfma_f32_16x16x32_bf16 v[8:11], v[174:177], v[222:225], v[8:11]
	s_setprio 0
	s_setprio 1
	v_mfma_f32_16x16x32_bf16 v[52:55], v[178:181], v[194:197], v[52:55]
	v_mfma_f32_16x16x32_bf16 v[48:51], v[186:189], v[194:197], v[48:51]
	v_mfma_f32_16x16x32_bf16 v[36:39], v[178:181], v[202:205], v[36:39]
	v_mfma_f32_16x16x32_bf16 v[32:35], v[186:189], v[202:205], v[32:35]
	v_mfma_f32_16x16x32_bf16 v[20:23], v[178:181], v[210:213], v[20:23]
	v_mfma_f32_16x16x32_bf16 v[16:19], v[186:189], v[210:213], v[16:19]
	v_mfma_f32_16x16x32_bf16 v[4:7], v[178:181], v[218:221], v[4:7]
	v_mfma_f32_16x16x32_bf16 v[0:3], v[186:189], v[218:221], v[0:3]
	v_mfma_f32_16x16x32_bf16 v[52:55], v[182:185], v[198:201], v[52:55]
	v_mfma_f32_16x16x32_bf16 v[48:51], v[190:193], v[198:201], v[48:51]
	v_mfma_f32_16x16x32_bf16 v[36:39], v[182:185], v[206:209], v[36:39]
	v_mfma_f32_16x16x32_bf16 v[32:35], v[190:193], v[206:209], v[32:35]
	v_mfma_f32_16x16x32_bf16 v[20:23], v[182:185], v[214:217], v[20:23]
	v_mfma_f32_16x16x32_bf16 v[16:19], v[190:193], v[214:217], v[16:19]
	v_mfma_f32_16x16x32_bf16 v[4:7], v[182:185], v[222:225], v[4:7]
	v_mfma_f32_16x16x32_bf16 v[0:3], v[190:193], v[222:225], v[0:3]
	s_setprio 0
	s_barrier
	s_add_i32 s59, 0, 0x18000
	s_add_i32 s60, 0, 0x1c000
	v_add_u32_e32 v174, s59, v167
	v_add_u32_e32 v190, s60, v167
	ds_read_b128 v[132:135], v174
	ds_read_b128 v[136:139], v174 offset:1024
	ds_read_b128 v[140:143], v174 offset:2048
	ds_read_b128 v[174:177], v174 offset:3072
	ds_read_b128 v[178:181], v190
	ds_read_b128 v[182:185], v190 offset:1024
	ds_read_b128 v[186:189], v190 offset:2048
	ds_read_b128 v[190:193], v190 offset:3072
	s_add_u32 s38, s38, 0x40000
	s_addc_u32 s39, s39, 0
	s_mov_b32 m0, s45
	v_lshl_add_u64 v[236:237], s[38:39], 0, v[152:153]
	ds_read_b128 v[194:197], v173 offset:32768
	ds_read_b128 v[198:201], v173 offset:33792
	ds_read_b128 v[202:205], v173 offset:34816
	ds_read_b128 v[206:209], v173 offset:35840
	ds_read_b128 v[210:213], v173 offset:36864
	ds_read_b128 v[214:217], v173 offset:37888
	ds_read_b128 v[218:221], v173 offset:38912
	ds_read_b128 v[222:225], v173 offset:39936
	global_load_lds_dwordx4 v[236:237], off
	v_lshl_add_u64 v[236:237], s[38:39], 0, v[148:149]
	s_mov_b32 m0, s46
	s_nop 0
	global_load_lds_dwordx4 v[236:237], off
	s_waitcnt vmcnt(8)
	s_waitcnt lgkmcnt(0)
	s_barrier
	s_setprio 1
	s_waitcnt lgkmcnt(0)
	v_mfma_f32_16x16x32_bf16 v[124:127], v[132:135], v[194:197], v[124:127]
	v_mfma_f32_16x16x32_bf16 v[120:123], v[140:143], v[194:197], v[120:123]
	v_mfma_f32_16x16x32_bf16 v[108:111], v[132:135], v[202:205], v[108:111]
	v_mfma_f32_16x16x32_bf16 v[104:107], v[140:143], v[202:205], v[104:107]
	v_mfma_f32_16x16x32_bf16 v[92:95], v[132:135], v[210:213], v[92:95]
	v_mfma_f32_16x16x32_bf16 v[88:91], v[140:143], v[210:213], v[88:91]
	v_mfma_f32_16x16x32_bf16 v[76:79], v[132:135], v[218:221], v[76:79]
	v_mfma_f32_16x16x32_bf16 v[72:75], v[140:143], v[218:221], v[72:75]
	v_mfma_f32_16x16x32_bf16 v[124:127], v[136:139], v[198:201], v[124:127]
	v_mfma_f32_16x16x32_bf16 v[120:123], v[174:177], v[198:201], v[120:123]
	v_mfma_f32_16x16x32_bf16 v[108:111], v[136:139], v[206:209], v[108:111]
	v_mfma_f32_16x16x32_bf16 v[104:107], v[174:177], v[206:209], v[104:107]
	v_mfma_f32_16x16x32_bf16 v[92:95], v[136:139], v[214:217], v[92:95]
	v_mfma_f32_16x16x32_bf16 v[88:91], v[174:177], v[214:217], v[88:91]
	v_mfma_f32_16x16x32_bf16 v[76:79], v[136:139], v[222:225], v[76:79]
	v_mfma_f32_16x16x32_bf16 v[72:75], v[174:177], v[222:225], v[72:75]
	s_setprio 0
	s_setprio 1
	v_mfma_f32_16x16x32_bf16 v[116:119], v[178:181], v[194:197], v[116:119]
	v_mfma_f32_16x16x32_bf16 v[112:115], v[186:189], v[194:197], v[112:115]
	v_mfma_f32_16x16x32_bf16 v[100:103], v[178:181], v[202:205], v[100:103]
	v_mfma_f32_16x16x32_bf16 v[96:99], v[186:189], v[202:205], v[96:99]
	v_mfma_f32_16x16x32_bf16 v[84:87], v[178:181], v[210:213], v[84:87]
	v_mfma_f32_16x16x32_bf16 v[80:83], v[186:189], v[210:213], v[80:83]
	v_mfma_f32_16x16x32_bf16 v[68:71], v[178:181], v[218:221], v[68:71]
	v_mfma_f32_16x16x32_bf16 v[64:67], v[186:189], v[218:221], v[64:67]
	v_mfma_f32_16x16x32_bf16 v[116:119], v[182:185], v[198:201], v[116:119]
	v_mfma_f32_16x16x32_bf16 v[112:115], v[190:193], v[198:201], v[112:115]
	v_mfma_f32_16x16x32_bf16 v[100:103], v[182:185], v[206:209], v[100:103]
	v_mfma_f32_16x16x32_bf16 v[96:99], v[190:193], v[206:209], v[96:99]
	v_mfma_f32_16x16x32_bf16 v[84:87], v[182:185], v[214:217], v[84:87]
	v_mfma_f32_16x16x32_bf16 v[80:83], v[190:193], v[214:217], v[80:83]
	v_mfma_f32_16x16x32_bf16 v[68:71], v[182:185], v[222:225], v[68:71]
	v_mfma_f32_16x16x32_bf16 v[64:67], v[190:193], v[222:225], v[64:67]
	s_setprio 0
	s_barrier
; #define PG8_STAGE(bufoff, gbase, voff) do { _Pragma("unroll") for (int _i = 0; _i < 2; ++_i) \
;         __builtin_amdgcn_global_load_lds((const unsigned*)((const char*)(gbase) + (voff)[_i]), (PG8_LAS unsigned*)(lds + (bufoff) + ldsw + _i * 8192), 16, 0, 0); } while (0)
; #define PG8_LDA(dst, b, h) do { _Pragma("unroll") for (int m = 0; m < 4; ++m) _Pragma("unroll") for (int k = 0; k < 2; ++k) dst[m][k] = *(const PG8_LAS bf16x8*)(lds + PG8_SA(b, h) + aoff + m * 2048 + k * 1024); } while (0)
; #define PG8_MMA(ai, bj, At, Bt) do { __builtin_amdgcn_s_setprio(1); _Pragma("unroll") for (int m = 0; m < 4; ++m) _Pragma("unroll") for (int n = 0; n < 2; ++n) _Pragma("unroll") for (int k = 0; k < 2; ++k) \
;         acc[ai][bj][m][n] = __builtin_amdgcn_mfma_f32_16x16x32_bf16(Bt[n][k], At[m][k], acc[ai][bj][m][n], 0, 0, 0); __builtin_amdgcn_s_setprio(0); } while (0)
; #define PG8_WAIT_V(n) asm volatile("s_waitcnt vmcnt(" #n ")" ::: "memory")
; #define PG8_WAIT_L(n) asm volatile("s_waitcnt lgkmcnt(" #n ")" ::: "memory")
; #define PG8_BAR __builtin_amdgcn_s_barrier()
; #define PG8_SCHED __builtin_amdgcn_sched_barrier(0)
; template <class Epi, class Sched, bool ALIGN_EPI = false, bool SP2 = false>
; __device__ __forceinline__ void gemm_phase(PG8_LAS unsigned char* lds, const Gemm g, const Sched& S, const Epi& E) {
;     ...
;             PG8_LDA(At, 1, 1); PG8_STAGE(PG8_SB(1, 0), b3, voffB); PG8_STAGE(PG8_SB(1, 1), b3 + hstep, voffB); PG8_STAGE(PG8_SA(1, 0), a3, voffA);
;             PG8_WAIT_V(8); PG8_WAIT_L(0); PG8_BAR; PG8_MMA(1, 0, At, B0); PG8_MMA(1, 1, At, B1); PG8_BAR; PG8_SCHED;
;     ...
;         if constexpr (ALIGN_EPI) { if (wr == 0) PG8_BAR; }
	s_add_i32 s38, s59, s40
	v_lshl_add_u64 v[228:229], v[228:229], 0, s[12:13]
	s_mov_b32 m0, s38
	ds_read_b128 v[194:197], v173 offset:49152
	ds_read_b128 v[198:201], v173 offset:50176
	ds_read_b128 v[202:205], v173 offset:51200
	ds_read_b128 v[206:209], v173 offset:52224
	ds_read_b128 v[210:213], v173 offset:53248
	ds_read_b128 v[214:217], v173 offset:54272
	ds_read_b128 v[218:221], v173 offset:55296
	ds_read_b128 v[222:225], v173 offset:56320
	global_load_lds_dwordx4 v[228:229], off
	v_lshl_add_u64 v[228:229], v[230:231], 0, s[12:13]
	s_add_i32 m0, s38, 0x2000
	v_lshl_add_u64 v[164:165], v[164:165], 0, s[14:15]
	s_add_i32 s38, s60, s40
	global_load_lds_dwordx4 v[228:229], off
	v_lshl_add_u64 v[228:229], v[164:165], 0, v[150:151]
	s_mov_b32 m0, s38
	v_lshl_add_u64 v[164:165], v[164:165], 0, v[146:147]
	global_load_lds_dwordx4 v[228:229], off
	s_add_i32 m0, s38, 0x2000
	s_nop 0
	global_load_lds_dwordx4 v[164:165], off
	v_lshl_add_u64 v[164:165], v[232:233], 0, s[12:13]
	s_mov_b32 m0, s48
	s_nop 0
	global_load_lds_dwordx4 v[164:165], off
	v_lshl_add_u64 v[164:165], v[234:235], 0, s[12:13]
	s_mov_b32 m0, s49
	s_nop 0
	global_load_lds_dwordx4 v[164:165], off
	s_waitcnt vmcnt(8)
	s_waitcnt lgkmcnt(0)
	s_barrier
	s_setprio 1
	s_waitcnt lgkmcnt(0)
	v_mfma_f32_16x16x32_bf16 v[60:63], v[132:135], v[194:197], v[60:63]
	v_mfma_f32_16x16x32_bf16 v[56:59], v[140:143], v[194:197], v[56:59]
	v_mfma_f32_16x16x32_bf16 v[44:47], v[132:135], v[202:205], v[44:47]
	v_mfma_f32_16x16x32_bf16 v[40:43], v[140:143], v[202:205], v[40:43]
	v_mfma_f32_16x16x32_bf16 v[28:31], v[132:135], v[210:213], v[28:31]
	v_mfma_f32_16x16x32_bf16 v[24:27], v[140:143], v[210:213], v[24:27]
	v_mfma_f32_16x16x32_bf16 v[12:15], v[132:135], v[218:221], v[12:15]
	v_mfma_f32_16x16x32_bf16 v[8:11], v[140:143], v[218:221], v[8:11]
	v_mfma_f32_16x16x32_bf16 v[60:63], v[136:139], v[198:201], v[60:63]
	v_mfma_f32_16x16x32_bf16 v[56:59], v[174:177], v[198:201], v[56:59]
	v_mfma_f32_16x16x32_bf16 v[44:47], v[136:139], v[206:209], v[44:47]
	v_mfma_f32_16x16x32_bf16 v[40:43], v[174:177], v[206:209], v[40:43]
	v_mfma_f32_16x16x32_bf16 v[28:31], v[136:139], v[214:217], v[28:31]
	v_mfma_f32_16x16x32_bf16 v[24:27], v[174:177], v[214:217], v[24:27]
	v_mfma_f32_16x16x32_bf16 v[12:15], v[136:139], v[222:225], v[12:15]
	v_mfma_f32_16x16x32_bf16 v[8:11], v[174:177], v[222:225], v[8:11]
	s_setprio 0
	s_setprio 1
	v_mfma_f32_16x16x32_bf16 v[52:55], v[178:181], v[194:197], v[52:55]
	v_mfma_f32_16x16x32_bf16 v[48:51], v[186:189], v[194:197], v[48:51]
	v_mfma_f32_16x16x32_bf16 v[36:39], v[178:181], v[202:205], v[36:39]
	v_mfma_f32_16x16x32_bf16 v[32:35], v[186:189], v[202:205], v[32:35]
	v_mfma_f32_16x16x32_bf16 v[20:23], v[178:181], v[210:213], v[20:23]
	v_mfma_f32_16x16x32_bf16 v[16:19], v[186:189], v[210:213], v[16:19]
	v_mfma_f32_16x16x32_bf16 v[4:7], v[178:181], v[218:221], v[4:7]
	v_mfma_f32_16x16x32_bf16 v[0:3], v[186:189], v[218:221], v[0:3]
	v_mfma_f32_16x16x32_bf16 v[52:55], v[182:185], v[198:201], v[52:55]
	v_mfma_f32_16x16x32_bf16 v[48:51], v[190:193], v[198:201], v[48:51]
	v_mfma_f32_16x16x32_bf16 v[36:39], v[182:185], v[206:209], v[36:39]
	v_mfma_f32_16x16x32_bf16 v[32:35], v[190:193], v[206:209], v[32:35]
	v_mfma_f32_16x16x32_bf16 v[20:23], v[182:185], v[214:217], v[20:23]
	v_mfma_f32_16x16x32_bf16 v[16:19], v[190:193], v[214:217], v[16:19]
	v_mfma_f32_16x16x32_bf16 v[4:7], v[182:185], v[222:225], v[4:7]
	v_mfma_f32_16x16x32_bf16 v[0:3], v[190:193], v[222:225], v[0:3]
	s_setprio 0
	s_add_i32 s21, s21, 2
	s_add_u32 s36, s36, 0x100
	s_addc_u32 s37, s37, 0
	s_cmp_gt_u32 s21, 13
	v_lshl_add_u64 v[130:131], v[130:131], 0, s[18:19]
	s_barrier
	s_cbranch_scc0 .LBB0_907
	s_and_b64 vcc, exec, s[16:17]
	s_cbranch_vccz .LBB0_910
	s_barrier

; #define PG8_STAGE(bufoff, gbase, voff) do { _Pragma("unroll") for (int _i = 0; _i < 2; ++_i) \
;         __builtin_amdgcn_global_load_lds((const unsigned*)((const char*)(gbase) + (voff)[_i]), (PG8_LAS unsigned*)(lds + (bufoff) + ldsw + _i * 8192), 16, 0, 0); } while (0)
; #define PG8_LDA(dst, b, h) do { _Pragma("unroll") for (int m = 0; m < 4; ++m) _Pragma("unroll") for (int k = 0; k < 2; ++k) dst[m][k] = *(const PG8_LAS bf16x8*)(lds + PG8_SA(b, h) + aoff + m * 2048 + k * 1024); } while (0)
; #define PG8_LDB(dst, b, h) do { _Pragma("unroll") for (int n = 0; n < 2; ++n) _Pragma("unroll") for (int k = 0; k < 2; ++k) dst[n][k] = *(const PG8_LAS bf16x8*)(lds + PG8_SB(b, h) + boff + n * 2048 + k * 1024); } while (0)
; #define PG8_MMA(ai, bj, At, Bt) do { __builtin_amdgcn_s_setprio(1); _Pragma("unroll") for (int m = 0; m < 4; ++m) _Pragma("unroll") for (int n = 0; n < 2; ++n) _Pragma("unroll") for (int k = 0; k < 2; ++k) \
;         acc[ai][bj][m][n] = __builtin_amdgcn_mfma_f32_16x16x32_bf16(Bt[n][k], At[m][k], acc[ai][bj][m][n], 0, 0, 0); __builtin_amdgcn_s_setprio(0); } while (0)
; #define PG8_WAIT_V(n) asm volatile("s_waitcnt vmcnt(" #n ")" ::: "memory")
; #define PG8_WAIT_L(n) asm volatile("s_waitcnt lgkmcnt(" #n ")" ::: "memory")
; #define PG8_BAR __builtin_amdgcn_s_barrier()
; #define PG8_SCHED __builtin_amdgcn_sched_barrier(0)
; template <class Epi, class Sched, bool ALIGN_EPI = false, bool SP2 = false>
; __device__ __forceinline__ void gemm_phase(PG8_LAS unsigned char* lds, const Gemm g, const Sched& S, const Epi& E) {
;     ...
;             const bool last = (t == nt - 2);
;             const char* a1 = cA + (size_t)(t + 1) * kstep;
;             const char* a2 = last ? nA : cA + (size_t)(t + 2) * kstep; const char* b2 = last ? nB : cB + (size_t)(t + 2) * kstep;
;             const char* a3 = a2 + kstep; const char* b3 = b2 + kstep;
;             if (last && has_next) S.a_ready(nxt);
;             if constexpr (SP2) {
;             PG8_LDB(B0, 0, 0); PG8_LDB(B1, 0, 1); PG8_SCHED; PG8_LDA(At, 0, 0); PG8_STAGE(PG8_SA(1, 1), a1 + hstep, voffA);
;             PG8_WAIT_V(8); PG8_WAIT_L(0); PG8_BAR; PG8_MMA(0, 0, At, B0); PG8_MMA(0, 1, At, B1); PG8_BAR; PG8_SCHED;
;             PG8_LDA(At, 0, 1); PG8_STAGE(PG8_SB(0, 0), b2, voffB); PG8_STAGE(PG8_SB(0, 1), b2 + hstep, voffB); PG8_STAGE(PG8_SA(0, 0), a2, voffA);
.LBB0_1007:
	ds_read_b128 v[144:147], v169
	ds_read_b128 v[148:151], v169 offset:1024
	ds_read_b128 v[152:155], v169 offset:2048
	ds_read_b128 v[156:159], v169 offset:3072
	ds_read_b128 v[160:163], v170
	ds_read_b128 v[172:175], v170 offset:1024
	ds_read_b128 v[176:179], v170 offset:2048
	ds_read_b128 v[180:183], v170 offset:3072
	s_add_u32 s26, s22, 0xfff50080
	s_addc_u32 s27, s23, -1
	s_cmp_eq_u32 s53, 40
	s_cselect_b32 s29, s5, s27
	s_cselect_b32 s28, s4, s26
	s_cselect_b32 s27, s21, s52
	s_cselect_b32 s26, s20, s51
	v_lshl_add_u64 v[164:165], s[22:23], 0, v[136:137]
	s_add_i32 m0, s31, 0xc000
	ds_read_b128 v[184:187], v171
	ds_read_b128 v[188:191], v171 offset:1024
	ds_read_b128 v[192:195], v171 offset:2048
	ds_read_b128 v[196:199], v171 offset:3072
	ds_read_b128 v[200:203], v171 offset:4096
	ds_read_b128 v[204:207], v171 offset:5120
	ds_read_b128 v[208:211], v171 offset:6144
	ds_read_b128 v[212:215], v171 offset:7168
	global_load_lds_dwordx4 v[164:165], off
	v_lshl_add_u64 v[164:165], s[22:23], 0, v[138:139]
	s_add_i32 m0, s31, 0xe000
	s_nop 0
	global_load_lds_dwordx4 v[164:165], off
	s_waitcnt vmcnt(8)
	s_waitcnt lgkmcnt(0)
	s_barrier
	s_setprio 1
	s_waitcnt lgkmcnt(0)
	v_mfma_f32_16x16x32_bf16 v[124:127], v[144:147], v[184:187], v[124:127]
	v_mfma_f32_16x16x32_bf16 v[120:123], v[152:155], v[184:187], v[120:123]
	v_mfma_f32_16x16x32_bf16 v[108:111], v[144:147], v[192:195], v[108:111]
	v_mfma_f32_16x16x32_bf16 v[104:107], v[152:155], v[192:195], v[104:107]
	v_mfma_f32_16x16x32_bf16 v[92:95], v[144:147], v[200:203], v[92:95]
	v_mfma_f32_16x16x32_bf16 v[88:91], v[152:155], v[200:203], v[88:91]
	v_mfma_f32_16x16x32_bf16 v[76:79], v[144:147], v[208:211], v[76:79]
	v_mfma_f32_16x16x32_bf16 v[72:75], v[152:155], v[208:211], v[72:75]
	v_mfma_f32_16x16x32_bf16 v[124:127], v[148:151], v[188:191], v[124:127]
	v_mfma_f32_16x16x32_bf16 v[120:123], v[156:159], v[188:191], v[120:123]
	v_mfma_f32_16x16x32_bf16 v[108:111], v[148:151], v[196:199], v[108:111]
	v_mfma_f32_16x16x32_bf16 v[104:107], v[156:159], v[196:199], v[104:107]
	v_mfma_f32_16x16x32_bf16 v[92:95], v[148:151], v[204:207], v[92:95]
	v_mfma_f32_16x16x32_bf16 v[88:91], v[156:159], v[204:207], v[88:91]
	v_mfma_f32_16x16x32_bf16 v[76:79], v[148:151], v[212:215], v[76:79]
	v_mfma_f32_16x16x32_bf16 v[72:75], v[156:159], v[212:215], v[72:75]
	s_setprio 0
	s_setprio 1
	v_mfma_f32_16x16x32_bf16 v[116:119], v[160:163], v[184:187], v[116:119]
	v_mfma_f32_16x16x32_bf16 v[112:115], v[176:179], v[184:187], v[112:115]
	v_mfma_f32_16x16x32_bf16 v[100:103], v[160:163], v[192:195], v[100:103]
	v_mfma_f32_16x16x32_bf16 v[96:99], v[176:179], v[192:195], v[96:99]
	v_mfma_f32_16x16x32_bf16 v[84:87], v[160:163], v[200:203], v[84:87]
	v_mfma_f32_16x16x32_bf16 v[80:83], v[176:179], v[200:203], v[80:83]
	v_mfma_f32_16x16x32_bf16 v[68:71], v[160:163], v[208:211], v[68:71]
	v_mfma_f32_16x16x32_bf16 v[64:67], v[176:179], v[208:211], v[64:67]
	v_mfma_f32_16x16x32_bf16 v[116:119], v[172:175], v[188:191], v[116:119]
	v_mfma_f32_16x16x32_bf16 v[112:115], v[180:183], v[188:191], v[112:115]
	v_mfma_f32_16x16x32_bf16 v[100:103], v[172:175], v[196:199], v[100:103]
	v_mfma_f32_16x16x32_bf16 v[96:99], v[180:183], v[196:199], v[96:99]
	v_mfma_f32_16x16x32_bf16 v[84:87], v[172:175], v[204:207], v[84:87]
	v_mfma_f32_16x16x32_bf16 v[80:83], v[180:183], v[204:207], v[80:83]
	v_mfma_f32_16x16x32_bf16 v[68:71], v[172:175], v[212:215], v[68:71]
	v_mfma_f32_16x16x32_bf16 v[64:67], v[180:183], v[212:215], v[64:67]
	s_setprio 0
	s_barrier
	s_add_i32 s54, s45, s30
	v_lshl_add_u64 v[164:165], s[26:27], 0, v[130:131]
	s_mov_b32 m0, s54
	ds_read_b128 v[184:187], v171 offset:16384
	ds_read_b128 v[188:191], v171 offset:17408
	ds_read_b128 v[192:195], v171 offset:18432
	ds_read_b128 v[196:199], v171 offset:19456
	ds_read_b128 v[200:203], v171 offset:20480
	ds_read_b128 v[204:207], v171 offset:21504
	ds_read_b128 v[208:211], v171 offset:22528
	ds_read_b128 v[212:215], v171 offset:23552
	global_load_lds_dwordx4 v[164:165], off
	s_add_i32 m0, s54, 0x2000
	s_add_u32 s54, s26, 0xb0000
	v_lshl_add_u64 v[216:217], s[26:27], 0, v[134:135]
	s_addc_u32 s55, s27, 0
	s_add_i32 s56, s46, s30
	global_load_lds_dwordx4 v[216:217], off
	v_lshl_add_u64 v[218:219], s[54:55], 0, v[130:131]
	s_mov_b32 m0, s56
	v_lshl_add_u64 v[220:221], s[28:29], 0, v[132:133]
	global_load_lds_dwordx4 v[218:219], off
	v_lshl_add_u64 v[218:219], s[54:55], 0, v[134:135]
	s_add_i32 m0, s56, 0x2000
	s_nop 0
	global_load_lds_dwordx4 v[218:219], off
	v_lshl_add_u64 v[218:219], s[28:29], 0, v[128:129]
	s_mov_b32 m0, s31
	s_nop 0
	global_load_lds_dwordx4 v[218:219], off
	s_mov_b32 m0, s33
	s_nop 0
	global_load_lds_dwordx4 v[220:221], off
	s_waitcnt vmcnt(8)
	s_waitcnt lgkmcnt(0)
	s_barrier
; #define PG8_STAGE(bufoff, gbase, voff) do { _Pragma("unroll") for (int _i = 0; _i < 2; ++_i) \
;         __builtin_amdgcn_global_load_lds((const unsigned*)((const char*)(gbase) + (voff)[_i]), (PG8_LAS unsigned*)(lds + (bufoff) + ldsw + _i * 8192), 16, 0, 0); } while (0)
; #define PG8_LDA(dst, b, h) do { _Pragma("unroll") for (int m = 0; m < 4; ++m) _Pragma("unroll") for (int k = 0; k < 2; ++k) dst[m][k] = *(const PG8_LAS bf16x8*)(lds + PG8_SA(b, h) + aoff + m * 2048 + k * 1024); } while (0)
; #define PG8_LDB(dst, b, h) do { _Pragma("unroll") for (int n = 0; n < 2; ++n) _Pragma("unroll") for (int k = 0; k < 2; ++k) dst[n][k] = *(const PG8_LAS bf16x8*)(lds + PG8_SB(b, h) + boff + n * 2048 + k * 1024); } while (0)
; #define PG8_MMA(ai, bj, At, Bt) do { __builtin_amdgcn_s_setprio(1); _Pragma("unroll") for (int m = 0; m < 4; ++m) _Pragma("unroll") for (int n = 0; n < 2; ++n) _Pragma("unroll") for (int k = 0; k < 2; ++k) \
;         acc[ai][bj][m][n] = __builtin_amdgcn_mfma_f32_16x16x32_bf16(Bt[n][k], At[m][k], acc[ai][bj][m][n], 0, 0, 0); __builtin_amdgcn_s_setprio(0); } while (0)
; #define PG8_WAIT_V(n) asm volatile("s_waitcnt vmcnt(" #n ")" ::: "memory")
; #define PG8_WAIT_L(n) asm volatile("s_waitcnt lgkmcnt(" #n ")" ::: "memory")
; #define PG8_BAR __builtin_amdgcn_s_barrier()
; #define PG8_SCHED __builtin_amdgcn_sched_barrier(0)
; template <class Epi, class Sched, bool ALIGN_EPI = false, bool SP2 = false>
; __device__ __forceinline__ void gemm_phase(PG8_LAS unsigned char* lds, const Gemm g, const Sched& S, const Epi& E) {
;     ...
;             PG8_WAIT_V(8); PG8_WAIT_L(0); PG8_BAR; PG8_MMA(1, 0, At, B0); PG8_MMA(1, 1, At, B1); PG8_BAR; PG8_SCHED;
;             PG8_LDB(B0, 1, 0); PG8_LDB(B1, 1, 1); PG8_SCHED; PG8_LDA(At, 1, 0); PG8_STAGE(PG8_SA(0, 1), a2 + hstep, voffA);
;             PG8_WAIT_V(8); PG8_WAIT_L(0); PG8_BAR; PG8_MMA(0, 0, At, B0); PG8_MMA(0, 1, At, B1); PG8_BAR; PG8_SCHED;
	s_setprio 1
	s_waitcnt lgkmcnt(0)
	v_mfma_f32_16x16x32_bf16 v[60:63], v[144:147], v[184:187], v[60:63]
	v_mfma_f32_16x16x32_bf16 v[56:59], v[152:155], v[184:187], v[56:59]
	v_mfma_f32_16x16x32_bf16 v[44:47], v[144:147], v[192:195], v[44:47]
	v_mfma_f32_16x16x32_bf16 v[40:43], v[152:155], v[192:195], v[40:43]
	v_mfma_f32_16x16x32_bf16 v[28:31], v[144:147], v[200:203], v[28:31]
	v_mfma_f32_16x16x32_bf16 v[24:27], v[152:155], v[200:203], v[24:27]
	v_mfma_f32_16x16x32_bf16 v[12:15], v[144:147], v[208:211], v[12:15]
	v_mfma_f32_16x16x32_bf16 v[8:11], v[152:155], v[208:211], v[8:11]
	v_mfma_f32_16x16x32_bf16 v[60:63], v[148:151], v[188:191], v[60:63]
	v_mfma_f32_16x16x32_bf16 v[56:59], v[156:159], v[188:191], v[56:59]
	v_mfma_f32_16x16x32_bf16 v[44:47], v[148:151], v[196:199], v[44:47]
	v_mfma_f32_16x16x32_bf16 v[40:43], v[156:159], v[196:199], v[40:43]
	v_mfma_f32_16x16x32_bf16 v[28:31], v[148:151], v[204:207], v[28:31]
	v_mfma_f32_16x16x32_bf16 v[24:27], v[156:159], v[204:207], v[24:27]
	v_mfma_f32_16x16x32_bf16 v[12:15], v[148:151], v[212:215], v[12:15]
	v_mfma_f32_16x16x32_bf16 v[8:11], v[156:159], v[212:215], v[8:11]
	s_setprio 0
	s_setprio 1
	v_mfma_f32_16x16x32_bf16 v[52:55], v[160:163], v[184:187], v[52:55]
	v_mfma_f32_16x16x32_bf16 v[48:51], v[176:179], v[184:187], v[48:51]
	v_mfma_f32_16x16x32_bf16 v[36:39], v[160:163], v[192:195], v[36:39]
	v_mfma_f32_16x16x32_bf16 v[32:35], v[176:179], v[192:195], v[32:35]
	v_mfma_f32_16x16x32_bf16 v[20:23], v[160:163], v[200:203], v[20:23]
	v_mfma_f32_16x16x32_bf16 v[16:19], v[176:179], v[200:203], v[16:19]
	v_mfma_f32_16x16x32_bf16 v[4:7], v[160:163], v[208:211], v[4:7]
	v_mfma_f32_16x16x32_bf16 v[0:3], v[176:179], v[208:211], v[0:3]
	v_mfma_f32_16x16x32_bf16 v[52:55], v[172:175], v[188:191], v[52:55]
	v_mfma_f32_16x16x32_bf16 v[48:51], v[180:183], v[188:191], v[48:51]
	v_mfma_f32_16x16x32_bf16 v[36:39], v[172:175], v[196:199], v[36:39]
	v_mfma_f32_16x16x32_bf16 v[32:35], v[180:183], v[196:199], v[32:35]
	v_mfma_f32_16x16x32_bf16 v[20:23], v[172:175], v[204:207], v[20:23]
	v_mfma_f32_16x16x32_bf16 v[16:19], v[180:183], v[204:207], v[16:19]
	v_mfma_f32_16x16x32_bf16 v[4:7], v[172:175], v[212:215], v[4:7]
	v_mfma_f32_16x16x32_bf16 v[0:3], v[180:183], v[212:215], v[0:3]
	s_setprio 0
	s_barrier
	s_add_i32 s54, 0, 0x18000
	s_add_i32 s55, 0, 0x1c000
	v_add_u32_e32 v156, s54, v167
	v_add_u32_e32 v180, s55, v167
	ds_read_b128 v[144:147], v156
	ds_read_b128 v[148:151], v156 offset:1024
	ds_read_b128 v[152:155], v156 offset:2048
	ds_read_b128 v[156:159], v156 offset:3072
	ds_read_b128 v[160:163], v180
	ds_read_b128 v[172:175], v180 offset:1024
	ds_read_b128 v[176:179], v180 offset:2048
	ds_read_b128 v[180:183], v180 offset:3072
	s_add_u32 s28, s28, 0xb0000
	s_addc_u32 s29, s29, 0
	s_mov_b32 m0, s36
	v_lshl_add_u64 v[222:223], s[28:29], 0, v[128:129]
	ds_read_b128 v[184:187], v171 offset:32768
	ds_read_b128 v[188:191], v171 offset:33792
	ds_read_b128 v[192:195], v171 offset:34816
	ds_read_b128 v[196:199], v171 offset:35840
	ds_read_b128 v[200:203], v171 offset:36864
	ds_read_b128 v[204:207], v171 offset:37888
	ds_read_b128 v[208:211], v171 offset:38912
	ds_read_b128 v[212:215], v171 offset:39936
	global_load_lds_dwordx4 v[222:223], off
	v_lshl_add_u64 v[222:223], s[28:29], 0, v[132:133]
	s_mov_b32 m0, s37
	s_nop 0
	global_load_lds_dwordx4 v[222:223], off
	s_waitcnt vmcnt(8)
	s_waitcnt lgkmcnt(0)
	s_barrier
	s_setprio 1
	s_waitcnt lgkmcnt(0)
	v_mfma_f32_16x16x32_bf16 v[124:127], v[144:147], v[184:187], v[124:127]
	v_mfma_f32_16x16x32_bf16 v[120:123], v[152:155], v[184:187], v[120:123]
	v_mfma_f32_16x16x32_bf16 v[108:111], v[144:147], v[192:195], v[108:111]
	v_mfma_f32_16x16x32_bf16 v[104:107], v[152:155], v[192:195], v[104:107]
	v_mfma_f32_16x16x32_bf16 v[92:95], v[144:147], v[200:203], v[92:95]
	v_mfma_f32_16x16x32_bf16 v[88:91], v[152:155], v[200:203], v[88:91]
	v_mfma_f32_16x16x32_bf16 v[76:79], v[144:147], v[208:211], v[76:79]
	v_mfma_f32_16x16x32_bf16 v[72:75], v[152:155], v[208:211], v[72:75]
	v_mfma_f32_16x16x32_bf16 v[124:127], v[148:151], v[188:191], v[124:127]
	v_mfma_f32_16x16x32_bf16 v[120:123], v[156:159], v[188:191], v[120:123]
	v_mfma_f32_16x16x32_bf16 v[108:111], v[148:151], v[196:199], v[108:111]
	v_mfma_f32_16x16x32_bf16 v[104:107], v[156:159], v[196:199], v[104:107]
	v_mfma_f32_16x16x32_bf16 v[92:95], v[148:151], v[204:207], v[92:95]
	v_mfma_f32_16x16x32_bf16 v[88:91], v[156:159], v[204:207], v[88:91]
	v_mfma_f32_16x16x32_bf16 v[76:79], v[148:151], v[212:215], v[76:79]
	v_mfma_f32_16x16x32_bf16 v[72:75], v[156:159], v[212:215], v[72:75]
	s_setprio 0
	s_setprio 1
	v_mfma_f32_16x16x32_bf16 v[116:119], v[160:163], v[184:187], v[116:119]
	v_mfma_f32_16x16x32_bf16 v[112:115], v[176:179], v[184:187], v[112:115]
	v_mfma_f32_16x16x32_bf16 v[100:103], v[160:163], v[192:195], v[100:103]
	v_mfma_f32_16x16x32_bf16 v[96:99], v[176:179], v[192:195], v[96:99]
	v_mfma_f32_16x16x32_bf16 v[84:87], v[160:163], v[200:203], v[84:87]
	v_mfma_f32_16x16x32_bf16 v[80:83], v[176:179], v[200:203], v[80:83]
	v_mfma_f32_16x16x32_bf16 v[68:71], v[160:163], v[208:211], v[68:71]
	v_mfma_f32_16x16x32_bf16 v[64:67], v[176:179], v[208:211], v[64:67]
	v_mfma_f32_16x16x32_bf16 v[116:119], v[172:175], v[188:191], v[116:119]
	v_mfma_f32_16x16x32_bf16 v[112:115], v[180:183], v[188:191], v[112:115]
	v_mfma_f32_16x16x32_bf16 v[100:103], v[172:175], v[196:199], v[100:103]
	v_mfma_f32_16x16x32_bf16 v[96:99], v[180:183], v[196:199], v[96:99]
	v_mfma_f32_16x16x32_bf16 v[84:87], v[172:175], v[204:207], v[84:87]
	v_mfma_f32_16x16x32_bf16 v[80:83], v[180:183], v[204:207], v[80:83]
	v_mfma_f32_16x16x32_bf16 v[68:71], v[172:175], v[212:215], v[68:71]
	v_mfma_f32_16x16x32_bf16 v[64:67], v[180:183], v[212:215], v[64:67]
	s_setprio 0
	s_barrier
; #define PG8_STAGE(bufoff, gbase, voff) do { _Pragma("unroll") for (int _i = 0; _i < 2; ++_i) \
;         __builtin_amdgcn_global_load_lds((const unsigned*)((const char*)(gbase) + (voff)[_i]), (PG8_LAS unsigned*)(lds + (bufoff) + ldsw + _i * 8192), 16, 0, 0); } while (0)
; #define PG8_LDA(dst, b, h) do { _Pragma("unroll") for (int m = 0; m < 4; ++m) _Pragma("unroll") for (int k = 0; k < 2; ++k) dst[m][k] = *(const PG8_LAS bf16x8*)(lds + PG8_SA(b, h) + aoff + m * 2048 + k * 1024); } while (0)
; #define PG8_MMA(ai, bj, At, Bt) do { __builtin_amdgcn_s_setprio(1); _Pragma("unroll") for (int m = 0; m < 4; ++m) _Pragma("unroll") for (int n = 0; n < 2; ++n) _Pragma("unroll") for (int k = 0; k < 2; ++k) \
;         acc[ai][bj][m][n] = __builtin_amdgcn_mfma_f32_16x16x32_bf16(Bt[n][k], At[m][k], acc[ai][bj][m][n], 0, 0, 0); __builtin_amdgcn_s_setprio(0); } while (0)
; #define PG8_WAIT_V(n) asm volatile("s_waitcnt vmcnt(" #n ")" ::: "memory")
; #define PG8_WAIT_L(n) asm volatile("s_waitcnt lgkmcnt(" #n ")" ::: "memory")
; #define PG8_BAR __builtin_amdgcn_s_barrier()
; #define PG8_SCHED __builtin_amdgcn_sched_barrier(0)
; template <class Epi, class Sched, bool ALIGN_EPI = false, bool SP2 = false>
; __device__ __forceinline__ void gemm_phase(PG8_LAS unsigned char* lds, const Gemm g, const Sched& S, const Epi& E) {
;     ...
;             PG8_LDA(At, 1, 1); PG8_STAGE(PG8_SB(1, 0), b3, voffB); PG8_STAGE(PG8_SB(1, 1), b3 + hstep, voffB); PG8_STAGE(PG8_SA(1, 0), a3, voffA);
;             PG8_WAIT_V(8); PG8_WAIT_L(0); PG8_BAR; PG8_MMA(1, 0, At, B0); PG8_MMA(1, 1, At, B1); PG8_BAR; PG8_SCHED;
;     ...
;         if constexpr (ALIGN_EPI) { if (wr == 0) PG8_BAR; }
	s_add_i32 s28, s54, s30
	v_lshl_add_u64 v[164:165], v[164:165], 0, s[8:9]
	s_mov_b32 m0, s28
	ds_read_b128 v[184:187], v171 offset:49152
	ds_read_b128 v[188:191], v171 offset:50176
	ds_read_b128 v[192:195], v171 offset:51200
	ds_read_b128 v[196:199], v171 offset:52224
	ds_read_b128 v[200:203], v171 offset:53248
	ds_read_b128 v[204:207], v171 offset:54272
	ds_read_b128 v[208:211], v171 offset:55296
	ds_read_b128 v[212:215], v171 offset:56320
	global_load_lds_dwordx4 v[164:165], off
	s_add_i32 m0, s28, 0x2000
	s_add_u32 s26, s26, 0xb0080
	v_lshl_add_u64 v[164:165], v[216:217], 0, s[8:9]
	s_addc_u32 s27, s27, 0
	s_add_i32 s28, s55, s30
	global_load_lds_dwordx4 v[164:165], off
	v_lshl_add_u64 v[164:165], s[26:27], 0, v[130:131]
	s_mov_b32 m0, s28
	s_nop 0
	global_load_lds_dwordx4 v[164:165], off
	v_lshl_add_u64 v[164:165], s[26:27], 0, v[134:135]
	s_add_i32 m0, s28, 0x2000
	s_nop 0
	global_load_lds_dwordx4 v[164:165], off
	v_lshl_add_u64 v[164:165], v[218:219], 0, s[8:9]
	s_mov_b32 m0, s41
	s_nop 0
	global_load_lds_dwordx4 v[164:165], off
	v_lshl_add_u64 v[164:165], v[220:221], 0, s[8:9]
	s_mov_b32 m0, s43
	s_nop 0
	global_load_lds_dwordx4 v[164:165], off
	s_waitcnt vmcnt(8)
	s_waitcnt lgkmcnt(0)
	s_barrier
	s_setprio 1
	s_waitcnt lgkmcnt(0)
	v_mfma_f32_16x16x32_bf16 v[60:63], v[144:147], v[184:187], v[60:63]
	v_mfma_f32_16x16x32_bf16 v[56:59], v[152:155], v[184:187], v[56:59]
	v_mfma_f32_16x16x32_bf16 v[44:47], v[144:147], v[192:195], v[44:47]
	v_mfma_f32_16x16x32_bf16 v[40:43], v[152:155], v[192:195], v[40:43]
	v_mfma_f32_16x16x32_bf16 v[28:31], v[144:147], v[200:203], v[28:31]
	v_mfma_f32_16x16x32_bf16 v[24:27], v[152:155], v[200:203], v[24:27]
	v_mfma_f32_16x16x32_bf16 v[12:15], v[144:147], v[208:211], v[12:15]
	v_mfma_f32_16x16x32_bf16 v[8:11], v[152:155], v[208:211], v[8:11]
	v_mfma_f32_16x16x32_bf16 v[60:63], v[148:151], v[188:191], v[60:63]
	v_mfma_f32_16x16x32_bf16 v[56:59], v[156:159], v[188:191], v[56:59]
	v_mfma_f32_16x16x32_bf16 v[44:47], v[148:151], v[196:199], v[44:47]
	v_mfma_f32_16x16x32_bf16 v[40:43], v[156:159], v[196:199], v[40:43]
	v_mfma_f32_16x16x32_bf16 v[28:31], v[148:151], v[204:207], v[28:31]
	v_mfma_f32_16x16x32_bf16 v[24:27], v[156:159], v[204:207], v[24:27]
	v_mfma_f32_16x16x32_bf16 v[12:15], v[148:151], v[212:215], v[12:15]
	v_mfma_f32_16x16x32_bf16 v[8:11], v[156:159], v[212:215], v[8:11]
	s_setprio 0
	s_setprio 1
	v_mfma_f32_16x16x32_bf16 v[52:55], v[160:163], v[184:187], v[52:55]
	v_mfma_f32_16x16x32_bf16 v[48:51], v[176:179], v[184:187], v[48:51]
	v_mfma_f32_16x16x32_bf16 v[36:39], v[160:163], v[192:195], v[36:39]
	v_mfma_f32_16x16x32_bf16 v[32:35], v[176:179], v[192:195], v[32:35]
	v_mfma_f32_16x16x32_bf16 v[20:23], v[160:163], v[200:203], v[20:23]
	v_mfma_f32_16x16x32_bf16 v[16:19], v[176:179], v[200:203], v[16:19]
	v_mfma_f32_16x16x32_bf16 v[4:7], v[160:163], v[208:211], v[4:7]
	v_mfma_f32_16x16x32_bf16 v[0:3], v[176:179], v[208:211], v[0:3]
	v_mfma_f32_16x16x32_bf16 v[52:55], v[172:175], v[188:191], v[52:55]
	v_mfma_f32_16x16x32_bf16 v[48:51], v[180:183], v[188:191], v[48:51]
	v_mfma_f32_16x16x32_bf16 v[36:39], v[172:175], v[196:199], v[36:39]
	v_mfma_f32_16x16x32_bf16 v[32:35], v[180:183], v[196:199], v[32:35]
	v_mfma_f32_16x16x32_bf16 v[20:23], v[172:175], v[204:207], v[20:23]
	v_mfma_f32_16x16x32_bf16 v[16:19], v[180:183], v[204:207], v[16:19]
	v_mfma_f32_16x16x32_bf16 v[4:7], v[172:175], v[212:215], v[4:7]
	v_mfma_f32_16x16x32_bf16 v[0:3], v[180:183], v[212:215], v[0:3]
	s_setprio 0
	s_add_i32 s53, s53, 2
	s_add_u32 s22, s22, 0x100
	s_addc_u32 s23, s23, 0
	s_add_u32 s51, s51, 0x100
	s_addc_u32 s52, s52, 0
	s_cmp_gt_u32 s53, 41
	s_barrier
	s_cbranch_scc0 .LBB0_1007
	s_and_b64 vcc, exec, s[10:11]
	s_cbranch_vccz .LBB0_1010
	s_barrier
